# v22 + GEMM K-loops: first K-iteration of each unit peeled with C=0 in each accumulator's first MFMA; the 128 v_mov accumulator zeroing per unit removed
# speedup vs baseline: 1.0033x; 1.0033x over previous
.LBB0_495:
	s_ashr_i32 s13, s12, 31
	s_lshl_b64 s[14:15], s[12:13], 19
	v_readlane_b32 s16, v244, 44
	v_readlane_b32 s17, v244, 45
	s_add_u32 s14, s16, s14
	s_addc_u32 s15, s17, s15
	s_and_b64 s[40:41], s[6:7], exec
	s_cselect_b32 s13, s15, s57
	s_cselect_b32 s81, s14, s56
	s_ashr_i32 s11, s10, 31
	s_lshl_b64 s[40:41], s[10:11], 19
	s_add_u32 s40, s38, s40
	s_addc_u32 s41, s39, s41
	s_and_b64 s[42:43], s[6:7], exec
	s_cselect_b32 s11, s41, s59
	s_cselect_b32 s82, s40, s58
	s_lshl_b32 s42, s80, 10
	s_lshl_b32 s60, s12, 8
	s_add_i32 s83, s42, 0
	s_ashr_i32 s61, s60, 31
	s_add_i32 s83, s83, 0x20800
	s_add_u32 s56, s56, 0x40080
	s_addc_u32 s57, s57, 0
	s_add_u32 s84, s58, 0x100
	s_mov_b32 s100, 1
	s_addc_u32 s85, s59, 0
	s_mov_b32 s86, -2
	v_lshl_add_u64 v[148:149], s[60:61], 2, v[132:133]
	s_branch .LBB0_497
.LBB0_496:
	s_cmp_lg_u32 s100, 0
	s_cbranch_scc1 .Lpeel_0
	v_add_u32_e32 v150, s72, v156
	v_add_u32_e32 v161, s72, v157
	ds_read_b128 v[150:153], v150
	ds_read_b128 v[162:165], v161
	v_add_u32_e32 v161, s73, v156
	v_add_u32_e32 v170, s73, v157
	ds_read_b128 v[166:169], v161
	ds_read_b128 v[170:173], v170
	v_add_u32_e32 v161, s74, v156
	v_add_u32_e32 v178, s74, v157
	ds_read_b128 v[174:177], v161
	ds_read_b128 v[178:181], v178
	v_add_u32_e32 v161, s75, v156
	v_add_u32_e32 v186, s75, v157
	ds_read_b128 v[182:185], v161
	ds_read_b128 v[186:189], v186
	s_add_u32 s44, s56, 0xfffc0080
	s_addc_u32 s45, s57, -1
	s_and_b64 s[42:43], s[58:59], exec
	s_cselect_b32 s61, s13, s45
	s_cselect_b32 s60, s81, s44
	s_cselect_b32 s59, s11, s85
	s_cselect_b32 s58, s82, s84
	v_lshl_add_u64 v[222:223], s[56:57], 0, v[140:141]
	s_add_i32 m0, s62, 0xc000
	ds_read_b128 v[190:193], v158
	ds_read_b128 v[194:197], v158 offset:2048
	ds_read_b128 v[198:201], v159
	ds_read_b128 v[202:205], v159 offset:2048
	ds_read_b128 v[206:209], v158 offset:4096
	ds_read_b128 v[210:213], v158 offset:6144
	ds_read_b128 v[214:217], v159 offset:4096
	ds_read_b128 v[218:221], v159 offset:6144
	global_load_lds_dwordx4 v[222:223], off
	v_lshl_add_u64 v[222:223], s[56:57], 0, v[142:143]
	s_add_i32 m0, s62, 0xe000
	s_nop 0
	global_load_lds_dwordx4 v[222:223], off
	s_waitcnt vmcnt(8)
	s_waitcnt lgkmcnt(0)
	s_barrier
	s_setprio 1
	s_waitcnt lgkmcnt(0)
	v_mfma_f32_16x16x32_bf16 v[126:129], v[150:153], v[190:193], v[126:129]
	v_mfma_f32_16x16x32_bf16 v[118:121], v[166:169], v[190:193], v[118:121]
	v_mfma_f32_16x16x32_bf16 v[110:113], v[150:153], v[194:197], v[110:113]
	v_mfma_f32_16x16x32_bf16 v[102:105], v[166:169], v[194:197], v[102:105]
	v_mfma_f32_16x16x32_bf16 v[94:97], v[150:153], v[206:209], v[94:97]
	v_mfma_f32_16x16x32_bf16 v[86:89], v[166:169], v[206:209], v[86:89]
	v_mfma_f32_16x16x32_bf16 v[78:81], v[150:153], v[210:213], v[78:81]
	v_mfma_f32_16x16x32_bf16 v[70:73], v[166:169], v[210:213], v[70:73]
	v_mfma_f32_16x16x32_bf16 v[126:129], v[162:165], v[198:201], v[126:129]
	v_mfma_f32_16x16x32_bf16 v[118:121], v[170:173], v[198:201], v[118:121]
	v_mfma_f32_16x16x32_bf16 v[110:113], v[162:165], v[202:205], v[110:113]
	v_mfma_f32_16x16x32_bf16 v[102:105], v[170:173], v[202:205], v[102:105]
	v_mfma_f32_16x16x32_bf16 v[94:97], v[162:165], v[214:217], v[94:97]
	v_mfma_f32_16x16x32_bf16 v[86:89], v[170:173], v[214:217], v[86:89]
	v_mfma_f32_16x16x32_bf16 v[78:81], v[162:165], v[218:221], v[78:81]
	v_mfma_f32_16x16x32_bf16 v[70:73], v[170:173], v[218:221], v[70:73]
	s_setprio 0
	s_setprio 1
	v_mfma_f32_16x16x32_bf16 v[122:125], v[174:177], v[190:193], v[122:125]
	v_mfma_f32_16x16x32_bf16 v[114:117], v[182:185], v[190:193], v[114:117]
	v_mfma_f32_16x16x32_bf16 v[106:109], v[174:177], v[194:197], v[106:109]
	v_mfma_f32_16x16x32_bf16 v[98:101], v[182:185], v[194:197], v[98:101]
	v_mfma_f32_16x16x32_bf16 v[90:93], v[174:177], v[206:209], v[90:93]
	v_mfma_f32_16x16x32_bf16 v[82:85], v[182:185], v[206:209], v[82:85]
	v_mfma_f32_16x16x32_bf16 v[74:77], v[174:177], v[210:213], v[74:77]
	v_mfma_f32_16x16x32_bf16 v[66:69], v[182:185], v[210:213], v[66:69]
	v_mfma_f32_16x16x32_bf16 v[122:125], v[178:181], v[198:201], v[122:125]
	v_mfma_f32_16x16x32_bf16 v[114:117], v[186:189], v[198:201], v[114:117]
	v_mfma_f32_16x16x32_bf16 v[106:109], v[178:181], v[202:205], v[106:109]
	v_mfma_f32_16x16x32_bf16 v[98:101], v[186:189], v[202:205], v[98:101]
	v_mfma_f32_16x16x32_bf16 v[90:93], v[178:181], v[214:217], v[90:93]
	v_mfma_f32_16x16x32_bf16 v[82:85], v[186:189], v[214:217], v[82:85]
	v_mfma_f32_16x16x32_bf16 v[74:77], v[178:181], v[218:221], v[74:77]
	v_mfma_f32_16x16x32_bf16 v[66:69], v[186:189], v[218:221], v[66:69]
	s_setprio 0
	s_barrier
	s_add_i32 s42, s72, s55
	v_lshl_add_u64 v[222:223], s[58:59], 0, v[130:131]
	s_mov_b32 m0, s42
	ds_read_b128 v[190:193], v158 offset:16384
	ds_read_b128 v[194:197], v158 offset:18432
	ds_read_b128 v[198:201], v159 offset:16384
	ds_read_b128 v[202:205], v159 offset:18432
	ds_read_b128 v[206:209], v158 offset:20480
	ds_read_b128 v[210:213], v158 offset:22528
	ds_read_b128 v[214:217], v159 offset:20480
	ds_read_b128 v[218:221], v159 offset:22528
	global_load_lds_dwordx4 v[222:223], off
	s_add_i32 m0, s42, 0x2000
	s_add_u32 s42, s58, 0x40000
	v_lshl_add_u64 v[224:225], s[58:59], 0, v[138:139]
	s_addc_u32 s43, s59, 0
	s_add_i32 s44, s74, s55
	global_load_lds_dwordx4 v[224:225], off
	v_lshl_add_u64 v[226:227], s[42:43], 0, v[130:131]
	s_mov_b32 m0, s44
	v_lshl_add_u64 v[228:229], s[60:61], 0, v[136:137]
	global_load_lds_dwordx4 v[226:227], off
	v_lshl_add_u64 v[226:227], s[42:43], 0, v[138:139]
	s_add_i32 m0, s44, 0x2000
	s_nop 0
	global_load_lds_dwordx4 v[226:227], off
	v_lshl_add_u64 v[226:227], s[60:61], 0, v[134:135]
	s_mov_b32 m0, s62
	s_nop 0
	global_load_lds_dwordx4 v[226:227], off
	s_mov_b32 m0, s63
	s_nop 0
	global_load_lds_dwordx4 v[228:229], off
	s_waitcnt vmcnt(8)
	s_waitcnt lgkmcnt(0)
	s_barrier
	s_setprio 1
	s_waitcnt lgkmcnt(0)
	v_mfma_f32_16x16x32_bf16 v[62:65], v[150:153], v[190:193], v[62:65]
	v_mfma_f32_16x16x32_bf16 v[54:57], v[166:169], v[190:193], v[54:57]
	v_mfma_f32_16x16x32_bf16 v[46:49], v[150:153], v[194:197], v[46:49]
	v_mfma_f32_16x16x32_bf16 v[38:41], v[166:169], v[194:197], v[38:41]
	v_mfma_f32_16x16x32_bf16 v[30:33], v[150:153], v[206:209], v[30:33]
	v_mfma_f32_16x16x32_bf16 v[22:25], v[166:169], v[206:209], v[22:25]
	v_mfma_f32_16x16x32_bf16 v[14:17], v[150:153], v[210:213], v[14:17]
	v_mfma_f32_16x16x32_bf16 v[6:9], v[166:169], v[210:213], v[6:9]
	v_mfma_f32_16x16x32_bf16 v[62:65], v[162:165], v[198:201], v[62:65]
	v_mfma_f32_16x16x32_bf16 v[54:57], v[170:173], v[198:201], v[54:57]
	v_mfma_f32_16x16x32_bf16 v[46:49], v[162:165], v[202:205], v[46:49]
	v_mfma_f32_16x16x32_bf16 v[38:41], v[170:173], v[202:205], v[38:41]
	v_mfma_f32_16x16x32_bf16 v[30:33], v[162:165], v[214:217], v[30:33]
	v_mfma_f32_16x16x32_bf16 v[22:25], v[170:173], v[214:217], v[22:25]
	v_mfma_f32_16x16x32_bf16 v[14:17], v[162:165], v[218:221], v[14:17]
	v_mfma_f32_16x16x32_bf16 v[6:9], v[170:173], v[218:221], v[6:9]
	s_setprio 0
	s_setprio 1
	v_mfma_f32_16x16x32_bf16 v[58:61], v[174:177], v[190:193], v[58:61]
	v_mfma_f32_16x16x32_bf16 v[50:53], v[182:185], v[190:193], v[50:53]
	v_mfma_f32_16x16x32_bf16 v[42:45], v[174:177], v[194:197], v[42:45]
	v_mfma_f32_16x16x32_bf16 v[34:37], v[182:185], v[194:197], v[34:37]
	v_mfma_f32_16x16x32_bf16 v[26:29], v[174:177], v[206:209], v[26:29]
	v_mfma_f32_16x16x32_bf16 v[18:21], v[182:185], v[206:209], v[18:21]
	v_mfma_f32_16x16x32_bf16 v[10:13], v[174:177], v[210:213], v[10:13]
	v_mfma_f32_16x16x32_bf16 v[2:5], v[182:185], v[210:213], v[2:5]
	v_mfma_f32_16x16x32_bf16 v[58:61], v[178:181], v[198:201], v[58:61]
	v_mfma_f32_16x16x32_bf16 v[50:53], v[186:189], v[198:201], v[50:53]
	v_mfma_f32_16x16x32_bf16 v[42:45], v[178:181], v[202:205], v[42:45]
	v_mfma_f32_16x16x32_bf16 v[34:37], v[186:189], v[202:205], v[34:37]
	v_mfma_f32_16x16x32_bf16 v[26:29], v[178:181], v[214:217], v[26:29]
	v_mfma_f32_16x16x32_bf16 v[18:21], v[186:189], v[214:217], v[18:21]
	v_mfma_f32_16x16x32_bf16 v[10:13], v[178:181], v[218:221], v[10:13]
	v_mfma_f32_16x16x32_bf16 v[2:5], v[186:189], v[218:221], v[2:5]
	s_setprio 0
	s_barrier
	s_add_i32 s44, 0, 0x18000
	v_add_u32_e32 v150, s44, v156
	v_add_u32_e32 v161, s44, v157
	ds_read_b128 v[150:153], v150
	ds_read_b128 v[162:165], v161
	v_add_u32_e32 v161, s76, v156
	v_add_u32_e32 v170, s76, v157
	s_add_i32 s45, 0, 0x1c000
	ds_read_b128 v[166:169], v161
	ds_read_b128 v[170:173], v170
	v_add_u32_e32 v161, s45, v156
	v_add_u32_e32 v178, s45, v157
	ds_read_b128 v[174:177], v161
	ds_read_b128 v[178:181], v178
	v_add_u32_e32 v161, s77, v156
	v_add_u32_e32 v186, s77, v157
	ds_read_b128 v[182:185], v161
	ds_read_b128 v[186:189], v186
	s_add_u32 s42, s60, 0x40000
	s_addc_u32 s43, s61, 0
	s_mov_b32 m0, s64
	v_lshl_add_u64 v[230:231], s[42:43], 0, v[134:135]
	ds_read_b128 v[190:193], v158 offset:32768
	ds_read_b128 v[194:197], v158 offset:34816
	ds_read_b128 v[198:201], v159 offset:32768
	ds_read_b128 v[202:205], v159 offset:34816
	ds_read_b128 v[206:209], v158 offset:36864
	ds_read_b128 v[210:213], v158 offset:38912
	ds_read_b128 v[214:217], v159 offset:36864
	ds_read_b128 v[218:221], v159 offset:38912
	global_load_lds_dwordx4 v[230:231], off
	v_lshl_add_u64 v[230:231], s[42:43], 0, v[136:137]
	s_mov_b32 m0, s65
	s_nop 0
	global_load_lds_dwordx4 v[230:231], off
	s_waitcnt vmcnt(8)
	s_waitcnt lgkmcnt(0)
	s_barrier
	s_setprio 1
	s_waitcnt lgkmcnt(0)
	v_mfma_f32_16x16x32_bf16 v[126:129], v[150:153], v[190:193], v[126:129]
	v_mfma_f32_16x16x32_bf16 v[118:121], v[166:169], v[190:193], v[118:121]
	v_mfma_f32_16x16x32_bf16 v[110:113], v[150:153], v[194:197], v[110:113]
	v_mfma_f32_16x16x32_bf16 v[102:105], v[166:169], v[194:197], v[102:105]
	v_mfma_f32_16x16x32_bf16 v[94:97], v[150:153], v[206:209], v[94:97]
	v_mfma_f32_16x16x32_bf16 v[86:89], v[166:169], v[206:209], v[86:89]
	v_mfma_f32_16x16x32_bf16 v[78:81], v[150:153], v[210:213], v[78:81]
	v_mfma_f32_16x16x32_bf16 v[70:73], v[166:169], v[210:213], v[70:73]
	v_mfma_f32_16x16x32_bf16 v[126:129], v[162:165], v[198:201], v[126:129]
	v_mfma_f32_16x16x32_bf16 v[118:121], v[170:173], v[198:201], v[118:121]
	v_mfma_f32_16x16x32_bf16 v[110:113], v[162:165], v[202:205], v[110:113]
	v_mfma_f32_16x16x32_bf16 v[102:105], v[170:173], v[202:205], v[102:105]
	v_mfma_f32_16x16x32_bf16 v[94:97], v[162:165], v[214:217], v[94:97]
	v_mfma_f32_16x16x32_bf16 v[86:89], v[170:173], v[214:217], v[86:89]
	v_mfma_f32_16x16x32_bf16 v[78:81], v[162:165], v[218:221], v[78:81]
	v_mfma_f32_16x16x32_bf16 v[70:73], v[170:173], v[218:221], v[70:73]
	s_setprio 0
	s_setprio 1
	v_mfma_f32_16x16x32_bf16 v[122:125], v[174:177], v[190:193], v[122:125]
	v_mfma_f32_16x16x32_bf16 v[114:117], v[182:185], v[190:193], v[114:117]
	v_mfma_f32_16x16x32_bf16 v[106:109], v[174:177], v[194:197], v[106:109]
	v_mfma_f32_16x16x32_bf16 v[98:101], v[182:185], v[194:197], v[98:101]
	v_mfma_f32_16x16x32_bf16 v[90:93], v[174:177], v[206:209], v[90:93]
	v_mfma_f32_16x16x32_bf16 v[82:85], v[182:185], v[206:209], v[82:85]
	v_mfma_f32_16x16x32_bf16 v[74:77], v[174:177], v[210:213], v[74:77]
	v_mfma_f32_16x16x32_bf16 v[66:69], v[182:185], v[210:213], v[66:69]
	v_mfma_f32_16x16x32_bf16 v[122:125], v[178:181], v[198:201], v[122:125]
	v_mfma_f32_16x16x32_bf16 v[114:117], v[186:189], v[198:201], v[114:117]
	v_mfma_f32_16x16x32_bf16 v[106:109], v[178:181], v[202:205], v[106:109]
	v_mfma_f32_16x16x32_bf16 v[98:101], v[186:189], v[202:205], v[98:101]
	v_mfma_f32_16x16x32_bf16 v[90:93], v[178:181], v[214:217], v[90:93]
	v_mfma_f32_16x16x32_bf16 v[82:85], v[186:189], v[214:217], v[82:85]
	v_mfma_f32_16x16x32_bf16 v[74:77], v[178:181], v[218:221], v[74:77]
	v_mfma_f32_16x16x32_bf16 v[66:69], v[186:189], v[218:221], v[66:69]
	s_setprio 0
	s_barrier
	s_add_i32 s42, s44, s55
	v_lshl_add_u64 v[222:223], v[222:223], 0, s[4:5]
	s_mov_b32 m0, s42
	ds_read_b128 v[190:193], v158 offset:49152
	ds_read_b128 v[194:197], v158 offset:51200
	ds_read_b128 v[198:201], v159 offset:49152
	ds_read_b128 v[202:205], v159 offset:51200
	ds_read_b128 v[206:209], v158 offset:53248
	ds_read_b128 v[210:213], v158 offset:55296
	ds_read_b128 v[214:217], v159 offset:53248
	ds_read_b128 v[218:221], v159 offset:55296
	global_load_lds_dwordx4 v[222:223], off
	s_add_i32 m0, s42, 0x2000
	s_add_u32 s42, s58, 0x40080
	v_lshl_add_u64 v[222:223], v[224:225], 0, s[4:5]
	s_addc_u32 s43, s59, 0
	s_add_i32 s44, s45, s55
	global_load_lds_dwordx4 v[222:223], off
	v_lshl_add_u64 v[222:223], s[42:43], 0, v[130:131]
	s_mov_b32 m0, s44
	s_nop 0
	global_load_lds_dwordx4 v[222:223], off
	v_lshl_add_u64 v[222:223], s[42:43], 0, v[138:139]
	s_add_i32 m0, s44, 0x2000
	s_nop 0
	global_load_lds_dwordx4 v[222:223], off
	v_lshl_add_u64 v[222:223], v[226:227], 0, s[4:5]
	s_mov_b32 m0, s69
	s_nop 0
	global_load_lds_dwordx4 v[222:223], off
	v_lshl_add_u64 v[222:223], v[228:229], 0, s[4:5]
	s_mov_b32 m0, s70
	s_nop 0
	global_load_lds_dwordx4 v[222:223], off
	s_waitcnt vmcnt(8)
	s_waitcnt lgkmcnt(0)
	s_barrier
	s_setprio 1
	s_waitcnt lgkmcnt(0)
	v_mfma_f32_16x16x32_bf16 v[62:65], v[150:153], v[190:193], v[62:65]
	v_mfma_f32_16x16x32_bf16 v[54:57], v[166:169], v[190:193], v[54:57]
	v_mfma_f32_16x16x32_bf16 v[46:49], v[150:153], v[194:197], v[46:49]
	v_mfma_f32_16x16x32_bf16 v[38:41], v[166:169], v[194:197], v[38:41]
	v_mfma_f32_16x16x32_bf16 v[30:33], v[150:153], v[206:209], v[30:33]
	v_mfma_f32_16x16x32_bf16 v[22:25], v[166:169], v[206:209], v[22:25]
	v_mfma_f32_16x16x32_bf16 v[14:17], v[150:153], v[210:213], v[14:17]
	v_mfma_f32_16x16x32_bf16 v[6:9], v[166:169], v[210:213], v[6:9]
	v_mfma_f32_16x16x32_bf16 v[62:65], v[162:165], v[198:201], v[62:65]
	v_mfma_f32_16x16x32_bf16 v[54:57], v[170:173], v[198:201], v[54:57]
	v_mfma_f32_16x16x32_bf16 v[46:49], v[162:165], v[202:205], v[46:49]
	v_mfma_f32_16x16x32_bf16 v[38:41], v[170:173], v[202:205], v[38:41]
	v_mfma_f32_16x16x32_bf16 v[30:33], v[162:165], v[214:217], v[30:33]
	v_mfma_f32_16x16x32_bf16 v[22:25], v[170:173], v[214:217], v[22:25]
	v_mfma_f32_16x16x32_bf16 v[14:17], v[162:165], v[218:221], v[14:17]
	v_mfma_f32_16x16x32_bf16 v[6:9], v[170:173], v[218:221], v[6:9]
	s_setprio 0
	s_setprio 1
	v_mfma_f32_16x16x32_bf16 v[58:61], v[174:177], v[190:193], v[58:61]
	v_mfma_f32_16x16x32_bf16 v[50:53], v[182:185], v[190:193], v[50:53]
	v_mfma_f32_16x16x32_bf16 v[42:45], v[174:177], v[194:197], v[42:45]
	v_mfma_f32_16x16x32_bf16 v[34:37], v[182:185], v[194:197], v[34:37]
	v_mfma_f32_16x16x32_bf16 v[26:29], v[174:177], v[206:209], v[26:29]
	v_mfma_f32_16x16x32_bf16 v[18:21], v[182:185], v[206:209], v[18:21]
	v_mfma_f32_16x16x32_bf16 v[10:13], v[174:177], v[210:213], v[10:13]
	v_mfma_f32_16x16x32_bf16 v[2:5], v[182:185], v[210:213], v[2:5]
	v_mfma_f32_16x16x32_bf16 v[58:61], v[178:181], v[198:201], v[58:61]
	v_mfma_f32_16x16x32_bf16 v[50:53], v[186:189], v[198:201], v[50:53]
	v_mfma_f32_16x16x32_bf16 v[42:45], v[178:181], v[202:205], v[42:45]
	v_mfma_f32_16x16x32_bf16 v[34:37], v[186:189], v[202:205], v[34:37]
	v_mfma_f32_16x16x32_bf16 v[26:29], v[178:181], v[214:217], v[26:29]
	v_mfma_f32_16x16x32_bf16 v[18:21], v[186:189], v[214:217], v[18:21]
	v_mfma_f32_16x16x32_bf16 v[10:13], v[178:181], v[218:221], v[10:13]
	v_mfma_f32_16x16x32_bf16 v[2:5], v[186:189], v[218:221], v[2:5]
	s_setprio 0
	s_barrier
	s_add_i32 s86, s86, 2
	s_add_u32 s56, s56, 0x100
	s_addc_u32 s57, s57, 0
	s_add_u32 s84, s84, 0x100
	s_addc_u32 s85, s85, 0
	s_cmp_gt_u32 s86, 13
	s_cbranch_scc1 .LBB0_500

.Lpeel_0:
	s_mov_b32 s100, 0
	v_add_u32_e32 v150, s72, v156
	v_add_u32_e32 v161, s72, v157
	ds_read_b128 v[150:153], v150
	ds_read_b128 v[162:165], v161
	v_add_u32_e32 v161, s73, v156
	v_add_u32_e32 v170, s73, v157
	ds_read_b128 v[166:169], v161
	ds_read_b128 v[170:173], v170
	v_add_u32_e32 v161, s74, v156
	v_add_u32_e32 v178, s74, v157
	ds_read_b128 v[174:177], v161
	ds_read_b128 v[178:181], v178
	v_add_u32_e32 v161, s75, v156
	v_add_u32_e32 v186, s75, v157
	ds_read_b128 v[182:185], v161
	ds_read_b128 v[186:189], v186
	s_add_u32 s44, s56, 0xfffc0080
	s_addc_u32 s45, s57, -1
	s_and_b64 s[42:43], s[58:59], exec
	s_cselect_b32 s61, s13, s45
	s_cselect_b32 s60, s81, s44
	s_cselect_b32 s59, s11, s85
	s_cselect_b32 s58, s82, s84
	v_lshl_add_u64 v[222:223], s[56:57], 0, v[140:141]
	s_add_i32 m0, s62, 0xc000
	ds_read_b128 v[190:193], v158
	ds_read_b128 v[194:197], v158 offset:2048
	ds_read_b128 v[198:201], v159
	ds_read_b128 v[202:205], v159 offset:2048
	ds_read_b128 v[206:209], v158 offset:4096
	ds_read_b128 v[210:213], v158 offset:6144
	ds_read_b128 v[214:217], v159 offset:4096
	ds_read_b128 v[218:221], v159 offset:6144
	global_load_lds_dwordx4 v[222:223], off
	v_lshl_add_u64 v[222:223], s[56:57], 0, v[142:143]
	s_add_i32 m0, s62, 0xe000
	s_nop 0
	global_load_lds_dwordx4 v[222:223], off
	s_waitcnt vmcnt(8)
	s_waitcnt lgkmcnt(0)
	s_barrier
	s_setprio 1
	s_waitcnt lgkmcnt(0)
	v_mfma_f32_16x16x32_bf16 v[126:129], v[150:153], v[190:193], 0
	v_mfma_f32_16x16x32_bf16 v[118:121], v[166:169], v[190:193], 0
	v_mfma_f32_16x16x32_bf16 v[110:113], v[150:153], v[194:197], 0
	v_mfma_f32_16x16x32_bf16 v[102:105], v[166:169], v[194:197], 0
	v_mfma_f32_16x16x32_bf16 v[94:97], v[150:153], v[206:209], 0
	v_mfma_f32_16x16x32_bf16 v[86:89], v[166:169], v[206:209], 0
	v_mfma_f32_16x16x32_bf16 v[78:81], v[150:153], v[210:213], 0
	v_mfma_f32_16x16x32_bf16 v[70:73], v[166:169], v[210:213], 0
	v_mfma_f32_16x16x32_bf16 v[126:129], v[162:165], v[198:201], v[126:129]
	v_mfma_f32_16x16x32_bf16 v[118:121], v[170:173], v[198:201], v[118:121]
	v_mfma_f32_16x16x32_bf16 v[110:113], v[162:165], v[202:205], v[110:113]
	v_mfma_f32_16x16x32_bf16 v[102:105], v[170:173], v[202:205], v[102:105]
	v_mfma_f32_16x16x32_bf16 v[94:97], v[162:165], v[214:217], v[94:97]
	v_mfma_f32_16x16x32_bf16 v[86:89], v[170:173], v[214:217], v[86:89]
	v_mfma_f32_16x16x32_bf16 v[78:81], v[162:165], v[218:221], v[78:81]
	v_mfma_f32_16x16x32_bf16 v[70:73], v[170:173], v[218:221], v[70:73]
	s_setprio 0
	s_setprio 1
	v_mfma_f32_16x16x32_bf16 v[122:125], v[174:177], v[190:193], 0
	v_mfma_f32_16x16x32_bf16 v[114:117], v[182:185], v[190:193], 0
	v_mfma_f32_16x16x32_bf16 v[106:109], v[174:177], v[194:197], 0
	v_mfma_f32_16x16x32_bf16 v[98:101], v[182:185], v[194:197], 0
	v_mfma_f32_16x16x32_bf16 v[90:93], v[174:177], v[206:209], 0
	v_mfma_f32_16x16x32_bf16 v[82:85], v[182:185], v[206:209], 0
	v_mfma_f32_16x16x32_bf16 v[74:77], v[174:177], v[210:213], 0
	v_mfma_f32_16x16x32_bf16 v[66:69], v[182:185], v[210:213], 0
	v_mfma_f32_16x16x32_bf16 v[122:125], v[178:181], v[198:201], v[122:125]
	v_mfma_f32_16x16x32_bf16 v[114:117], v[186:189], v[198:201], v[114:117]
	v_mfma_f32_16x16x32_bf16 v[106:109], v[178:181], v[202:205], v[106:109]
	v_mfma_f32_16x16x32_bf16 v[98:101], v[186:189], v[202:205], v[98:101]
	v_mfma_f32_16x16x32_bf16 v[90:93], v[178:181], v[214:217], v[90:93]
	v_mfma_f32_16x16x32_bf16 v[82:85], v[186:189], v[214:217], v[82:85]
	v_mfma_f32_16x16x32_bf16 v[74:77], v[178:181], v[218:221], v[74:77]
	v_mfma_f32_16x16x32_bf16 v[66:69], v[186:189], v[218:221], v[66:69]
	s_setprio 0
	s_barrier
	s_add_i32 s42, s72, s55
	v_lshl_add_u64 v[222:223], s[58:59], 0, v[130:131]
	s_mov_b32 m0, s42
	ds_read_b128 v[190:193], v158 offset:16384
	ds_read_b128 v[194:197], v158 offset:18432
	ds_read_b128 v[198:201], v159 offset:16384
	ds_read_b128 v[202:205], v159 offset:18432
	ds_read_b128 v[206:209], v158 offset:20480
	ds_read_b128 v[210:213], v158 offset:22528
	ds_read_b128 v[214:217], v159 offset:20480
	ds_read_b128 v[218:221], v159 offset:22528
	global_load_lds_dwordx4 v[222:223], off
	s_add_i32 m0, s42, 0x2000
	s_add_u32 s42, s58, 0x40000
	v_lshl_add_u64 v[224:225], s[58:59], 0, v[138:139]
	s_addc_u32 s43, s59, 0
	s_add_i32 s44, s74, s55
	global_load_lds_dwordx4 v[224:225], off
	v_lshl_add_u64 v[226:227], s[42:43], 0, v[130:131]
	s_mov_b32 m0, s44
	v_lshl_add_u64 v[228:229], s[60:61], 0, v[136:137]
	global_load_lds_dwordx4 v[226:227], off
	v_lshl_add_u64 v[226:227], s[42:43], 0, v[138:139]
	s_add_i32 m0, s44, 0x2000
	s_nop 0
	global_load_lds_dwordx4 v[226:227], off
	v_lshl_add_u64 v[226:227], s[60:61], 0, v[134:135]
	s_mov_b32 m0, s62
	s_nop 0
	global_load_lds_dwordx4 v[226:227], off
	s_mov_b32 m0, s63
	s_nop 0
	global_load_lds_dwordx4 v[228:229], off
	s_waitcnt vmcnt(8)
	s_waitcnt lgkmcnt(0)
	s_barrier
	s_setprio 1
	s_waitcnt lgkmcnt(0)
	v_mfma_f32_16x16x32_bf16 v[62:65], v[150:153], v[190:193], 0
	v_mfma_f32_16x16x32_bf16 v[54:57], v[166:169], v[190:193], 0
	v_mfma_f32_16x16x32_bf16 v[46:49], v[150:153], v[194:197], 0
	v_mfma_f32_16x16x32_bf16 v[38:41], v[166:169], v[194:197], 0
	v_mfma_f32_16x16x32_bf16 v[30:33], v[150:153], v[206:209], 0
	v_mfma_f32_16x16x32_bf16 v[22:25], v[166:169], v[206:209], 0
	v_mfma_f32_16x16x32_bf16 v[14:17], v[150:153], v[210:213], 0
	v_mfma_f32_16x16x32_bf16 v[6:9], v[166:169], v[210:213], 0
	v_mfma_f32_16x16x32_bf16 v[62:65], v[162:165], v[198:201], v[62:65]
	v_mfma_f32_16x16x32_bf16 v[54:57], v[170:173], v[198:201], v[54:57]
	v_mfma_f32_16x16x32_bf16 v[46:49], v[162:165], v[202:205], v[46:49]
	v_mfma_f32_16x16x32_bf16 v[38:41], v[170:173], v[202:205], v[38:41]
	v_mfma_f32_16x16x32_bf16 v[30:33], v[162:165], v[214:217], v[30:33]
	v_mfma_f32_16x16x32_bf16 v[22:25], v[170:173], v[214:217], v[22:25]
	v_mfma_f32_16x16x32_bf16 v[14:17], v[162:165], v[218:221], v[14:17]
	v_mfma_f32_16x16x32_bf16 v[6:9], v[170:173], v[218:221], v[6:9]
	s_setprio 0
	s_setprio 1
	v_mfma_f32_16x16x32_bf16 v[58:61], v[174:177], v[190:193], 0
	v_mfma_f32_16x16x32_bf16 v[50:53], v[182:185], v[190:193], 0
	v_mfma_f32_16x16x32_bf16 v[42:45], v[174:177], v[194:197], 0
	v_mfma_f32_16x16x32_bf16 v[34:37], v[182:185], v[194:197], 0
	v_mfma_f32_16x16x32_bf16 v[26:29], v[174:177], v[206:209], 0
	v_mfma_f32_16x16x32_bf16 v[18:21], v[182:185], v[206:209], 0
	v_mfma_f32_16x16x32_bf16 v[10:13], v[174:177], v[210:213], 0
	v_mfma_f32_16x16x32_bf16 v[2:5], v[182:185], v[210:213], 0
	v_mfma_f32_16x16x32_bf16 v[58:61], v[178:181], v[198:201], v[58:61]
	v_mfma_f32_16x16x32_bf16 v[50:53], v[186:189], v[198:201], v[50:53]
	v_mfma_f32_16x16x32_bf16 v[42:45], v[178:181], v[202:205], v[42:45]
	v_mfma_f32_16x16x32_bf16 v[34:37], v[186:189], v[202:205], v[34:37]
	v_mfma_f32_16x16x32_bf16 v[26:29], v[178:181], v[214:217], v[26:29]
	v_mfma_f32_16x16x32_bf16 v[18:21], v[186:189], v[214:217], v[18:21]
	v_mfma_f32_16x16x32_bf16 v[10:13], v[178:181], v[218:221], v[10:13]
	v_mfma_f32_16x16x32_bf16 v[2:5], v[186:189], v[218:221], v[2:5]
	s_setprio 0
	s_barrier
	s_add_i32 s44, 0, 0x18000
	v_add_u32_e32 v150, s44, v156
	v_add_u32_e32 v161, s44, v157
	ds_read_b128 v[150:153], v150
	ds_read_b128 v[162:165], v161
	v_add_u32_e32 v161, s76, v156
	v_add_u32_e32 v170, s76, v157
	s_add_i32 s45, 0, 0x1c000
	ds_read_b128 v[166:169], v161
	ds_read_b128 v[170:173], v170
	v_add_u32_e32 v161, s45, v156
	v_add_u32_e32 v178, s45, v157
	ds_read_b128 v[174:177], v161
	ds_read_b128 v[178:181], v178
	v_add_u32_e32 v161, s77, v156
	v_add_u32_e32 v186, s77, v157
	ds_read_b128 v[182:185], v161
	ds_read_b128 v[186:189], v186
	s_add_u32 s42, s60, 0x40000
	s_addc_u32 s43, s61, 0
	s_mov_b32 m0, s64
	v_lshl_add_u64 v[230:231], s[42:43], 0, v[134:135]
	ds_read_b128 v[190:193], v158 offset:32768
	ds_read_b128 v[194:197], v158 offset:34816
	ds_read_b128 v[198:201], v159 offset:32768
	ds_read_b128 v[202:205], v159 offset:34816
	ds_read_b128 v[206:209], v158 offset:36864
	ds_read_b128 v[210:213], v158 offset:38912
	ds_read_b128 v[214:217], v159 offset:36864
	ds_read_b128 v[218:221], v159 offset:38912
	global_load_lds_dwordx4 v[230:231], off
	v_lshl_add_u64 v[230:231], s[42:43], 0, v[136:137]
	s_mov_b32 m0, s65
	s_nop 0
	global_load_lds_dwordx4 v[230:231], off
	s_waitcnt vmcnt(8)
	s_waitcnt lgkmcnt(0)
	s_barrier
	s_setprio 1
	s_waitcnt lgkmcnt(0)
	v_mfma_f32_16x16x32_bf16 v[126:129], v[150:153], v[190:193], v[126:129]
	v_mfma_f32_16x16x32_bf16 v[118:121], v[166:169], v[190:193], v[118:121]
	v_mfma_f32_16x16x32_bf16 v[110:113], v[150:153], v[194:197], v[110:113]
	v_mfma_f32_16x16x32_bf16 v[102:105], v[166:169], v[194:197], v[102:105]
	v_mfma_f32_16x16x32_bf16 v[94:97], v[150:153], v[206:209], v[94:97]
	v_mfma_f32_16x16x32_bf16 v[86:89], v[166:169], v[206:209], v[86:89]
	v_mfma_f32_16x16x32_bf16 v[78:81], v[150:153], v[210:213], v[78:81]
	v_mfma_f32_16x16x32_bf16 v[70:73], v[166:169], v[210:213], v[70:73]
	v_mfma_f32_16x16x32_bf16 v[126:129], v[162:165], v[198:201], v[126:129]
	v_mfma_f32_16x16x32_bf16 v[118:121], v[170:173], v[198:201], v[118:121]
	v_mfma_f32_16x16x32_bf16 v[110:113], v[162:165], v[202:205], v[110:113]
	v_mfma_f32_16x16x32_bf16 v[102:105], v[170:173], v[202:205], v[102:105]
	v_mfma_f32_16x16x32_bf16 v[94:97], v[162:165], v[214:217], v[94:97]
	v_mfma_f32_16x16x32_bf16 v[86:89], v[170:173], v[214:217], v[86:89]
	v_mfma_f32_16x16x32_bf16 v[78:81], v[162:165], v[218:221], v[78:81]
	v_mfma_f32_16x16x32_bf16 v[70:73], v[170:173], v[218:221], v[70:73]
	s_setprio 0
	s_setprio 1
	v_mfma_f32_16x16x32_bf16 v[122:125], v[174:177], v[190:193], v[122:125]
	v_mfma_f32_16x16x32_bf16 v[114:117], v[182:185], v[190:193], v[114:117]
	v_mfma_f32_16x16x32_bf16 v[106:109], v[174:177], v[194:197], v[106:109]
	v_mfma_f32_16x16x32_bf16 v[98:101], v[182:185], v[194:197], v[98:101]
	v_mfma_f32_16x16x32_bf16 v[90:93], v[174:177], v[206:209], v[90:93]
	v_mfma_f32_16x16x32_bf16 v[82:85], v[182:185], v[206:209], v[82:85]
	v_mfma_f32_16x16x32_bf16 v[74:77], v[174:177], v[210:213], v[74:77]
	v_mfma_f32_16x16x32_bf16 v[66:69], v[182:185], v[210:213], v[66:69]
	v_mfma_f32_16x16x32_bf16 v[122:125], v[178:181], v[198:201], v[122:125]
	v_mfma_f32_16x16x32_bf16 v[114:117], v[186:189], v[198:201], v[114:117]
	v_mfma_f32_16x16x32_bf16 v[106:109], v[178:181], v[202:205], v[106:109]
	v_mfma_f32_16x16x32_bf16 v[98:101], v[186:189], v[202:205], v[98:101]
	v_mfma_f32_16x16x32_bf16 v[90:93], v[178:181], v[214:217], v[90:93]
	v_mfma_f32_16x16x32_bf16 v[82:85], v[186:189], v[214:217], v[82:85]
	v_mfma_f32_16x16x32_bf16 v[74:77], v[178:181], v[218:221], v[74:77]
	v_mfma_f32_16x16x32_bf16 v[66:69], v[186:189], v[218:221], v[66:69]
	s_setprio 0
	s_barrier
	s_add_i32 s42, s44, s55
	v_lshl_add_u64 v[222:223], v[222:223], 0, s[4:5]
	s_mov_b32 m0, s42
	ds_read_b128 v[190:193], v158 offset:49152
	ds_read_b128 v[194:197], v158 offset:51200
	ds_read_b128 v[198:201], v159 offset:49152
	ds_read_b128 v[202:205], v159 offset:51200
	ds_read_b128 v[206:209], v158 offset:53248
	ds_read_b128 v[210:213], v158 offset:55296
	ds_read_b128 v[214:217], v159 offset:53248
	ds_read_b128 v[218:221], v159 offset:55296
	global_load_lds_dwordx4 v[222:223], off
	s_add_i32 m0, s42, 0x2000
	s_add_u32 s42, s58, 0x40080
	v_lshl_add_u64 v[222:223], v[224:225], 0, s[4:5]
	s_addc_u32 s43, s59, 0
	s_add_i32 s44, s45, s55
	global_load_lds_dwordx4 v[222:223], off
	v_lshl_add_u64 v[222:223], s[42:43], 0, v[130:131]
	s_mov_b32 m0, s44
	s_nop 0
	global_load_lds_dwordx4 v[222:223], off
	v_lshl_add_u64 v[222:223], s[42:43], 0, v[138:139]
	s_add_i32 m0, s44, 0x2000
	s_nop 0
	global_load_lds_dwordx4 v[222:223], off
	v_lshl_add_u64 v[222:223], v[226:227], 0, s[4:5]
	s_mov_b32 m0, s69
	s_nop 0
	global_load_lds_dwordx4 v[222:223], off
	v_lshl_add_u64 v[222:223], v[228:229], 0, s[4:5]
	s_mov_b32 m0, s70
	s_nop 0
	global_load_lds_dwordx4 v[222:223], off
	s_waitcnt vmcnt(8)
	s_waitcnt lgkmcnt(0)
	s_barrier
	s_setprio 1
	s_waitcnt lgkmcnt(0)
	v_mfma_f32_16x16x32_bf16 v[62:65], v[150:153], v[190:193], v[62:65]
	v_mfma_f32_16x16x32_bf16 v[54:57], v[166:169], v[190:193], v[54:57]
	v_mfma_f32_16x16x32_bf16 v[46:49], v[150:153], v[194:197], v[46:49]
	v_mfma_f32_16x16x32_bf16 v[38:41], v[166:169], v[194:197], v[38:41]
	v_mfma_f32_16x16x32_bf16 v[30:33], v[150:153], v[206:209], v[30:33]
	v_mfma_f32_16x16x32_bf16 v[22:25], v[166:169], v[206:209], v[22:25]
	v_mfma_f32_16x16x32_bf16 v[14:17], v[150:153], v[210:213], v[14:17]
	v_mfma_f32_16x16x32_bf16 v[6:9], v[166:169], v[210:213], v[6:9]
	v_mfma_f32_16x16x32_bf16 v[62:65], v[162:165], v[198:201], v[62:65]
	v_mfma_f32_16x16x32_bf16 v[54:57], v[170:173], v[198:201], v[54:57]
	v_mfma_f32_16x16x32_bf16 v[46:49], v[162:165], v[202:205], v[46:49]
	v_mfma_f32_16x16x32_bf16 v[38:41], v[170:173], v[202:205], v[38:41]
	v_mfma_f32_16x16x32_bf16 v[30:33], v[162:165], v[214:217], v[30:33]
	v_mfma_f32_16x16x32_bf16 v[22:25], v[170:173], v[214:217], v[22:25]
	v_mfma_f32_16x16x32_bf16 v[14:17], v[162:165], v[218:221], v[14:17]
	v_mfma_f32_16x16x32_bf16 v[6:9], v[170:173], v[218:221], v[6:9]
	s_setprio 0
	s_setprio 1
	v_mfma_f32_16x16x32_bf16 v[58:61], v[174:177], v[190:193], v[58:61]
	v_mfma_f32_16x16x32_bf16 v[50:53], v[182:185], v[190:193], v[50:53]
	v_mfma_f32_16x16x32_bf16 v[42:45], v[174:177], v[194:197], v[42:45]
	v_mfma_f32_16x16x32_bf16 v[34:37], v[182:185], v[194:197], v[34:37]
	v_mfma_f32_16x16x32_bf16 v[26:29], v[174:177], v[206:209], v[26:29]
	v_mfma_f32_16x16x32_bf16 v[18:21], v[182:185], v[206:209], v[18:21]
	v_mfma_f32_16x16x32_bf16 v[10:13], v[174:177], v[210:213], v[10:13]
	v_mfma_f32_16x16x32_bf16 v[2:5], v[182:185], v[210:213], v[2:5]
	v_mfma_f32_16x16x32_bf16 v[58:61], v[178:181], v[198:201], v[58:61]
	v_mfma_f32_16x16x32_bf16 v[50:53], v[186:189], v[198:201], v[50:53]
	v_mfma_f32_16x16x32_bf16 v[42:45], v[178:181], v[202:205], v[42:45]
	v_mfma_f32_16x16x32_bf16 v[34:37], v[186:189], v[202:205], v[34:37]
	v_mfma_f32_16x16x32_bf16 v[26:29], v[178:181], v[214:217], v[26:29]
	v_mfma_f32_16x16x32_bf16 v[18:21], v[186:189], v[214:217], v[18:21]
	v_mfma_f32_16x16x32_bf16 v[10:13], v[178:181], v[218:221], v[10:13]
	v_mfma_f32_16x16x32_bf16 v[2:5], v[186:189], v[218:221], v[2:5]
	s_setprio 0
	s_barrier
	s_add_i32 s86, s86, 2
	s_add_u32 s56, s56, 0x100
	s_addc_u32 s57, s57, 0
	s_add_u32 s84, s84, 0x100
	s_addc_u32 s85, s85, 0
	s_cmp_gt_u32 s86, 13
	s_cbranch_scc1 .LBB0_500
	s_branch .LBB0_497

.LBB0_588:
	s_add_u32 s40, s40, 0xb0080
	s_addc_u32 s41, s41, 0
	s_add_u32 s42, s52, 0x100
	s_mov_b32 s100, 1
	s_addc_u32 s43, s53, 0
	s_mov_b32 s44, -2
.LBB0_589:
	s_cmp_lg_u32 s100, 0
	s_cbranch_scc1 .Lpeel_1
	ds_read_b128 v[90:93], v212
	ds_read_b128 v[102:105], v213
	ds_read_b128 v[114:117], v214
	ds_read_b128 v[126:129], v215
	ds_read_b128 v[138:141], v216
	ds_read_b128 v[150:153], v217
	ds_read_b128 v[154:157], v218
	ds_read_b128 v[158:161], v219
	s_add_u32 s45, s40, 0xfff50080
	s_addc_u32 s46, s41, -1
	s_cmp_eq_u32 s44, 40
	s_cselect_b32 s55, s1, s46
	s_cselect_b32 s54, s0, s45
	s_cselect_b32 s53, s15, s43
	s_cselect_b32 s52, s14, s42
	v_lshl_add_u64 v[230:231], s[40:41], 0, v[196:197]
	s_add_i32 m0, s56, 0xc000
	ds_read_b128 v[162:165], v220
	ds_read_b128 v[166:169], v220 offset:2048
	ds_read_b128 v[170:173], v221
	ds_read_b128 v[174:177], v221 offset:2048
	ds_read_b128 v[178:181], v220 offset:4096
	ds_read_b128 v[182:185], v220 offset:6144
	ds_read_b128 v[204:207], v221 offset:4096
	ds_read_b128 v[226:229], v221 offset:6144
	global_load_lds_dwordx4 v[230:231], off
	v_lshl_add_u64 v[230:231], s[40:41], 0, v[198:199]
	s_add_i32 m0, s56, 0xe000
	s_nop 0
	global_load_lds_dwordx4 v[230:231], off
	s_waitcnt vmcnt(8)
	s_waitcnt lgkmcnt(0)
	s_barrier
	s_setprio 1
	s_waitcnt lgkmcnt(0)
	v_mfma_f32_16x16x32_bf16 v[146:149], v[90:93], v[162:165], v[146:149]
	v_mfma_f32_16x16x32_bf16 v[142:145], v[114:117], v[162:165], v[142:145]
	v_mfma_f32_16x16x32_bf16 v[122:125], v[90:93], v[166:169], v[122:125]
	v_mfma_f32_16x16x32_bf16 v[118:121], v[114:117], v[166:169], v[118:121]
	v_mfma_f32_16x16x32_bf16 v[98:101], v[90:93], v[178:181], v[98:101]
	v_mfma_f32_16x16x32_bf16 v[94:97], v[114:117], v[178:181], v[94:97]
	v_mfma_f32_16x16x32_bf16 v[78:81], v[90:93], v[182:185], v[78:81]
	v_mfma_f32_16x16x32_bf16 v[74:77], v[114:117], v[182:185], v[74:77]
	v_mfma_f32_16x16x32_bf16 v[146:149], v[102:105], v[170:173], v[146:149]
	v_mfma_f32_16x16x32_bf16 v[142:145], v[126:129], v[170:173], v[142:145]
	v_mfma_f32_16x16x32_bf16 v[122:125], v[102:105], v[174:177], v[122:125]
	v_mfma_f32_16x16x32_bf16 v[118:121], v[126:129], v[174:177], v[118:121]
	v_mfma_f32_16x16x32_bf16 v[98:101], v[102:105], v[204:207], v[98:101]
	v_mfma_f32_16x16x32_bf16 v[94:97], v[126:129], v[204:207], v[94:97]
	v_mfma_f32_16x16x32_bf16 v[78:81], v[102:105], v[226:229], v[78:81]
	v_mfma_f32_16x16x32_bf16 v[74:77], v[126:129], v[226:229], v[74:77]
	s_setprio 0
	s_setprio 1
	v_mfma_f32_16x16x32_bf16 v[134:137], v[138:141], v[162:165], v[134:137]
	v_mfma_f32_16x16x32_bf16 v[130:133], v[154:157], v[162:165], v[130:133]
	v_mfma_f32_16x16x32_bf16 v[110:113], v[138:141], v[166:169], v[110:113]
	v_mfma_f32_16x16x32_bf16 v[106:109], v[154:157], v[166:169], v[106:109]
	v_mfma_f32_16x16x32_bf16 v[86:89], v[138:141], v[178:181], v[86:89]
	v_mfma_f32_16x16x32_bf16 v[82:85], v[154:157], v[178:181], v[82:85]
	v_mfma_f32_16x16x32_bf16 v[70:73], v[138:141], v[182:185], v[70:73]
	v_mfma_f32_16x16x32_bf16 v[66:69], v[154:157], v[182:185], v[66:69]
	v_mfma_f32_16x16x32_bf16 v[134:137], v[150:153], v[170:173], v[134:137]
	v_mfma_f32_16x16x32_bf16 v[130:133], v[158:161], v[170:173], v[130:133]
	v_mfma_f32_16x16x32_bf16 v[110:113], v[150:153], v[174:177], v[110:113]
	v_mfma_f32_16x16x32_bf16 v[106:109], v[158:161], v[174:177], v[106:109]
	v_mfma_f32_16x16x32_bf16 v[86:89], v[150:153], v[204:207], v[86:89]
	v_mfma_f32_16x16x32_bf16 v[82:85], v[158:161], v[204:207], v[82:85]
	v_mfma_f32_16x16x32_bf16 v[70:73], v[150:153], v[226:229], v[70:73]
	v_mfma_f32_16x16x32_bf16 v[66:69], v[158:161], v[226:229], v[66:69]
	s_setprio 0
	s_barrier
	s_add_i32 s45, s68, s39
	v_lshl_add_u64 v[230:231], s[52:53], 0, v[188:189]
	s_mov_b32 m0, s45
	ds_read_b128 v[162:165], v220 offset:16384
	ds_read_b128 v[166:169], v220 offset:18432
	ds_read_b128 v[170:173], v221 offset:16384
	ds_read_b128 v[174:177], v221 offset:18432
	ds_read_b128 v[178:181], v220 offset:20480
	ds_read_b128 v[182:185], v220 offset:22528
	ds_read_b128 v[204:207], v221 offset:20480
	ds_read_b128 v[226:229], v221 offset:22528
	global_load_lds_dwordx4 v[230:231], off
	s_add_i32 m0, s45, 0x2000
	s_add_u32 s46, s52, 0xb0000
	v_lshl_add_u64 v[232:233], s[52:53], 0, v[192:193]
	s_addc_u32 s47, s53, 0
	s_add_i32 s45, s69, s39
	global_load_lds_dwordx4 v[232:233], off
	v_lshl_add_u64 v[234:235], s[46:47], 0, v[188:189]
	s_mov_b32 m0, s45
	v_lshl_add_u64 v[236:237], s[54:55], 0, v[190:191]
	global_load_lds_dwordx4 v[234:235], off
	v_lshl_add_u64 v[234:235], s[46:47], 0, v[192:193]
	s_add_i32 m0, s45, 0x2000
	s_nop 0
	global_load_lds_dwordx4 v[234:235], off
	v_lshl_add_u64 v[234:235], s[54:55], 0, v[186:187]
	s_mov_b32 m0, s56
	s_nop 0
	global_load_lds_dwordx4 v[234:235], off
	s_mov_b32 m0, s57
	s_nop 0
	global_load_lds_dwordx4 v[236:237], off
	s_waitcnt vmcnt(8)
	s_waitcnt lgkmcnt(0)
	s_barrier
	s_setprio 1
	s_waitcnt lgkmcnt(0)
	v_mfma_f32_16x16x32_bf16 v[62:65], v[90:93], v[162:165], v[62:65]
	v_mfma_f32_16x16x32_bf16 v[58:61], v[114:117], v[162:165], v[58:61]
	v_mfma_f32_16x16x32_bf16 v[46:49], v[90:93], v[166:169], v[46:49]
	v_mfma_f32_16x16x32_bf16 v[42:45], v[114:117], v[166:169], v[42:45]
	v_mfma_f32_16x16x32_bf16 v[30:33], v[90:93], v[178:181], v[30:33]
	v_mfma_f32_16x16x32_bf16 v[26:29], v[114:117], v[178:181], v[26:29]
	v_mfma_f32_16x16x32_bf16 v[14:17], v[90:93], v[182:185], v[14:17]
	v_mfma_f32_16x16x32_bf16 v[10:13], v[114:117], v[182:185], v[10:13]
	v_mfma_f32_16x16x32_bf16 v[62:65], v[102:105], v[170:173], v[62:65]
	v_mfma_f32_16x16x32_bf16 v[58:61], v[126:129], v[170:173], v[58:61]
	v_mfma_f32_16x16x32_bf16 v[46:49], v[102:105], v[174:177], v[46:49]
	v_mfma_f32_16x16x32_bf16 v[42:45], v[126:129], v[174:177], v[42:45]
	v_mfma_f32_16x16x32_bf16 v[30:33], v[102:105], v[204:207], v[30:33]
	v_mfma_f32_16x16x32_bf16 v[26:29], v[126:129], v[204:207], v[26:29]
	v_mfma_f32_16x16x32_bf16 v[14:17], v[102:105], v[226:229], v[14:17]
	v_mfma_f32_16x16x32_bf16 v[10:13], v[126:129], v[226:229], v[10:13]
	s_setprio 0
	s_setprio 1
	v_mfma_f32_16x16x32_bf16 v[54:57], v[138:141], v[162:165], v[54:57]
	v_mfma_f32_16x16x32_bf16 v[50:53], v[154:157], v[162:165], v[50:53]
	v_mfma_f32_16x16x32_bf16 v[38:41], v[138:141], v[166:169], v[38:41]
	v_mfma_f32_16x16x32_bf16 v[34:37], v[154:157], v[166:169], v[34:37]
	v_mfma_f32_16x16x32_bf16 v[22:25], v[138:141], v[178:181], v[22:25]
	v_mfma_f32_16x16x32_bf16 v[18:21], v[154:157], v[178:181], v[18:21]
	v_mfma_f32_16x16x32_bf16 v[6:9], v[138:141], v[182:185], v[6:9]
	v_mfma_f32_16x16x32_bf16 v[2:5], v[154:157], v[182:185], v[2:5]
	v_mfma_f32_16x16x32_bf16 v[54:57], v[150:153], v[170:173], v[54:57]
	v_mfma_f32_16x16x32_bf16 v[50:53], v[158:161], v[170:173], v[50:53]
	v_mfma_f32_16x16x32_bf16 v[38:41], v[150:153], v[174:177], v[38:41]
	v_mfma_f32_16x16x32_bf16 v[34:37], v[158:161], v[174:177], v[34:37]
	v_mfma_f32_16x16x32_bf16 v[22:25], v[150:153], v[204:207], v[22:25]
	v_mfma_f32_16x16x32_bf16 v[18:21], v[158:161], v[204:207], v[18:21]
	v_mfma_f32_16x16x32_bf16 v[6:9], v[150:153], v[226:229], v[6:9]
	v_mfma_f32_16x16x32_bf16 v[2:5], v[158:161], v[226:229], v[2:5]
	s_setprio 0
	s_barrier
	s_add_i32 s45, 0, 0x18000
	s_add_i32 s48, 0, 0x1c000
	v_add_u32_e32 v90, s45, v210
	v_add_u32_e32 v102, s45, v211
	v_add_u32_e32 v138, s48, v210
	v_add_u32_e32 v150, s48, v211
	ds_read_b128 v[90:93], v90
	ds_read_b128 v[102:105], v102
	ds_read_b128 v[114:117], v222
	ds_read_b128 v[126:129], v223
	ds_read_b128 v[138:141], v138
	ds_read_b128 v[150:153], v150
	ds_read_b128 v[154:157], v224
	ds_read_b128 v[158:161], v225
	s_add_u32 s46, s54, 0xb0000
	s_addc_u32 s47, s55, 0
	s_mov_b32 m0, s58
	v_lshl_add_u64 v[238:239], s[46:47], 0, v[186:187]
	ds_read_b128 v[162:165], v220 offset:32768
	ds_read_b128 v[166:169], v220 offset:34816
	ds_read_b128 v[170:173], v221 offset:32768
	ds_read_b128 v[174:177], v221 offset:34816
	ds_read_b128 v[178:181], v220 offset:36864
	ds_read_b128 v[182:185], v220 offset:38912
	ds_read_b128 v[204:207], v221 offset:36864
	ds_read_b128 v[226:229], v221 offset:38912
	global_load_lds_dwordx4 v[238:239], off
	v_lshl_add_u64 v[238:239], s[46:47], 0, v[190:191]
	s_mov_b32 m0, s59
	s_nop 0
	global_load_lds_dwordx4 v[238:239], off
	s_waitcnt vmcnt(8)
	s_waitcnt lgkmcnt(0)
	s_barrier
	s_setprio 1
	s_waitcnt lgkmcnt(0)
	v_mfma_f32_16x16x32_bf16 v[146:149], v[90:93], v[162:165], v[146:149]
	v_mfma_f32_16x16x32_bf16 v[142:145], v[114:117], v[162:165], v[142:145]
	v_mfma_f32_16x16x32_bf16 v[122:125], v[90:93], v[166:169], v[122:125]
	v_mfma_f32_16x16x32_bf16 v[118:121], v[114:117], v[166:169], v[118:121]
	v_mfma_f32_16x16x32_bf16 v[98:101], v[90:93], v[178:181], v[98:101]
	v_mfma_f32_16x16x32_bf16 v[94:97], v[114:117], v[178:181], v[94:97]
	v_mfma_f32_16x16x32_bf16 v[78:81], v[90:93], v[182:185], v[78:81]
	v_mfma_f32_16x16x32_bf16 v[74:77], v[114:117], v[182:185], v[74:77]
	v_mfma_f32_16x16x32_bf16 v[146:149], v[102:105], v[170:173], v[146:149]
	v_mfma_f32_16x16x32_bf16 v[142:145], v[126:129], v[170:173], v[142:145]
	v_mfma_f32_16x16x32_bf16 v[122:125], v[102:105], v[174:177], v[122:125]
	v_mfma_f32_16x16x32_bf16 v[118:121], v[126:129], v[174:177], v[118:121]
	v_mfma_f32_16x16x32_bf16 v[98:101], v[102:105], v[204:207], v[98:101]
	v_mfma_f32_16x16x32_bf16 v[94:97], v[126:129], v[204:207], v[94:97]
	v_mfma_f32_16x16x32_bf16 v[78:81], v[102:105], v[226:229], v[78:81]
	v_mfma_f32_16x16x32_bf16 v[74:77], v[126:129], v[226:229], v[74:77]
	s_setprio 0
	s_setprio 1
	v_mfma_f32_16x16x32_bf16 v[134:137], v[138:141], v[162:165], v[134:137]
	v_mfma_f32_16x16x32_bf16 v[130:133], v[154:157], v[162:165], v[130:133]
	v_mfma_f32_16x16x32_bf16 v[110:113], v[138:141], v[166:169], v[110:113]
	v_mfma_f32_16x16x32_bf16 v[106:109], v[154:157], v[166:169], v[106:109]
	v_mfma_f32_16x16x32_bf16 v[86:89], v[138:141], v[178:181], v[86:89]
	v_mfma_f32_16x16x32_bf16 v[82:85], v[154:157], v[178:181], v[82:85]
	v_mfma_f32_16x16x32_bf16 v[70:73], v[138:141], v[182:185], v[70:73]
	v_mfma_f32_16x16x32_bf16 v[66:69], v[154:157], v[182:185], v[66:69]
	v_mfma_f32_16x16x32_bf16 v[134:137], v[150:153], v[170:173], v[134:137]
	v_mfma_f32_16x16x32_bf16 v[130:133], v[158:161], v[170:173], v[130:133]
	v_mfma_f32_16x16x32_bf16 v[110:113], v[150:153], v[174:177], v[110:113]
	v_mfma_f32_16x16x32_bf16 v[106:109], v[158:161], v[174:177], v[106:109]
	v_mfma_f32_16x16x32_bf16 v[86:89], v[150:153], v[204:207], v[86:89]
	v_mfma_f32_16x16x32_bf16 v[82:85], v[158:161], v[204:207], v[82:85]
	v_mfma_f32_16x16x32_bf16 v[70:73], v[150:153], v[226:229], v[70:73]
	v_mfma_f32_16x16x32_bf16 v[66:69], v[158:161], v[226:229], v[66:69]
	s_setprio 0
	s_barrier
	s_add_i32 s45, s45, s39
	v_lshl_add_u64 v[230:231], v[230:231], 0, s[10:11]
	s_mov_b32 m0, s45
	ds_read_b128 v[162:165], v220 offset:49152
	ds_read_b128 v[166:169], v220 offset:51200
	ds_read_b128 v[170:173], v221 offset:49152
	ds_read_b128 v[174:177], v221 offset:51200
	ds_read_b128 v[178:181], v220 offset:53248
	ds_read_b128 v[182:185], v220 offset:55296
	ds_read_b128 v[204:207], v221 offset:53248
	ds_read_b128 v[226:229], v221 offset:55296
	global_load_lds_dwordx4 v[230:231], off
	s_add_i32 m0, s45, 0x2000
	s_add_u32 s46, s52, 0xb0080
	v_lshl_add_u64 v[230:231], v[232:233], 0, s[10:11]
	s_addc_u32 s47, s53, 0
	s_add_i32 s45, s48, s39
	global_load_lds_dwordx4 v[230:231], off
	v_lshl_add_u64 v[230:231], s[46:47], 0, v[188:189]
	s_mov_b32 m0, s45
	s_nop 0
	global_load_lds_dwordx4 v[230:231], off
	v_lshl_add_u64 v[230:231], s[46:47], 0, v[192:193]
	s_add_i32 m0, s45, 0x2000
	s_nop 0
	global_load_lds_dwordx4 v[230:231], off
	v_lshl_add_u64 v[230:231], v[234:235], 0, s[10:11]
	s_mov_b32 m0, s63
	s_nop 0
	global_load_lds_dwordx4 v[230:231], off
	v_lshl_add_u64 v[230:231], v[236:237], 0, s[10:11]
	s_mov_b32 m0, s64
	s_nop 0
	global_load_lds_dwordx4 v[230:231], off
	s_waitcnt vmcnt(8)
	s_waitcnt lgkmcnt(0)
	s_barrier
	s_setprio 1
	s_waitcnt lgkmcnt(0)
	v_mfma_f32_16x16x32_bf16 v[62:65], v[90:93], v[162:165], v[62:65]
	v_mfma_f32_16x16x32_bf16 v[58:61], v[114:117], v[162:165], v[58:61]
	v_mfma_f32_16x16x32_bf16 v[46:49], v[90:93], v[166:169], v[46:49]
	v_mfma_f32_16x16x32_bf16 v[42:45], v[114:117], v[166:169], v[42:45]
	v_mfma_f32_16x16x32_bf16 v[30:33], v[90:93], v[178:181], v[30:33]
	v_mfma_f32_16x16x32_bf16 v[26:29], v[114:117], v[178:181], v[26:29]
	v_mfma_f32_16x16x32_bf16 v[14:17], v[90:93], v[182:185], v[14:17]
	v_mfma_f32_16x16x32_bf16 v[10:13], v[114:117], v[182:185], v[10:13]
	v_mfma_f32_16x16x32_bf16 v[62:65], v[102:105], v[170:173], v[62:65]
	v_mfma_f32_16x16x32_bf16 v[58:61], v[126:129], v[170:173], v[58:61]
	v_mfma_f32_16x16x32_bf16 v[46:49], v[102:105], v[174:177], v[46:49]
	v_mfma_f32_16x16x32_bf16 v[42:45], v[126:129], v[174:177], v[42:45]
	v_mfma_f32_16x16x32_bf16 v[30:33], v[102:105], v[204:207], v[30:33]
	v_mfma_f32_16x16x32_bf16 v[26:29], v[126:129], v[204:207], v[26:29]
	v_mfma_f32_16x16x32_bf16 v[14:17], v[102:105], v[226:229], v[14:17]
	v_mfma_f32_16x16x32_bf16 v[10:13], v[126:129], v[226:229], v[10:13]
	s_setprio 0
	s_setprio 1
	v_mfma_f32_16x16x32_bf16 v[54:57], v[138:141], v[162:165], v[54:57]
	v_mfma_f32_16x16x32_bf16 v[50:53], v[154:157], v[162:165], v[50:53]
	v_mfma_f32_16x16x32_bf16 v[38:41], v[138:141], v[166:169], v[38:41]
	v_mfma_f32_16x16x32_bf16 v[34:37], v[154:157], v[166:169], v[34:37]
	v_mfma_f32_16x16x32_bf16 v[22:25], v[138:141], v[178:181], v[22:25]
	v_mfma_f32_16x16x32_bf16 v[18:21], v[154:157], v[178:181], v[18:21]
	v_mfma_f32_16x16x32_bf16 v[6:9], v[138:141], v[182:185], v[6:9]
	v_mfma_f32_16x16x32_bf16 v[2:5], v[154:157], v[182:185], v[2:5]
	v_mfma_f32_16x16x32_bf16 v[54:57], v[150:153], v[170:173], v[54:57]
	v_mfma_f32_16x16x32_bf16 v[50:53], v[158:161], v[170:173], v[50:53]
	v_mfma_f32_16x16x32_bf16 v[38:41], v[150:153], v[174:177], v[38:41]
	v_mfma_f32_16x16x32_bf16 v[34:37], v[158:161], v[174:177], v[34:37]
	v_mfma_f32_16x16x32_bf16 v[22:25], v[150:153], v[204:207], v[22:25]
	v_mfma_f32_16x16x32_bf16 v[18:21], v[158:161], v[204:207], v[18:21]
	v_mfma_f32_16x16x32_bf16 v[6:9], v[150:153], v[226:229], v[6:9]
	v_mfma_f32_16x16x32_bf16 v[2:5], v[158:161], v[226:229], v[2:5]
	s_setprio 0
	s_barrier
	s_add_i32 s44, s44, 2
	s_add_u32 s40, s40, 0x100
	s_addc_u32 s41, s41, 0
	s_add_u32 s42, s42, 0x100
	s_addc_u32 s43, s43, 0
	s_cmp_gt_u32 s44, 41
	s_cbranch_scc0 .LBB0_589
	s_branch .Lpx_1
.Lpeel_1:
	s_mov_b32 s100, 0
	ds_read_b128 v[90:93], v212
	ds_read_b128 v[102:105], v213
	ds_read_b128 v[114:117], v214
	ds_read_b128 v[126:129], v215
	ds_read_b128 v[138:141], v216
	ds_read_b128 v[150:153], v217
	ds_read_b128 v[154:157], v218
	ds_read_b128 v[158:161], v219
	s_add_u32 s45, s40, 0xfff50080
	s_addc_u32 s46, s41, -1
	s_cmp_eq_u32 s44, 40
	s_cselect_b32 s55, s1, s46
	s_cselect_b32 s54, s0, s45
	s_cselect_b32 s53, s15, s43
	s_cselect_b32 s52, s14, s42
	v_lshl_add_u64 v[230:231], s[40:41], 0, v[196:197]
	s_add_i32 m0, s56, 0xc000
	ds_read_b128 v[162:165], v220
	ds_read_b128 v[166:169], v220 offset:2048
	ds_read_b128 v[170:173], v221
	ds_read_b128 v[174:177], v221 offset:2048
	ds_read_b128 v[178:181], v220 offset:4096
	ds_read_b128 v[182:185], v220 offset:6144
	ds_read_b128 v[204:207], v221 offset:4096
	ds_read_b128 v[226:229], v221 offset:6144
	global_load_lds_dwordx4 v[230:231], off
	v_lshl_add_u64 v[230:231], s[40:41], 0, v[198:199]
	s_add_i32 m0, s56, 0xe000
	s_nop 0
	global_load_lds_dwordx4 v[230:231], off
	s_waitcnt vmcnt(8)
	s_waitcnt lgkmcnt(0)
	s_barrier
	s_setprio 1
	s_waitcnt lgkmcnt(0)
	v_mfma_f32_16x16x32_bf16 v[146:149], v[90:93], v[162:165], 0
	v_mfma_f32_16x16x32_bf16 v[142:145], v[114:117], v[162:165], 0
	v_mfma_f32_16x16x32_bf16 v[122:125], v[90:93], v[166:169], 0
	v_mfma_f32_16x16x32_bf16 v[118:121], v[114:117], v[166:169], 0
	v_mfma_f32_16x16x32_bf16 v[98:101], v[90:93], v[178:181], 0
	v_mfma_f32_16x16x32_bf16 v[94:97], v[114:117], v[178:181], 0
	v_mfma_f32_16x16x32_bf16 v[78:81], v[90:93], v[182:185], 0
	v_mfma_f32_16x16x32_bf16 v[74:77], v[114:117], v[182:185], 0
	v_mfma_f32_16x16x32_bf16 v[146:149], v[102:105], v[170:173], v[146:149]
	v_mfma_f32_16x16x32_bf16 v[142:145], v[126:129], v[170:173], v[142:145]
	v_mfma_f32_16x16x32_bf16 v[122:125], v[102:105], v[174:177], v[122:125]
	v_mfma_f32_16x16x32_bf16 v[118:121], v[126:129], v[174:177], v[118:121]
	v_mfma_f32_16x16x32_bf16 v[98:101], v[102:105], v[204:207], v[98:101]
	v_mfma_f32_16x16x32_bf16 v[94:97], v[126:129], v[204:207], v[94:97]
	v_mfma_f32_16x16x32_bf16 v[78:81], v[102:105], v[226:229], v[78:81]
	v_mfma_f32_16x16x32_bf16 v[74:77], v[126:129], v[226:229], v[74:77]
	s_setprio 0
	s_setprio 1
	v_mfma_f32_16x16x32_bf16 v[134:137], v[138:141], v[162:165], 0
	v_mfma_f32_16x16x32_bf16 v[130:133], v[154:157], v[162:165], 0
	v_mfma_f32_16x16x32_bf16 v[110:113], v[138:141], v[166:169], 0
	v_mfma_f32_16x16x32_bf16 v[106:109], v[154:157], v[166:169], 0
	v_mfma_f32_16x16x32_bf16 v[86:89], v[138:141], v[178:181], 0
	v_mfma_f32_16x16x32_bf16 v[82:85], v[154:157], v[178:181], 0
	v_mfma_f32_16x16x32_bf16 v[70:73], v[138:141], v[182:185], 0
	v_mfma_f32_16x16x32_bf16 v[66:69], v[154:157], v[182:185], 0
	v_mfma_f32_16x16x32_bf16 v[134:137], v[150:153], v[170:173], v[134:137]
	v_mfma_f32_16x16x32_bf16 v[130:133], v[158:161], v[170:173], v[130:133]
	v_mfma_f32_16x16x32_bf16 v[110:113], v[150:153], v[174:177], v[110:113]
	v_mfma_f32_16x16x32_bf16 v[106:109], v[158:161], v[174:177], v[106:109]
	v_mfma_f32_16x16x32_bf16 v[86:89], v[150:153], v[204:207], v[86:89]
	v_mfma_f32_16x16x32_bf16 v[82:85], v[158:161], v[204:207], v[82:85]
	v_mfma_f32_16x16x32_bf16 v[70:73], v[150:153], v[226:229], v[70:73]
	v_mfma_f32_16x16x32_bf16 v[66:69], v[158:161], v[226:229], v[66:69]
	s_setprio 0
	s_barrier
	s_add_i32 s45, s68, s39
	v_lshl_add_u64 v[230:231], s[52:53], 0, v[188:189]
	s_mov_b32 m0, s45
	ds_read_b128 v[162:165], v220 offset:16384
	ds_read_b128 v[166:169], v220 offset:18432
	ds_read_b128 v[170:173], v221 offset:16384
	ds_read_b128 v[174:177], v221 offset:18432
	ds_read_b128 v[178:181], v220 offset:20480
	ds_read_b128 v[182:185], v220 offset:22528
	ds_read_b128 v[204:207], v221 offset:20480
	ds_read_b128 v[226:229], v221 offset:22528
	global_load_lds_dwordx4 v[230:231], off
	s_add_i32 m0, s45, 0x2000
	s_add_u32 s46, s52, 0xb0000
	v_lshl_add_u64 v[232:233], s[52:53], 0, v[192:193]
	s_addc_u32 s47, s53, 0
	s_add_i32 s45, s69, s39
	global_load_lds_dwordx4 v[232:233], off
	v_lshl_add_u64 v[234:235], s[46:47], 0, v[188:189]
	s_mov_b32 m0, s45
	v_lshl_add_u64 v[236:237], s[54:55], 0, v[190:191]
	global_load_lds_dwordx4 v[234:235], off
	v_lshl_add_u64 v[234:235], s[46:47], 0, v[192:193]
	s_add_i32 m0, s45, 0x2000
	s_nop 0
	global_load_lds_dwordx4 v[234:235], off
	v_lshl_add_u64 v[234:235], s[54:55], 0, v[186:187]
	s_mov_b32 m0, s56
	s_nop 0
	global_load_lds_dwordx4 v[234:235], off
	s_mov_b32 m0, s57
	s_nop 0
	global_load_lds_dwordx4 v[236:237], off
	s_waitcnt vmcnt(8)
	s_waitcnt lgkmcnt(0)
	s_barrier
	s_setprio 1
	s_waitcnt lgkmcnt(0)
	v_mfma_f32_16x16x32_bf16 v[62:65], v[90:93], v[162:165], 0
	v_mfma_f32_16x16x32_bf16 v[58:61], v[114:117], v[162:165], 0
	v_mfma_f32_16x16x32_bf16 v[46:49], v[90:93], v[166:169], 0
	v_mfma_f32_16x16x32_bf16 v[42:45], v[114:117], v[166:169], 0
	v_mfma_f32_16x16x32_bf16 v[30:33], v[90:93], v[178:181], 0
	v_mfma_f32_16x16x32_bf16 v[26:29], v[114:117], v[178:181], 0
	v_mfma_f32_16x16x32_bf16 v[14:17], v[90:93], v[182:185], 0
	v_mfma_f32_16x16x32_bf16 v[10:13], v[114:117], v[182:185], 0
	v_mfma_f32_16x16x32_bf16 v[62:65], v[102:105], v[170:173], v[62:65]
	v_mfma_f32_16x16x32_bf16 v[58:61], v[126:129], v[170:173], v[58:61]
	v_mfma_f32_16x16x32_bf16 v[46:49], v[102:105], v[174:177], v[46:49]
	v_mfma_f32_16x16x32_bf16 v[42:45], v[126:129], v[174:177], v[42:45]
	v_mfma_f32_16x16x32_bf16 v[30:33], v[102:105], v[204:207], v[30:33]
	v_mfma_f32_16x16x32_bf16 v[26:29], v[126:129], v[204:207], v[26:29]
	v_mfma_f32_16x16x32_bf16 v[14:17], v[102:105], v[226:229], v[14:17]
	v_mfma_f32_16x16x32_bf16 v[10:13], v[126:129], v[226:229], v[10:13]
	s_setprio 0
	s_setprio 1
	v_mfma_f32_16x16x32_bf16 v[54:57], v[138:141], v[162:165], 0
	v_mfma_f32_16x16x32_bf16 v[50:53], v[154:157], v[162:165], 0
	v_mfma_f32_16x16x32_bf16 v[38:41], v[138:141], v[166:169], 0
	v_mfma_f32_16x16x32_bf16 v[34:37], v[154:157], v[166:169], 0
	v_mfma_f32_16x16x32_bf16 v[22:25], v[138:141], v[178:181], 0
	v_mfma_f32_16x16x32_bf16 v[18:21], v[154:157], v[178:181], 0
	v_mfma_f32_16x16x32_bf16 v[6:9], v[138:141], v[182:185], 0
	v_mfma_f32_16x16x32_bf16 v[2:5], v[154:157], v[182:185], 0
	v_mfma_f32_16x16x32_bf16 v[54:57], v[150:153], v[170:173], v[54:57]
	v_mfma_f32_16x16x32_bf16 v[50:53], v[158:161], v[170:173], v[50:53]
	v_mfma_f32_16x16x32_bf16 v[38:41], v[150:153], v[174:177], v[38:41]
	v_mfma_f32_16x16x32_bf16 v[34:37], v[158:161], v[174:177], v[34:37]
	v_mfma_f32_16x16x32_bf16 v[22:25], v[150:153], v[204:207], v[22:25]
	v_mfma_f32_16x16x32_bf16 v[18:21], v[158:161], v[204:207], v[18:21]
	v_mfma_f32_16x16x32_bf16 v[6:9], v[150:153], v[226:229], v[6:9]
	v_mfma_f32_16x16x32_bf16 v[2:5], v[158:161], v[226:229], v[2:5]
	s_setprio 0
	s_barrier
	s_add_i32 s45, 0, 0x18000
	s_add_i32 s48, 0, 0x1c000
	v_add_u32_e32 v90, s45, v210
	v_add_u32_e32 v102, s45, v211
	v_add_u32_e32 v138, s48, v210
	v_add_u32_e32 v150, s48, v211
	ds_read_b128 v[90:93], v90
	ds_read_b128 v[102:105], v102
	ds_read_b128 v[114:117], v222
	ds_read_b128 v[126:129], v223
	ds_read_b128 v[138:141], v138
	ds_read_b128 v[150:153], v150
	ds_read_b128 v[154:157], v224
	ds_read_b128 v[158:161], v225
	s_add_u32 s46, s54, 0xb0000
	s_addc_u32 s47, s55, 0
	s_mov_b32 m0, s58
	v_lshl_add_u64 v[238:239], s[46:47], 0, v[186:187]
	ds_read_b128 v[162:165], v220 offset:32768
	ds_read_b128 v[166:169], v220 offset:34816
	ds_read_b128 v[170:173], v221 offset:32768
	ds_read_b128 v[174:177], v221 offset:34816
	ds_read_b128 v[178:181], v220 offset:36864
	ds_read_b128 v[182:185], v220 offset:38912
	ds_read_b128 v[204:207], v221 offset:36864
	ds_read_b128 v[226:229], v221 offset:38912
	global_load_lds_dwordx4 v[238:239], off
	v_lshl_add_u64 v[238:239], s[46:47], 0, v[190:191]
	s_mov_b32 m0, s59
	s_nop 0
	global_load_lds_dwordx4 v[238:239], off
	s_waitcnt vmcnt(8)
	s_waitcnt lgkmcnt(0)
	s_barrier
	s_setprio 1
	s_waitcnt lgkmcnt(0)
	v_mfma_f32_16x16x32_bf16 v[146:149], v[90:93], v[162:165], v[146:149]
	v_mfma_f32_16x16x32_bf16 v[142:145], v[114:117], v[162:165], v[142:145]
	v_mfma_f32_16x16x32_bf16 v[122:125], v[90:93], v[166:169], v[122:125]
	v_mfma_f32_16x16x32_bf16 v[118:121], v[114:117], v[166:169], v[118:121]
	v_mfma_f32_16x16x32_bf16 v[98:101], v[90:93], v[178:181], v[98:101]
	v_mfma_f32_16x16x32_bf16 v[94:97], v[114:117], v[178:181], v[94:97]
	v_mfma_f32_16x16x32_bf16 v[78:81], v[90:93], v[182:185], v[78:81]
	v_mfma_f32_16x16x32_bf16 v[74:77], v[114:117], v[182:185], v[74:77]
	v_mfma_f32_16x16x32_bf16 v[146:149], v[102:105], v[170:173], v[146:149]
	v_mfma_f32_16x16x32_bf16 v[142:145], v[126:129], v[170:173], v[142:145]
	v_mfma_f32_16x16x32_bf16 v[122:125], v[102:105], v[174:177], v[122:125]
	v_mfma_f32_16x16x32_bf16 v[118:121], v[126:129], v[174:177], v[118:121]
	v_mfma_f32_16x16x32_bf16 v[98:101], v[102:105], v[204:207], v[98:101]
	v_mfma_f32_16x16x32_bf16 v[94:97], v[126:129], v[204:207], v[94:97]
	v_mfma_f32_16x16x32_bf16 v[78:81], v[102:105], v[226:229], v[78:81]
	v_mfma_f32_16x16x32_bf16 v[74:77], v[126:129], v[226:229], v[74:77]
	s_setprio 0
	s_setprio 1
	v_mfma_f32_16x16x32_bf16 v[134:137], v[138:141], v[162:165], v[134:137]
	v_mfma_f32_16x16x32_bf16 v[130:133], v[154:157], v[162:165], v[130:133]
	v_mfma_f32_16x16x32_bf16 v[110:113], v[138:141], v[166:169], v[110:113]
	v_mfma_f32_16x16x32_bf16 v[106:109], v[154:157], v[166:169], v[106:109]
	v_mfma_f32_16x16x32_bf16 v[86:89], v[138:141], v[178:181], v[86:89]
	v_mfma_f32_16x16x32_bf16 v[82:85], v[154:157], v[178:181], v[82:85]
	v_mfma_f32_16x16x32_bf16 v[70:73], v[138:141], v[182:185], v[70:73]
	v_mfma_f32_16x16x32_bf16 v[66:69], v[154:157], v[182:185], v[66:69]
	v_mfma_f32_16x16x32_bf16 v[134:137], v[150:153], v[170:173], v[134:137]
	v_mfma_f32_16x16x32_bf16 v[130:133], v[158:161], v[170:173], v[130:133]
	v_mfma_f32_16x16x32_bf16 v[110:113], v[150:153], v[174:177], v[110:113]
	v_mfma_f32_16x16x32_bf16 v[106:109], v[158:161], v[174:177], v[106:109]
	v_mfma_f32_16x16x32_bf16 v[86:89], v[150:153], v[204:207], v[86:89]
	v_mfma_f32_16x16x32_bf16 v[82:85], v[158:161], v[204:207], v[82:85]
	v_mfma_f32_16x16x32_bf16 v[70:73], v[150:153], v[226:229], v[70:73]
	v_mfma_f32_16x16x32_bf16 v[66:69], v[158:161], v[226:229], v[66:69]
	s_setprio 0
	s_barrier
	s_add_i32 s45, s45, s39
	v_lshl_add_u64 v[230:231], v[230:231], 0, s[10:11]
	s_mov_b32 m0, s45
	ds_read_b128 v[162:165], v220 offset:49152
	ds_read_b128 v[166:169], v220 offset:51200
	ds_read_b128 v[170:173], v221 offset:49152
	ds_read_b128 v[174:177], v221 offset:51200
	ds_read_b128 v[178:181], v220 offset:53248
	ds_read_b128 v[182:185], v220 offset:55296
	ds_read_b128 v[204:207], v221 offset:53248
	ds_read_b128 v[226:229], v221 offset:55296
	global_load_lds_dwordx4 v[230:231], off
	s_add_i32 m0, s45, 0x2000
	s_add_u32 s46, s52, 0xb0080
	v_lshl_add_u64 v[230:231], v[232:233], 0, s[10:11]
	s_addc_u32 s47, s53, 0
	s_add_i32 s45, s48, s39
	global_load_lds_dwordx4 v[230:231], off
	v_lshl_add_u64 v[230:231], s[46:47], 0, v[188:189]
	s_mov_b32 m0, s45
	s_nop 0
	global_load_lds_dwordx4 v[230:231], off
	v_lshl_add_u64 v[230:231], s[46:47], 0, v[192:193]
	s_add_i32 m0, s45, 0x2000
	s_nop 0
	global_load_lds_dwordx4 v[230:231], off
	v_lshl_add_u64 v[230:231], v[234:235], 0, s[10:11]
	s_mov_b32 m0, s63
	s_nop 0
	global_load_lds_dwordx4 v[230:231], off
	v_lshl_add_u64 v[230:231], v[236:237], 0, s[10:11]
	s_mov_b32 m0, s64
	s_nop 0
	global_load_lds_dwordx4 v[230:231], off
	s_waitcnt vmcnt(8)
	s_waitcnt lgkmcnt(0)
	s_barrier
	s_setprio 1
	s_waitcnt lgkmcnt(0)
	v_mfma_f32_16x16x32_bf16 v[62:65], v[90:93], v[162:165], v[62:65]
	v_mfma_f32_16x16x32_bf16 v[58:61], v[114:117], v[162:165], v[58:61]
	v_mfma_f32_16x16x32_bf16 v[46:49], v[90:93], v[166:169], v[46:49]
	v_mfma_f32_16x16x32_bf16 v[42:45], v[114:117], v[166:169], v[42:45]
	v_mfma_f32_16x16x32_bf16 v[30:33], v[90:93], v[178:181], v[30:33]
	v_mfma_f32_16x16x32_bf16 v[26:29], v[114:117], v[178:181], v[26:29]
	v_mfma_f32_16x16x32_bf16 v[14:17], v[90:93], v[182:185], v[14:17]
	v_mfma_f32_16x16x32_bf16 v[10:13], v[114:117], v[182:185], v[10:13]
	v_mfma_f32_16x16x32_bf16 v[62:65], v[102:105], v[170:173], v[62:65]
	v_mfma_f32_16x16x32_bf16 v[58:61], v[126:129], v[170:173], v[58:61]
	v_mfma_f32_16x16x32_bf16 v[46:49], v[102:105], v[174:177], v[46:49]
	v_mfma_f32_16x16x32_bf16 v[42:45], v[126:129], v[174:177], v[42:45]
	v_mfma_f32_16x16x32_bf16 v[30:33], v[102:105], v[204:207], v[30:33]
	v_mfma_f32_16x16x32_bf16 v[26:29], v[126:129], v[204:207], v[26:29]
	v_mfma_f32_16x16x32_bf16 v[14:17], v[102:105], v[226:229], v[14:17]
	v_mfma_f32_16x16x32_bf16 v[10:13], v[126:129], v[226:229], v[10:13]
	s_setprio 0
	s_setprio 1
	v_mfma_f32_16x16x32_bf16 v[54:57], v[138:141], v[162:165], v[54:57]
	v_mfma_f32_16x16x32_bf16 v[50:53], v[154:157], v[162:165], v[50:53]
	v_mfma_f32_16x16x32_bf16 v[38:41], v[138:141], v[166:169], v[38:41]
	v_mfma_f32_16x16x32_bf16 v[34:37], v[154:157], v[166:169], v[34:37]
	v_mfma_f32_16x16x32_bf16 v[22:25], v[138:141], v[178:181], v[22:25]
	v_mfma_f32_16x16x32_bf16 v[18:21], v[154:157], v[178:181], v[18:21]
	v_mfma_f32_16x16x32_bf16 v[6:9], v[138:141], v[182:185], v[6:9]
	v_mfma_f32_16x16x32_bf16 v[2:5], v[154:157], v[182:185], v[2:5]
	v_mfma_f32_16x16x32_bf16 v[54:57], v[150:153], v[170:173], v[54:57]
	v_mfma_f32_16x16x32_bf16 v[50:53], v[158:161], v[170:173], v[50:53]
	v_mfma_f32_16x16x32_bf16 v[38:41], v[150:153], v[174:177], v[38:41]
	v_mfma_f32_16x16x32_bf16 v[34:37], v[158:161], v[174:177], v[34:37]
	v_mfma_f32_16x16x32_bf16 v[22:25], v[150:153], v[204:207], v[22:25]
	v_mfma_f32_16x16x32_bf16 v[18:21], v[158:161], v[204:207], v[18:21]
	v_mfma_f32_16x16x32_bf16 v[6:9], v[150:153], v[226:229], v[6:9]
	v_mfma_f32_16x16x32_bf16 v[2:5], v[158:161], v[226:229], v[2:5]
	s_setprio 0
	s_barrier
	s_add_i32 s44, s44, 2
	s_add_u32 s40, s40, 0x100
	s_addc_u32 s41, s41, 0
	s_add_u32 s42, s42, 0x100
	s_addc_u32 s43, s43, 0
	s_cmp_gt_u32 s44, 41
	s_cbranch_scc0 .LBB0_589
.Lpx_1:
	s_and_b64 vcc, exec, s[12:13]
	s_cbranch_vccz .LBB0_592
	s_barrier

.LBB0_683:
	s_ashr_i32 s5, s4, 31
	s_lshl_b64 s[38:39], s[4:5], 19
	v_readlane_b32 s16, v244, 44
	v_readlane_b32 s17, v244, 45
	s_add_u32 s72, s16, s38
	s_addc_u32 s73, s17, s39
	s_and_b64 s[38:39], s[6:7], exec
	s_cselect_b32 s5, s73, s11
	s_cselect_b32 s38, s72, s10
	s_ashr_i32 s13, s12, 31
	s_lshl_b64 s[42:43], s[12:13], 19
	s_add_u32 s70, s3, s42
	s_addc_u32 s71, s34, s43
	s_and_b64 s[42:43], s[6:7], exec
	s_cselect_b32 s13, s71, s87
	s_cselect_b32 s39, s70, s86
	s_lshl_b32 s44, s52, 10
	s_lshl_b32 s42, s4, 8
	s_add_i32 s53, s44, 0
	s_ashr_i32 s43, s42, 31
	s_add_i32 s53, s53, 0x20800
	s_add_u32 s10, s10, 0x40080
	s_addc_u32 s11, s11, 0
	s_add_u32 s68, s86, 0x100
	s_mov_b32 s100, 1
	s_waitcnt vmcnt(0)
	v_lshl_add_u64 v[130:131], s[42:43], 2, v[172:173]
	s_addc_u32 s69, s87, 0
	s_mov_b32 s42, -2
	s_branch .LBB0_685
.LBB0_684:
	s_cmp_lg_u32 s100, 0
	s_cbranch_scc1 .Lpeel_2
	v_add_u32_e32 v132, s78, v213
	v_add_u32_e32 v136, s78, v214
	v_add_u32_e32 v140, s79, v213
	v_add_u32_e32 v144, s79, v214
	v_add_u32_e32 v148, s82, v213
	v_add_u32_e32 v152, s82, v214
	v_add_u32_e32 v156, s62, v213
	v_add_u32_e32 v160, s62, v214
	ds_read_b128 v[132:135], v132
	ds_read_b128 v[136:139], v136
	ds_read_b128 v[140:143], v140
	ds_read_b128 v[144:147], v144
	ds_read_b128 v[148:151], v148
	ds_read_b128 v[152:155], v152
	ds_read_b128 v[156:159], v156
	ds_read_b128 v[160:163], v160
	s_add_u32 s43, s10, 0xfffc0080
	s_addc_u32 s46, s11, -1
	s_and_b64 s[44:45], s[86:87], exec
	s_cselect_b32 vcc_hi, s5, s46
	s_cselect_b32 vcc_lo, s38, s43
	s_cselect_b32 s87, s13, s69
	s_cselect_b32 s86, s39, s68
	v_lshl_add_u64 v[168:169], s[10:11], 0, v[180:181]
	s_add_i32 m0, s88, 0xc000
	ds_read_b128 v[164:167], v215
	s_waitcnt lgkmcnt(0)
	ds_read_b128 v[190:193], v215 offset:2048
	ds_read_b128 v[194:197], v216
	ds_read_b128 v[198:201], v216 offset:2048
	ds_read_b128 v[202:205], v215 offset:4096
	ds_read_b128 v[206:209], v215 offset:6144
	ds_read_b128 v[218:221], v216 offset:4096
	ds_read_b128 v[222:225], v216 offset:6144
	global_load_lds_dwordx4 v[168:169], off
	v_lshl_add_u64 v[168:169], s[10:11], 0, v[184:185]
	s_add_i32 m0, s88, 0xe000
	s_nop 0
	global_load_lds_dwordx4 v[168:169], off
	s_waitcnt vmcnt(8)
	s_waitcnt lgkmcnt(0)
	s_barrier
	s_setprio 1
	s_waitcnt lgkmcnt(0)
	v_mfma_f32_16x16x32_bf16 v[126:129], v[132:135], v[164:167], v[126:129]
	v_mfma_f32_16x16x32_bf16 v[122:125], v[140:143], v[164:167], v[122:125]
	v_mfma_f32_16x16x32_bf16 v[110:113], v[132:135], v[190:193], v[110:113]
	v_mfma_f32_16x16x32_bf16 v[106:109], v[140:143], v[190:193], v[106:109]
	v_mfma_f32_16x16x32_bf16 v[94:97], v[132:135], v[202:205], v[94:97]
	v_mfma_f32_16x16x32_bf16 v[90:93], v[140:143], v[202:205], v[90:93]
	v_mfma_f32_16x16x32_bf16 v[78:81], v[132:135], v[206:209], v[78:81]
	v_mfma_f32_16x16x32_bf16 v[74:77], v[140:143], v[206:209], v[74:77]
	v_mfma_f32_16x16x32_bf16 v[126:129], v[136:139], v[194:197], v[126:129]
	v_mfma_f32_16x16x32_bf16 v[122:125], v[144:147], v[194:197], v[122:125]
	v_mfma_f32_16x16x32_bf16 v[110:113], v[136:139], v[198:201], v[110:113]
	v_mfma_f32_16x16x32_bf16 v[106:109], v[144:147], v[198:201], v[106:109]
	v_mfma_f32_16x16x32_bf16 v[94:97], v[136:139], v[218:221], v[94:97]
	v_mfma_f32_16x16x32_bf16 v[90:93], v[144:147], v[218:221], v[90:93]
	v_mfma_f32_16x16x32_bf16 v[78:81], v[136:139], v[222:225], v[78:81]
	v_mfma_f32_16x16x32_bf16 v[74:77], v[144:147], v[222:225], v[74:77]
	s_setprio 0
	s_setprio 1
	v_mfma_f32_16x16x32_bf16 v[118:121], v[148:151], v[164:167], v[118:121]
	v_mfma_f32_16x16x32_bf16 v[114:117], v[156:159], v[164:167], v[114:117]
	v_mfma_f32_16x16x32_bf16 v[102:105], v[148:151], v[190:193], v[102:105]
	v_mfma_f32_16x16x32_bf16 v[98:101], v[156:159], v[190:193], v[98:101]
	v_mfma_f32_16x16x32_bf16 v[86:89], v[148:151], v[202:205], v[86:89]
	v_mfma_f32_16x16x32_bf16 v[82:85], v[156:159], v[202:205], v[82:85]
	v_mfma_f32_16x16x32_bf16 v[70:73], v[148:151], v[206:209], v[70:73]
	v_mfma_f32_16x16x32_bf16 v[66:69], v[156:159], v[206:209], v[66:69]
	v_mfma_f32_16x16x32_bf16 v[118:121], v[152:155], v[194:197], v[118:121]
	v_mfma_f32_16x16x32_bf16 v[114:117], v[160:163], v[194:197], v[114:117]
	v_mfma_f32_16x16x32_bf16 v[102:105], v[152:155], v[198:201], v[102:105]
	v_mfma_f32_16x16x32_bf16 v[98:101], v[160:163], v[198:201], v[98:101]
	v_mfma_f32_16x16x32_bf16 v[86:89], v[152:155], v[218:221], v[86:89]
	v_mfma_f32_16x16x32_bf16 v[82:85], v[160:163], v[218:221], v[82:85]
	v_mfma_f32_16x16x32_bf16 v[70:73], v[152:155], v[222:225], v[70:73]
	v_mfma_f32_16x16x32_bf16 v[66:69], v[160:163], v[222:225], v[66:69]
	s_setprio 0
	s_barrier
	s_add_i32 s43, s78, s15
	v_lshl_add_u64 v[168:169], s[86:87], 0, v[170:171]
	s_mov_b32 m0, s43
	ds_read_b128 v[164:167], v215 offset:16384
	ds_read_b128 v[190:193], v215 offset:18432
	ds_read_b128 v[194:197], v216 offset:16384
	ds_read_b128 v[198:201], v216 offset:18432
	ds_read_b128 v[202:205], v215 offset:20480
	ds_read_b128 v[206:209], v215 offset:22528
	ds_read_b128 v[218:221], v216 offset:20480
	ds_read_b128 v[222:225], v216 offset:22528
	global_load_lds_dwordx4 v[168:169], off
	s_add_i32 m0, s43, 0x2000
	s_add_u32 s44, s86, 0x40000
	v_lshl_add_u64 v[226:227], s[86:87], 0, v[178:179]
	s_addc_u32 s45, s87, 0
	s_add_i32 s43, s82, s15
	global_load_lds_dwordx4 v[226:227], off
	v_lshl_add_u64 v[228:229], s[44:45], 0, v[170:171]
	s_mov_b32 m0, s43
	v_lshl_add_u64 v[230:231], vcc, 0, v[176:177]
	global_load_lds_dwordx4 v[228:229], off
	v_lshl_add_u64 v[228:229], s[44:45], 0, v[178:179]
	s_add_i32 m0, s43, 0x2000
	s_nop 0
	global_load_lds_dwordx4 v[228:229], off
	v_lshl_add_u64 v[228:229], vcc, 0, v[174:175]
	s_mov_b32 m0, s88
	s_nop 0
	global_load_lds_dwordx4 v[228:229], off
	s_mov_b32 m0, s89
	s_nop 0
	global_load_lds_dwordx4 v[230:231], off
	s_waitcnt vmcnt(8)
	s_waitcnt lgkmcnt(0)
	s_barrier
	s_setprio 1
	s_waitcnt lgkmcnt(0)
	v_mfma_f32_16x16x32_bf16 v[62:65], v[132:135], v[164:167], v[62:65]
	v_mfma_f32_16x16x32_bf16 v[58:61], v[140:143], v[164:167], v[58:61]
	v_mfma_f32_16x16x32_bf16 v[46:49], v[132:135], v[190:193], v[46:49]
	v_mfma_f32_16x16x32_bf16 v[42:45], v[140:143], v[190:193], v[42:45]
	v_mfma_f32_16x16x32_bf16 v[30:33], v[132:135], v[202:205], v[30:33]
	v_mfma_f32_16x16x32_bf16 v[26:29], v[140:143], v[202:205], v[26:29]
	v_mfma_f32_16x16x32_bf16 v[14:17], v[132:135], v[206:209], v[14:17]
	v_mfma_f32_16x16x32_bf16 v[10:13], v[140:143], v[206:209], v[10:13]
	v_mfma_f32_16x16x32_bf16 v[62:65], v[136:139], v[194:197], v[62:65]
	v_mfma_f32_16x16x32_bf16 v[58:61], v[144:147], v[194:197], v[58:61]
	v_mfma_f32_16x16x32_bf16 v[46:49], v[136:139], v[198:201], v[46:49]
	v_mfma_f32_16x16x32_bf16 v[42:45], v[144:147], v[198:201], v[42:45]
	v_mfma_f32_16x16x32_bf16 v[30:33], v[136:139], v[218:221], v[30:33]
	v_mfma_f32_16x16x32_bf16 v[26:29], v[144:147], v[218:221], v[26:29]
	v_mfma_f32_16x16x32_bf16 v[14:17], v[136:139], v[222:225], v[14:17]
	v_mfma_f32_16x16x32_bf16 v[10:13], v[144:147], v[222:225], v[10:13]
	s_setprio 0
	s_setprio 1
	v_mfma_f32_16x16x32_bf16 v[54:57], v[148:151], v[164:167], v[54:57]
	v_mfma_f32_16x16x32_bf16 v[50:53], v[156:159], v[164:167], v[50:53]
	v_mfma_f32_16x16x32_bf16 v[38:41], v[148:151], v[190:193], v[38:41]
	v_mfma_f32_16x16x32_bf16 v[34:37], v[156:159], v[190:193], v[34:37]
	v_mfma_f32_16x16x32_bf16 v[22:25], v[148:151], v[202:205], v[22:25]
	v_mfma_f32_16x16x32_bf16 v[18:21], v[156:159], v[202:205], v[18:21]
	v_mfma_f32_16x16x32_bf16 v[6:9], v[148:151], v[206:209], v[6:9]
	v_mfma_f32_16x16x32_bf16 v[2:5], v[156:159], v[206:209], v[2:5]
	v_mfma_f32_16x16x32_bf16 v[54:57], v[152:155], v[194:197], v[54:57]
	v_mfma_f32_16x16x32_bf16 v[50:53], v[160:163], v[194:197], v[50:53]
	v_mfma_f32_16x16x32_bf16 v[38:41], v[152:155], v[198:201], v[38:41]
	v_mfma_f32_16x16x32_bf16 v[34:37], v[160:163], v[198:201], v[34:37]
	v_mfma_f32_16x16x32_bf16 v[22:25], v[152:155], v[218:221], v[22:25]
	v_mfma_f32_16x16x32_bf16 v[18:21], v[160:163], v[218:221], v[18:21]
	v_mfma_f32_16x16x32_bf16 v[6:9], v[152:155], v[222:225], v[6:9]
	v_mfma_f32_16x16x32_bf16 v[2:5], v[160:163], v[222:225], v[2:5]
	s_setprio 0
	s_barrier
	s_add_i32 s43, 0, 0x18000
	s_add_i32 s46, 0, 0x1c000
	v_add_u32_e32 v132, s43, v213
	v_add_u32_e32 v136, s43, v214
	v_add_u32_e32 v140, s63, v213
	v_add_u32_e32 v144, s63, v214
	v_add_u32_e32 v148, s46, v213
	v_add_u32_e32 v152, s46, v214
	v_add_u32_e32 v156, s64, v213
	v_add_u32_e32 v160, s64, v214
	ds_read_b128 v[132:135], v132
	ds_read_b128 v[136:139], v136
	ds_read_b128 v[140:143], v140
	ds_read_b128 v[144:147], v144
	ds_read_b128 v[148:151], v148
	ds_read_b128 v[152:155], v152
	ds_read_b128 v[156:159], v156
	ds_read_b128 v[160:163], v160
	s_add_u32 s44, vcc_lo, 0x40000
	s_addc_u32 s45, vcc_hi, 0
	s_mov_b32 m0, s94
	v_lshl_add_u64 v[232:233], s[44:45], 0, v[174:175]
	ds_read_b128 v[164:167], v215 offset:32768
	ds_read_b128 v[190:193], v215 offset:34816
	ds_read_b128 v[194:197], v216 offset:32768
	ds_read_b128 v[198:201], v216 offset:34816
	ds_read_b128 v[202:205], v215 offset:36864
	ds_read_b128 v[206:209], v215 offset:38912
	ds_read_b128 v[218:221], v216 offset:36864
	ds_read_b128 v[222:225], v216 offset:38912
	global_load_lds_dwordx4 v[232:233], off
	v_lshl_add_u64 v[232:233], s[44:45], 0, v[176:177]
	s_mov_b32 m0, s95
	s_nop 0
	global_load_lds_dwordx4 v[232:233], off
	s_waitcnt vmcnt(8)
	s_waitcnt lgkmcnt(0)
	s_barrier
	s_setprio 1
	s_waitcnt lgkmcnt(0)
	v_mfma_f32_16x16x32_bf16 v[126:129], v[132:135], v[164:167], v[126:129]
	v_mfma_f32_16x16x32_bf16 v[122:125], v[140:143], v[164:167], v[122:125]
	v_mfma_f32_16x16x32_bf16 v[110:113], v[132:135], v[190:193], v[110:113]
	v_mfma_f32_16x16x32_bf16 v[106:109], v[140:143], v[190:193], v[106:109]
	v_mfma_f32_16x16x32_bf16 v[94:97], v[132:135], v[202:205], v[94:97]
	v_mfma_f32_16x16x32_bf16 v[90:93], v[140:143], v[202:205], v[90:93]
	v_mfma_f32_16x16x32_bf16 v[78:81], v[132:135], v[206:209], v[78:81]
	v_mfma_f32_16x16x32_bf16 v[74:77], v[140:143], v[206:209], v[74:77]
	v_mfma_f32_16x16x32_bf16 v[126:129], v[136:139], v[194:197], v[126:129]
	v_mfma_f32_16x16x32_bf16 v[122:125], v[144:147], v[194:197], v[122:125]
	v_mfma_f32_16x16x32_bf16 v[110:113], v[136:139], v[198:201], v[110:113]
	v_mfma_f32_16x16x32_bf16 v[106:109], v[144:147], v[198:201], v[106:109]
	v_mfma_f32_16x16x32_bf16 v[94:97], v[136:139], v[218:221], v[94:97]
	v_mfma_f32_16x16x32_bf16 v[90:93], v[144:147], v[218:221], v[90:93]
	v_mfma_f32_16x16x32_bf16 v[78:81], v[136:139], v[222:225], v[78:81]
	v_mfma_f32_16x16x32_bf16 v[74:77], v[144:147], v[222:225], v[74:77]
	s_setprio 0
	s_setprio 1
	v_mfma_f32_16x16x32_bf16 v[118:121], v[148:151], v[164:167], v[118:121]
	v_mfma_f32_16x16x32_bf16 v[114:117], v[156:159], v[164:167], v[114:117]
	v_mfma_f32_16x16x32_bf16 v[102:105], v[148:151], v[190:193], v[102:105]
	v_mfma_f32_16x16x32_bf16 v[98:101], v[156:159], v[190:193], v[98:101]
	v_mfma_f32_16x16x32_bf16 v[86:89], v[148:151], v[202:205], v[86:89]
	v_mfma_f32_16x16x32_bf16 v[82:85], v[156:159], v[202:205], v[82:85]
	v_mfma_f32_16x16x32_bf16 v[70:73], v[148:151], v[206:209], v[70:73]
	v_mfma_f32_16x16x32_bf16 v[66:69], v[156:159], v[206:209], v[66:69]
	v_mfma_f32_16x16x32_bf16 v[118:121], v[152:155], v[194:197], v[118:121]
	v_mfma_f32_16x16x32_bf16 v[114:117], v[160:163], v[194:197], v[114:117]
	v_mfma_f32_16x16x32_bf16 v[102:105], v[152:155], v[198:201], v[102:105]
	v_mfma_f32_16x16x32_bf16 v[98:101], v[160:163], v[198:201], v[98:101]
	v_mfma_f32_16x16x32_bf16 v[86:89], v[152:155], v[218:221], v[86:89]
	v_mfma_f32_16x16x32_bf16 v[82:85], v[160:163], v[218:221], v[82:85]
	v_mfma_f32_16x16x32_bf16 v[70:73], v[152:155], v[222:225], v[70:73]
	v_mfma_f32_16x16x32_bf16 v[66:69], v[160:163], v[222:225], v[66:69]
	s_setprio 0
	s_barrier
	s_add_i32 s43, s43, s15
	v_lshl_add_u64 v[168:169], v[168:169], 0, s[66:67]
	s_mov_b32 m0, s43
	ds_read_b128 v[164:167], v215 offset:49152
	ds_read_b128 v[190:193], v215 offset:51200
	ds_read_b128 v[194:197], v216 offset:49152
	ds_read_b128 v[198:201], v216 offset:51200
	ds_read_b128 v[202:205], v215 offset:53248
	ds_read_b128 v[206:209], v215 offset:55296
	ds_read_b128 v[218:221], v216 offset:53248
	ds_read_b128 v[222:225], v216 offset:55296
	global_load_lds_dwordx4 v[168:169], off
	s_add_i32 m0, s43, 0x2000
	s_add_u32 s44, s86, 0x40080
	v_lshl_add_u64 v[168:169], v[226:227], 0, s[66:67]
	s_addc_u32 s45, s87, 0
	s_add_i32 s43, s46, s15
	global_load_lds_dwordx4 v[168:169], off
	v_lshl_add_u64 v[168:169], s[44:45], 0, v[170:171]
	s_mov_b32 m0, s43
	s_nop 0
	global_load_lds_dwordx4 v[168:169], off
	v_lshl_add_u64 v[168:169], s[44:45], 0, v[178:179]
	s_add_i32 m0, s43, 0x2000
	s_nop 0
	global_load_lds_dwordx4 v[168:169], off
	v_lshl_add_u64 v[168:169], v[228:229], 0, s[66:67]
	s_mov_b32 m0, s80
	s_nop 0
	global_load_lds_dwordx4 v[168:169], off
	v_lshl_add_u64 v[168:169], v[230:231], 0, s[66:67]
	s_mov_b32 m0, s81
	s_nop 0
	global_load_lds_dwordx4 v[168:169], off
	s_waitcnt vmcnt(8)
	s_waitcnt lgkmcnt(0)
	s_barrier
	s_setprio 1
	s_waitcnt lgkmcnt(0)
	v_mfma_f32_16x16x32_bf16 v[62:65], v[132:135], v[164:167], v[62:65]
	v_mfma_f32_16x16x32_bf16 v[58:61], v[140:143], v[164:167], v[58:61]
	v_mfma_f32_16x16x32_bf16 v[46:49], v[132:135], v[190:193], v[46:49]
	v_mfma_f32_16x16x32_bf16 v[42:45], v[140:143], v[190:193], v[42:45]
	v_mfma_f32_16x16x32_bf16 v[30:33], v[132:135], v[202:205], v[30:33]
	v_mfma_f32_16x16x32_bf16 v[26:29], v[140:143], v[202:205], v[26:29]
	v_mfma_f32_16x16x32_bf16 v[14:17], v[132:135], v[206:209], v[14:17]
	v_mfma_f32_16x16x32_bf16 v[10:13], v[140:143], v[206:209], v[10:13]
	v_mfma_f32_16x16x32_bf16 v[62:65], v[136:139], v[194:197], v[62:65]
	v_mfma_f32_16x16x32_bf16 v[58:61], v[144:147], v[194:197], v[58:61]
	v_mfma_f32_16x16x32_bf16 v[46:49], v[136:139], v[198:201], v[46:49]
	v_mfma_f32_16x16x32_bf16 v[42:45], v[144:147], v[198:201], v[42:45]
	v_mfma_f32_16x16x32_bf16 v[30:33], v[136:139], v[218:221], v[30:33]
	v_mfma_f32_16x16x32_bf16 v[26:29], v[144:147], v[218:221], v[26:29]
	v_mfma_f32_16x16x32_bf16 v[14:17], v[136:139], v[222:225], v[14:17]
	v_mfma_f32_16x16x32_bf16 v[10:13], v[144:147], v[222:225], v[10:13]
	s_setprio 0
	s_setprio 1
	v_mfma_f32_16x16x32_bf16 v[54:57], v[148:151], v[164:167], v[54:57]
	v_mfma_f32_16x16x32_bf16 v[50:53], v[156:159], v[164:167], v[50:53]
	v_mfma_f32_16x16x32_bf16 v[38:41], v[148:151], v[190:193], v[38:41]
	v_mfma_f32_16x16x32_bf16 v[34:37], v[156:159], v[190:193], v[34:37]
	v_mfma_f32_16x16x32_bf16 v[22:25], v[148:151], v[202:205], v[22:25]
	v_mfma_f32_16x16x32_bf16 v[18:21], v[156:159], v[202:205], v[18:21]
	v_mfma_f32_16x16x32_bf16 v[6:9], v[148:151], v[206:209], v[6:9]
	v_mfma_f32_16x16x32_bf16 v[2:5], v[156:159], v[206:209], v[2:5]
	v_mfma_f32_16x16x32_bf16 v[54:57], v[152:155], v[194:197], v[54:57]
	v_mfma_f32_16x16x32_bf16 v[50:53], v[160:163], v[194:197], v[50:53]
	v_mfma_f32_16x16x32_bf16 v[38:41], v[152:155], v[198:201], v[38:41]
	v_mfma_f32_16x16x32_bf16 v[34:37], v[160:163], v[198:201], v[34:37]
	v_mfma_f32_16x16x32_bf16 v[22:25], v[152:155], v[218:221], v[22:25]
	v_mfma_f32_16x16x32_bf16 v[18:21], v[160:163], v[218:221], v[18:21]
	v_mfma_f32_16x16x32_bf16 v[6:9], v[152:155], v[222:225], v[6:9]
	v_mfma_f32_16x16x32_bf16 v[2:5], v[160:163], v[222:225], v[2:5]
	s_setprio 0
	s_barrier
	s_add_i32 s42, s42, 2
	s_add_u32 s10, s10, 0x100
	s_addc_u32 s11, s11, 0
	s_add_u32 s68, s68, 0x100
	s_addc_u32 s69, s69, 0
	s_cmp_gt_u32 s42, 13
	s_cbranch_scc1 .LBB0_688

.Lpeel_2:
	s_mov_b32 s100, 0
	v_add_u32_e32 v132, s78, v213
	v_add_u32_e32 v136, s78, v214
	v_add_u32_e32 v140, s79, v213
	v_add_u32_e32 v144, s79, v214
	v_add_u32_e32 v148, s82, v213
	v_add_u32_e32 v152, s82, v214
	v_add_u32_e32 v156, s62, v213
	v_add_u32_e32 v160, s62, v214
	ds_read_b128 v[132:135], v132
	ds_read_b128 v[136:139], v136
	ds_read_b128 v[140:143], v140
	ds_read_b128 v[144:147], v144
	ds_read_b128 v[148:151], v148
	ds_read_b128 v[152:155], v152
	ds_read_b128 v[156:159], v156
	ds_read_b128 v[160:163], v160
	s_add_u32 s43, s10, 0xfffc0080
	s_addc_u32 s46, s11, -1
	s_and_b64 s[44:45], s[86:87], exec
	s_cselect_b32 vcc_hi, s5, s46
	s_cselect_b32 vcc_lo, s38, s43
	s_cselect_b32 s87, s13, s69
	s_cselect_b32 s86, s39, s68
	v_lshl_add_u64 v[168:169], s[10:11], 0, v[180:181]
	s_add_i32 m0, s88, 0xc000
	ds_read_b128 v[164:167], v215
	s_waitcnt lgkmcnt(0)
	ds_read_b128 v[190:193], v215 offset:2048
	ds_read_b128 v[194:197], v216
	ds_read_b128 v[198:201], v216 offset:2048
	ds_read_b128 v[202:205], v215 offset:4096
	ds_read_b128 v[206:209], v215 offset:6144
	ds_read_b128 v[218:221], v216 offset:4096
	ds_read_b128 v[222:225], v216 offset:6144
	global_load_lds_dwordx4 v[168:169], off
	v_lshl_add_u64 v[168:169], s[10:11], 0, v[184:185]
	s_add_i32 m0, s88, 0xe000
	s_nop 0
	global_load_lds_dwordx4 v[168:169], off
	s_waitcnt vmcnt(8)
	s_waitcnt lgkmcnt(0)
	s_barrier
	s_setprio 1
	s_waitcnt lgkmcnt(0)
	v_mfma_f32_16x16x32_bf16 v[126:129], v[132:135], v[164:167], 0
	v_mfma_f32_16x16x32_bf16 v[122:125], v[140:143], v[164:167], 0
	v_mfma_f32_16x16x32_bf16 v[110:113], v[132:135], v[190:193], 0
	v_mfma_f32_16x16x32_bf16 v[106:109], v[140:143], v[190:193], 0
	v_mfma_f32_16x16x32_bf16 v[94:97], v[132:135], v[202:205], 0
	v_mfma_f32_16x16x32_bf16 v[90:93], v[140:143], v[202:205], 0
	v_mfma_f32_16x16x32_bf16 v[78:81], v[132:135], v[206:209], 0
	v_mfma_f32_16x16x32_bf16 v[74:77], v[140:143], v[206:209], 0
	v_mfma_f32_16x16x32_bf16 v[126:129], v[136:139], v[194:197], v[126:129]
	v_mfma_f32_16x16x32_bf16 v[122:125], v[144:147], v[194:197], v[122:125]
	v_mfma_f32_16x16x32_bf16 v[110:113], v[136:139], v[198:201], v[110:113]
	v_mfma_f32_16x16x32_bf16 v[106:109], v[144:147], v[198:201], v[106:109]
	v_mfma_f32_16x16x32_bf16 v[94:97], v[136:139], v[218:221], v[94:97]
	v_mfma_f32_16x16x32_bf16 v[90:93], v[144:147], v[218:221], v[90:93]
	v_mfma_f32_16x16x32_bf16 v[78:81], v[136:139], v[222:225], v[78:81]
	v_mfma_f32_16x16x32_bf16 v[74:77], v[144:147], v[222:225], v[74:77]
	s_setprio 0
	s_setprio 1
	v_mfma_f32_16x16x32_bf16 v[118:121], v[148:151], v[164:167], 0
	v_mfma_f32_16x16x32_bf16 v[114:117], v[156:159], v[164:167], 0
	v_mfma_f32_16x16x32_bf16 v[102:105], v[148:151], v[190:193], 0
	v_mfma_f32_16x16x32_bf16 v[98:101], v[156:159], v[190:193], 0
	v_mfma_f32_16x16x32_bf16 v[86:89], v[148:151], v[202:205], 0
	v_mfma_f32_16x16x32_bf16 v[82:85], v[156:159], v[202:205], 0
	v_mfma_f32_16x16x32_bf16 v[70:73], v[148:151], v[206:209], 0
	v_mfma_f32_16x16x32_bf16 v[66:69], v[156:159], v[206:209], 0
	v_mfma_f32_16x16x32_bf16 v[118:121], v[152:155], v[194:197], v[118:121]
	v_mfma_f32_16x16x32_bf16 v[114:117], v[160:163], v[194:197], v[114:117]
	v_mfma_f32_16x16x32_bf16 v[102:105], v[152:155], v[198:201], v[102:105]
	v_mfma_f32_16x16x32_bf16 v[98:101], v[160:163], v[198:201], v[98:101]
	v_mfma_f32_16x16x32_bf16 v[86:89], v[152:155], v[218:221], v[86:89]
	v_mfma_f32_16x16x32_bf16 v[82:85], v[160:163], v[218:221], v[82:85]
	v_mfma_f32_16x16x32_bf16 v[70:73], v[152:155], v[222:225], v[70:73]
	v_mfma_f32_16x16x32_bf16 v[66:69], v[160:163], v[222:225], v[66:69]
	s_setprio 0
	s_barrier
	s_add_i32 s43, s78, s15
	v_lshl_add_u64 v[168:169], s[86:87], 0, v[170:171]
	s_mov_b32 m0, s43
	ds_read_b128 v[164:167], v215 offset:16384
	ds_read_b128 v[190:193], v215 offset:18432
	ds_read_b128 v[194:197], v216 offset:16384
	ds_read_b128 v[198:201], v216 offset:18432
	ds_read_b128 v[202:205], v215 offset:20480
	ds_read_b128 v[206:209], v215 offset:22528
	ds_read_b128 v[218:221], v216 offset:20480
	ds_read_b128 v[222:225], v216 offset:22528
	global_load_lds_dwordx4 v[168:169], off
	s_add_i32 m0, s43, 0x2000
	s_add_u32 s44, s86, 0x40000
	v_lshl_add_u64 v[226:227], s[86:87], 0, v[178:179]
	s_addc_u32 s45, s87, 0
	s_add_i32 s43, s82, s15
	global_load_lds_dwordx4 v[226:227], off
	v_lshl_add_u64 v[228:229], s[44:45], 0, v[170:171]
	s_mov_b32 m0, s43
	v_lshl_add_u64 v[230:231], vcc, 0, v[176:177]
	global_load_lds_dwordx4 v[228:229], off
	v_lshl_add_u64 v[228:229], s[44:45], 0, v[178:179]
	s_add_i32 m0, s43, 0x2000
	s_nop 0
	global_load_lds_dwordx4 v[228:229], off
	v_lshl_add_u64 v[228:229], vcc, 0, v[174:175]
	s_mov_b32 m0, s88
	s_nop 0
	global_load_lds_dwordx4 v[228:229], off
	s_mov_b32 m0, s89
	s_nop 0
	global_load_lds_dwordx4 v[230:231], off
	s_waitcnt vmcnt(8)
	s_waitcnt lgkmcnt(0)
	s_barrier
	s_setprio 1
	s_waitcnt lgkmcnt(0)
	v_mfma_f32_16x16x32_bf16 v[62:65], v[132:135], v[164:167], 0
	v_mfma_f32_16x16x32_bf16 v[58:61], v[140:143], v[164:167], 0
	v_mfma_f32_16x16x32_bf16 v[46:49], v[132:135], v[190:193], 0
	v_mfma_f32_16x16x32_bf16 v[42:45], v[140:143], v[190:193], 0
	v_mfma_f32_16x16x32_bf16 v[30:33], v[132:135], v[202:205], 0
	v_mfma_f32_16x16x32_bf16 v[26:29], v[140:143], v[202:205], 0
	v_mfma_f32_16x16x32_bf16 v[14:17], v[132:135], v[206:209], 0
	v_mfma_f32_16x16x32_bf16 v[10:13], v[140:143], v[206:209], 0
	v_mfma_f32_16x16x32_bf16 v[62:65], v[136:139], v[194:197], v[62:65]
	v_mfma_f32_16x16x32_bf16 v[58:61], v[144:147], v[194:197], v[58:61]
	v_mfma_f32_16x16x32_bf16 v[46:49], v[136:139], v[198:201], v[46:49]
	v_mfma_f32_16x16x32_bf16 v[42:45], v[144:147], v[198:201], v[42:45]
	v_mfma_f32_16x16x32_bf16 v[30:33], v[136:139], v[218:221], v[30:33]
	v_mfma_f32_16x16x32_bf16 v[26:29], v[144:147], v[218:221], v[26:29]
	v_mfma_f32_16x16x32_bf16 v[14:17], v[136:139], v[222:225], v[14:17]
	v_mfma_f32_16x16x32_bf16 v[10:13], v[144:147], v[222:225], v[10:13]
	s_setprio 0
	s_setprio 1
	v_mfma_f32_16x16x32_bf16 v[54:57], v[148:151], v[164:167], 0
	v_mfma_f32_16x16x32_bf16 v[50:53], v[156:159], v[164:167], 0
	v_mfma_f32_16x16x32_bf16 v[38:41], v[148:151], v[190:193], 0
	v_mfma_f32_16x16x32_bf16 v[34:37], v[156:159], v[190:193], 0
	v_mfma_f32_16x16x32_bf16 v[22:25], v[148:151], v[202:205], 0
	v_mfma_f32_16x16x32_bf16 v[18:21], v[156:159], v[202:205], 0
	v_mfma_f32_16x16x32_bf16 v[6:9], v[148:151], v[206:209], 0
	v_mfma_f32_16x16x32_bf16 v[2:5], v[156:159], v[206:209], 0
	v_mfma_f32_16x16x32_bf16 v[54:57], v[152:155], v[194:197], v[54:57]
	v_mfma_f32_16x16x32_bf16 v[50:53], v[160:163], v[194:197], v[50:53]
	v_mfma_f32_16x16x32_bf16 v[38:41], v[152:155], v[198:201], v[38:41]
	v_mfma_f32_16x16x32_bf16 v[34:37], v[160:163], v[198:201], v[34:37]
	v_mfma_f32_16x16x32_bf16 v[22:25], v[152:155], v[218:221], v[22:25]
	v_mfma_f32_16x16x32_bf16 v[18:21], v[160:163], v[218:221], v[18:21]
	v_mfma_f32_16x16x32_bf16 v[6:9], v[152:155], v[222:225], v[6:9]
	v_mfma_f32_16x16x32_bf16 v[2:5], v[160:163], v[222:225], v[2:5]
	s_setprio 0
	s_barrier
	s_add_i32 s43, 0, 0x18000
	s_add_i32 s46, 0, 0x1c000
	v_add_u32_e32 v132, s43, v213
	v_add_u32_e32 v136, s43, v214
	v_add_u32_e32 v140, s63, v213
	v_add_u32_e32 v144, s63, v214
	v_add_u32_e32 v148, s46, v213
	v_add_u32_e32 v152, s46, v214
	v_add_u32_e32 v156, s64, v213
	v_add_u32_e32 v160, s64, v214
	ds_read_b128 v[132:135], v132
	ds_read_b128 v[136:139], v136
	ds_read_b128 v[140:143], v140
	ds_read_b128 v[144:147], v144
	ds_read_b128 v[148:151], v148
	ds_read_b128 v[152:155], v152
	ds_read_b128 v[156:159], v156
	ds_read_b128 v[160:163], v160
	s_add_u32 s44, vcc_lo, 0x40000
	s_addc_u32 s45, vcc_hi, 0
	s_mov_b32 m0, s94
	v_lshl_add_u64 v[232:233], s[44:45], 0, v[174:175]
	ds_read_b128 v[164:167], v215 offset:32768
	ds_read_b128 v[190:193], v215 offset:34816
	ds_read_b128 v[194:197], v216 offset:32768
	ds_read_b128 v[198:201], v216 offset:34816
	ds_read_b128 v[202:205], v215 offset:36864
	ds_read_b128 v[206:209], v215 offset:38912
	ds_read_b128 v[218:221], v216 offset:36864
	ds_read_b128 v[222:225], v216 offset:38912
	global_load_lds_dwordx4 v[232:233], off
	v_lshl_add_u64 v[232:233], s[44:45], 0, v[176:177]
	s_mov_b32 m0, s95
	s_nop 0
	global_load_lds_dwordx4 v[232:233], off
	s_waitcnt vmcnt(8)
	s_waitcnt lgkmcnt(0)
	s_barrier
	s_setprio 1
	s_waitcnt lgkmcnt(0)
	v_mfma_f32_16x16x32_bf16 v[126:129], v[132:135], v[164:167], v[126:129]
	v_mfma_f32_16x16x32_bf16 v[122:125], v[140:143], v[164:167], v[122:125]
	v_mfma_f32_16x16x32_bf16 v[110:113], v[132:135], v[190:193], v[110:113]
	v_mfma_f32_16x16x32_bf16 v[106:109], v[140:143], v[190:193], v[106:109]
	v_mfma_f32_16x16x32_bf16 v[94:97], v[132:135], v[202:205], v[94:97]
	v_mfma_f32_16x16x32_bf16 v[90:93], v[140:143], v[202:205], v[90:93]
	v_mfma_f32_16x16x32_bf16 v[78:81], v[132:135], v[206:209], v[78:81]
	v_mfma_f32_16x16x32_bf16 v[74:77], v[140:143], v[206:209], v[74:77]
	v_mfma_f32_16x16x32_bf16 v[126:129], v[136:139], v[194:197], v[126:129]
	v_mfma_f32_16x16x32_bf16 v[122:125], v[144:147], v[194:197], v[122:125]
	v_mfma_f32_16x16x32_bf16 v[110:113], v[136:139], v[198:201], v[110:113]
	v_mfma_f32_16x16x32_bf16 v[106:109], v[144:147], v[198:201], v[106:109]
	v_mfma_f32_16x16x32_bf16 v[94:97], v[136:139], v[218:221], v[94:97]
	v_mfma_f32_16x16x32_bf16 v[90:93], v[144:147], v[218:221], v[90:93]
	v_mfma_f32_16x16x32_bf16 v[78:81], v[136:139], v[222:225], v[78:81]
	v_mfma_f32_16x16x32_bf16 v[74:77], v[144:147], v[222:225], v[74:77]
	s_setprio 0
	s_setprio 1
	v_mfma_f32_16x16x32_bf16 v[118:121], v[148:151], v[164:167], v[118:121]
	v_mfma_f32_16x16x32_bf16 v[114:117], v[156:159], v[164:167], v[114:117]
	v_mfma_f32_16x16x32_bf16 v[102:105], v[148:151], v[190:193], v[102:105]
	v_mfma_f32_16x16x32_bf16 v[98:101], v[156:159], v[190:193], v[98:101]
	v_mfma_f32_16x16x32_bf16 v[86:89], v[148:151], v[202:205], v[86:89]
	v_mfma_f32_16x16x32_bf16 v[82:85], v[156:159], v[202:205], v[82:85]
	v_mfma_f32_16x16x32_bf16 v[70:73], v[148:151], v[206:209], v[70:73]
	v_mfma_f32_16x16x32_bf16 v[66:69], v[156:159], v[206:209], v[66:69]
	v_mfma_f32_16x16x32_bf16 v[118:121], v[152:155], v[194:197], v[118:121]
	v_mfma_f32_16x16x32_bf16 v[114:117], v[160:163], v[194:197], v[114:117]
	v_mfma_f32_16x16x32_bf16 v[102:105], v[152:155], v[198:201], v[102:105]
	v_mfma_f32_16x16x32_bf16 v[98:101], v[160:163], v[198:201], v[98:101]
	v_mfma_f32_16x16x32_bf16 v[86:89], v[152:155], v[218:221], v[86:89]
	v_mfma_f32_16x16x32_bf16 v[82:85], v[160:163], v[218:221], v[82:85]
	v_mfma_f32_16x16x32_bf16 v[70:73], v[152:155], v[222:225], v[70:73]
	v_mfma_f32_16x16x32_bf16 v[66:69], v[160:163], v[222:225], v[66:69]
	s_setprio 0
	s_barrier
	s_add_i32 s43, s43, s15
	v_lshl_add_u64 v[168:169], v[168:169], 0, s[66:67]
	s_mov_b32 m0, s43
	ds_read_b128 v[164:167], v215 offset:49152
	ds_read_b128 v[190:193], v215 offset:51200
	ds_read_b128 v[194:197], v216 offset:49152
	ds_read_b128 v[198:201], v216 offset:51200
	ds_read_b128 v[202:205], v215 offset:53248
	ds_read_b128 v[206:209], v215 offset:55296
	ds_read_b128 v[218:221], v216 offset:53248
	ds_read_b128 v[222:225], v216 offset:55296
	global_load_lds_dwordx4 v[168:169], off
	s_add_i32 m0, s43, 0x2000
	s_add_u32 s44, s86, 0x40080
	v_lshl_add_u64 v[168:169], v[226:227], 0, s[66:67]
	s_addc_u32 s45, s87, 0
	s_add_i32 s43, s46, s15
	global_load_lds_dwordx4 v[168:169], off
	v_lshl_add_u64 v[168:169], s[44:45], 0, v[170:171]
	s_mov_b32 m0, s43
	s_nop 0
	global_load_lds_dwordx4 v[168:169], off
	v_lshl_add_u64 v[168:169], s[44:45], 0, v[178:179]
	s_add_i32 m0, s43, 0x2000
	s_nop 0
	global_load_lds_dwordx4 v[168:169], off
	v_lshl_add_u64 v[168:169], v[228:229], 0, s[66:67]
	s_mov_b32 m0, s80
	s_nop 0
	global_load_lds_dwordx4 v[168:169], off
	v_lshl_add_u64 v[168:169], v[230:231], 0, s[66:67]
	s_mov_b32 m0, s81
	s_nop 0
	global_load_lds_dwordx4 v[168:169], off
	s_waitcnt vmcnt(8)
	s_waitcnt lgkmcnt(0)
	s_barrier
	s_setprio 1
	s_waitcnt lgkmcnt(0)
	v_mfma_f32_16x16x32_bf16 v[62:65], v[132:135], v[164:167], v[62:65]
	v_mfma_f32_16x16x32_bf16 v[58:61], v[140:143], v[164:167], v[58:61]
	v_mfma_f32_16x16x32_bf16 v[46:49], v[132:135], v[190:193], v[46:49]
	v_mfma_f32_16x16x32_bf16 v[42:45], v[140:143], v[190:193], v[42:45]
	v_mfma_f32_16x16x32_bf16 v[30:33], v[132:135], v[202:205], v[30:33]
	v_mfma_f32_16x16x32_bf16 v[26:29], v[140:143], v[202:205], v[26:29]
	v_mfma_f32_16x16x32_bf16 v[14:17], v[132:135], v[206:209], v[14:17]
	v_mfma_f32_16x16x32_bf16 v[10:13], v[140:143], v[206:209], v[10:13]
	v_mfma_f32_16x16x32_bf16 v[62:65], v[136:139], v[194:197], v[62:65]
	v_mfma_f32_16x16x32_bf16 v[58:61], v[144:147], v[194:197], v[58:61]
	v_mfma_f32_16x16x32_bf16 v[46:49], v[136:139], v[198:201], v[46:49]
	v_mfma_f32_16x16x32_bf16 v[42:45], v[144:147], v[198:201], v[42:45]
	v_mfma_f32_16x16x32_bf16 v[30:33], v[136:139], v[218:221], v[30:33]
	v_mfma_f32_16x16x32_bf16 v[26:29], v[144:147], v[218:221], v[26:29]
	v_mfma_f32_16x16x32_bf16 v[14:17], v[136:139], v[222:225], v[14:17]
	v_mfma_f32_16x16x32_bf16 v[10:13], v[144:147], v[222:225], v[10:13]
	s_setprio 0
	s_setprio 1
	v_mfma_f32_16x16x32_bf16 v[54:57], v[148:151], v[164:167], v[54:57]
	v_mfma_f32_16x16x32_bf16 v[50:53], v[156:159], v[164:167], v[50:53]
	v_mfma_f32_16x16x32_bf16 v[38:41], v[148:151], v[190:193], v[38:41]
	v_mfma_f32_16x16x32_bf16 v[34:37], v[156:159], v[190:193], v[34:37]
	v_mfma_f32_16x16x32_bf16 v[22:25], v[148:151], v[202:205], v[22:25]
	v_mfma_f32_16x16x32_bf16 v[18:21], v[156:159], v[202:205], v[18:21]
	v_mfma_f32_16x16x32_bf16 v[6:9], v[148:151], v[206:209], v[6:9]
	v_mfma_f32_16x16x32_bf16 v[2:5], v[156:159], v[206:209], v[2:5]
	v_mfma_f32_16x16x32_bf16 v[54:57], v[152:155], v[194:197], v[54:57]
	v_mfma_f32_16x16x32_bf16 v[50:53], v[160:163], v[194:197], v[50:53]
	v_mfma_f32_16x16x32_bf16 v[38:41], v[152:155], v[198:201], v[38:41]
	v_mfma_f32_16x16x32_bf16 v[34:37], v[160:163], v[198:201], v[34:37]
	v_mfma_f32_16x16x32_bf16 v[22:25], v[152:155], v[218:221], v[22:25]
	v_mfma_f32_16x16x32_bf16 v[18:21], v[160:163], v[218:221], v[18:21]
	v_mfma_f32_16x16x32_bf16 v[6:9], v[152:155], v[222:225], v[6:9]
	v_mfma_f32_16x16x32_bf16 v[2:5], v[160:163], v[222:225], v[2:5]
	s_setprio 0
	s_barrier
	s_add_i32 s42, s42, 2
	s_add_u32 s10, s10, 0x100
	s_addc_u32 s11, s11, 0
	s_add_u32 s68, s68, 0x100
	s_addc_u32 s69, s69, 0
	s_cmp_gt_u32 s42, 13
	s_cbranch_scc1 .LBB0_688
	s_branch .LBB0_685

.LBB0_1315:
	s_lshl_b32 s44, s66, 10
	s_lshl_b32 s42, s67, 8
	s_add_i32 s69, s44, 0
	s_add_i32 s68, s39, -2
	s_ashr_i32 s43, s42, 31
	s_add_i32 s69, s69, 0x20800
	s_cmp_lt_i32 s28, 3
	s_cselect_b32 s44, s93, s61
	s_cselect_b32 s45, s92, s60
	s_lshl_b64 s[42:43], s[42:43], 2
	s_add_u32 s42, s45, s42
	s_addc_u32 s43, s44, s43
	s_add_u32 s12, s12, 0x18080
	s_addc_u32 s13, s13, 0
	s_add_u32 s48, s78, 0x100
	s_mov_b32 s100, 1
	v_lshl_add_u64 v[130:131], s[42:43], 0, v[188:189]
	s_addc_u32 s72, s79, 0
	s_mov_b32 s42, 0
	s_branch .LBB0_1317
.LBB0_1316:
	s_cmp_lg_u32 s100, 0
	s_cbranch_scc1 .Lpeel_3
	v_add_u32_e32 v132, s96, v209
	v_add_u32_e32 v136, s96, v210
	v_add_u32_e32 v140, s97, v209
	v_add_u32_e32 v144, s97, v210
	v_add_u32_e32 v148, s83, v209
	v_add_u32_e32 v152, s83, v210
	v_add_u32_e32 v156, s88, v209
	v_add_u32_e32 v160, s88, v210
	ds_read_b128 v[132:135], v132
	ds_read_b128 v[136:139], v136
	ds_read_b128 v[140:143], v140
	ds_read_b128 v[144:147], v144
	ds_read_b128 v[148:151], v148
	ds_read_b128 v[152:155], v152
	ds_read_b128 v[156:159], v156
	ds_read_b128 v[160:163], v160
	s_add_i32 s42, s42, 2
	s_add_u32 s43, s12, 0xfffe8080
	s_addc_u32 s46, s13, -1
	s_and_b64 s[44:45], s[78:79], exec
	s_cselect_b32 s81, s75, s46
	s_cselect_b32 s80, s74, s43
	s_cselect_b32 s79, s77, s72
	s_cselect_b32 s78, s76, s48
	v_lshl_add_u64 v[168:169], s[12:13], 0, v[178:179]
	s_add_i32 m0, s63, 0xc000
	ds_read_b128 v[164:167], v211
	ds_read_b128 v[190:193], v211 offset:2048
	s_waitcnt lgkmcnt(0)
	ds_read_b128 v[194:197], v212
	ds_read_b128 v[198:201], v212 offset:2048
	ds_read_b128 v[202:205], v211 offset:4096
	ds_read_b128 v[214:217], v211 offset:6144
	ds_read_b128 v[218:221], v212 offset:4096
	ds_read_b128 v[222:225], v212 offset:6144
	global_load_lds_dwordx4 v[168:169], off
	v_lshl_add_u64 v[168:169], s[12:13], 0, v[182:183]
	s_add_i32 m0, s63, 0xe000
	s_nop 0
	global_load_lds_dwordx4 v[168:169], off
	s_waitcnt vmcnt(8)
	s_waitcnt lgkmcnt(0)
	s_barrier
	s_setprio 1
	s_waitcnt lgkmcnt(0)
	v_mfma_f32_16x16x32_bf16 v[126:129], v[132:135], v[164:167], v[126:129]
	v_mfma_f32_16x16x32_bf16 v[122:125], v[140:143], v[164:167], v[122:125]
	v_mfma_f32_16x16x32_bf16 v[110:113], v[132:135], v[190:193], v[110:113]
	v_mfma_f32_16x16x32_bf16 v[106:109], v[140:143], v[190:193], v[106:109]
	v_mfma_f32_16x16x32_bf16 v[94:97], v[132:135], v[202:205], v[94:97]
	v_mfma_f32_16x16x32_bf16 v[90:93], v[140:143], v[202:205], v[90:93]
	v_mfma_f32_16x16x32_bf16 v[78:81], v[132:135], v[214:217], v[78:81]
	v_mfma_f32_16x16x32_bf16 v[74:77], v[140:143], v[214:217], v[74:77]
	v_mfma_f32_16x16x32_bf16 v[126:129], v[136:139], v[194:197], v[126:129]
	v_mfma_f32_16x16x32_bf16 v[122:125], v[144:147], v[194:197], v[122:125]
	v_mfma_f32_16x16x32_bf16 v[110:113], v[136:139], v[198:201], v[110:113]
	v_mfma_f32_16x16x32_bf16 v[106:109], v[144:147], v[198:201], v[106:109]
	v_mfma_f32_16x16x32_bf16 v[94:97], v[136:139], v[218:221], v[94:97]
	v_mfma_f32_16x16x32_bf16 v[90:93], v[144:147], v[218:221], v[90:93]
	v_mfma_f32_16x16x32_bf16 v[78:81], v[136:139], v[222:225], v[78:81]
	v_mfma_f32_16x16x32_bf16 v[74:77], v[144:147], v[222:225], v[74:77]
	s_setprio 0
	s_setprio 1
	v_mfma_f32_16x16x32_bf16 v[118:121], v[148:151], v[164:167], v[118:121]
	v_mfma_f32_16x16x32_bf16 v[114:117], v[156:159], v[164:167], v[114:117]
	v_mfma_f32_16x16x32_bf16 v[102:105], v[148:151], v[190:193], v[102:105]
	v_mfma_f32_16x16x32_bf16 v[98:101], v[156:159], v[190:193], v[98:101]
	v_mfma_f32_16x16x32_bf16 v[86:89], v[148:151], v[202:205], v[86:89]
	v_mfma_f32_16x16x32_bf16 v[82:85], v[156:159], v[202:205], v[82:85]
	v_mfma_f32_16x16x32_bf16 v[70:73], v[148:151], v[214:217], v[70:73]
	v_mfma_f32_16x16x32_bf16 v[66:69], v[156:159], v[214:217], v[66:69]
	v_mfma_f32_16x16x32_bf16 v[118:121], v[152:155], v[194:197], v[118:121]
	v_mfma_f32_16x16x32_bf16 v[114:117], v[160:163], v[194:197], v[114:117]
	v_mfma_f32_16x16x32_bf16 v[102:105], v[152:155], v[198:201], v[102:105]
	v_mfma_f32_16x16x32_bf16 v[98:101], v[160:163], v[198:201], v[98:101]
	v_mfma_f32_16x16x32_bf16 v[86:89], v[152:155], v[218:221], v[86:89]
	v_mfma_f32_16x16x32_bf16 v[82:85], v[160:163], v[218:221], v[82:85]
	v_mfma_f32_16x16x32_bf16 v[70:73], v[152:155], v[222:225], v[70:73]
	v_mfma_f32_16x16x32_bf16 v[66:69], v[160:163], v[222:225], v[66:69]
	s_setprio 0
	s_barrier
	s_add_i32 s43, s96, s62
	v_lshl_add_u64 v[168:169], s[78:79], 0, v[170:171]
	s_mov_b32 m0, s43
	ds_read_b128 v[164:167], v211 offset:16384
	ds_read_b128 v[190:193], v211 offset:18432
	ds_read_b128 v[194:197], v212 offset:16384
	ds_read_b128 v[198:201], v212 offset:18432
	ds_read_b128 v[202:205], v211 offset:20480
	ds_read_b128 v[214:217], v211 offset:22528
	ds_read_b128 v[218:221], v212 offset:20480
	ds_read_b128 v[222:225], v212 offset:22528
	global_load_lds_dwordx4 v[168:169], off
	s_add_i32 m0, s43, 0x2000
	s_add_u32 s44, s78, 0x18000
	v_lshl_add_u64 v[206:207], s[78:79], 0, v[176:177]
	s_addc_u32 s45, s79, 0
	s_add_i32 s43, s83, s62
	global_load_lds_dwordx4 v[206:207], off
	v_lshl_add_u64 v[226:227], s[44:45], 0, v[170:171]
	s_mov_b32 m0, s43
	v_lshl_add_u64 v[228:229], s[80:81], 0, v[174:175]
	global_load_lds_dwordx4 v[226:227], off
	v_lshl_add_u64 v[226:227], s[44:45], 0, v[176:177]
	s_add_i32 m0, s43, 0x2000
	s_nop 0
	global_load_lds_dwordx4 v[226:227], off
	v_lshl_add_u64 v[226:227], s[80:81], 0, v[172:173]
	s_mov_b32 m0, s63
	s_nop 0
	global_load_lds_dwordx4 v[226:227], off
	s_mov_b32 m0, s64
	s_nop 0
	global_load_lds_dwordx4 v[228:229], off
	s_waitcnt vmcnt(8)
	s_waitcnt lgkmcnt(0)
	s_barrier
	s_setprio 1
	s_waitcnt lgkmcnt(0)
	v_mfma_f32_16x16x32_bf16 v[62:65], v[132:135], v[164:167], v[62:65]
	v_mfma_f32_16x16x32_bf16 v[58:61], v[140:143], v[164:167], v[58:61]
	v_mfma_f32_16x16x32_bf16 v[46:49], v[132:135], v[190:193], v[46:49]
	v_mfma_f32_16x16x32_bf16 v[42:45], v[140:143], v[190:193], v[42:45]
	v_mfma_f32_16x16x32_bf16 v[30:33], v[132:135], v[202:205], v[30:33]
	v_mfma_f32_16x16x32_bf16 v[26:29], v[140:143], v[202:205], v[26:29]
	v_mfma_f32_16x16x32_bf16 v[14:17], v[132:135], v[214:217], v[14:17]
	v_mfma_f32_16x16x32_bf16 v[10:13], v[140:143], v[214:217], v[10:13]
	v_mfma_f32_16x16x32_bf16 v[62:65], v[136:139], v[194:197], v[62:65]
	v_mfma_f32_16x16x32_bf16 v[58:61], v[144:147], v[194:197], v[58:61]
	v_mfma_f32_16x16x32_bf16 v[46:49], v[136:139], v[198:201], v[46:49]
	v_mfma_f32_16x16x32_bf16 v[42:45], v[144:147], v[198:201], v[42:45]
	v_mfma_f32_16x16x32_bf16 v[30:33], v[136:139], v[218:221], v[30:33]
	v_mfma_f32_16x16x32_bf16 v[26:29], v[144:147], v[218:221], v[26:29]
	v_mfma_f32_16x16x32_bf16 v[14:17], v[136:139], v[222:225], v[14:17]
	v_mfma_f32_16x16x32_bf16 v[10:13], v[144:147], v[222:225], v[10:13]
	s_setprio 0
	s_setprio 1
	v_mfma_f32_16x16x32_bf16 v[54:57], v[148:151], v[164:167], v[54:57]
	v_mfma_f32_16x16x32_bf16 v[50:53], v[156:159], v[164:167], v[50:53]
	v_mfma_f32_16x16x32_bf16 v[38:41], v[148:151], v[190:193], v[38:41]
	v_mfma_f32_16x16x32_bf16 v[34:37], v[156:159], v[190:193], v[34:37]
	v_mfma_f32_16x16x32_bf16 v[22:25], v[148:151], v[202:205], v[22:25]
	v_mfma_f32_16x16x32_bf16 v[18:21], v[156:159], v[202:205], v[18:21]
	v_mfma_f32_16x16x32_bf16 v[6:9], v[148:151], v[214:217], v[6:9]
	v_mfma_f32_16x16x32_bf16 v[2:5], v[156:159], v[214:217], v[2:5]
	v_mfma_f32_16x16x32_bf16 v[54:57], v[152:155], v[194:197], v[54:57]
	v_mfma_f32_16x16x32_bf16 v[50:53], v[160:163], v[194:197], v[50:53]
	v_mfma_f32_16x16x32_bf16 v[38:41], v[152:155], v[198:201], v[38:41]
	v_mfma_f32_16x16x32_bf16 v[34:37], v[160:163], v[198:201], v[34:37]
	v_mfma_f32_16x16x32_bf16 v[22:25], v[152:155], v[218:221], v[22:25]
	v_mfma_f32_16x16x32_bf16 v[18:21], v[160:163], v[218:221], v[18:21]
	v_mfma_f32_16x16x32_bf16 v[6:9], v[152:155], v[222:225], v[6:9]
	v_mfma_f32_16x16x32_bf16 v[2:5], v[160:163], v[222:225], v[2:5]
	s_setprio 0
	s_barrier
	s_add_i32 s43, 0, 0x18000
	s_add_i32 s46, 0, 0x1c000
	v_add_u32_e32 v132, s43, v209
	v_add_u32_e32 v136, s43, v210
	v_add_u32_e32 v140, s26, v209
	v_add_u32_e32 v144, s26, v210
	v_add_u32_e32 v148, s46, v209
	v_add_u32_e32 v152, s46, v210
	v_add_u32_e32 v156, s27, v209
	v_add_u32_e32 v160, s27, v210
	ds_read_b128 v[132:135], v132
	ds_read_b128 v[136:139], v136
	ds_read_b128 v[140:143], v140
	ds_read_b128 v[144:147], v144
	ds_read_b128 v[148:151], v148
	ds_read_b128 v[152:155], v152
	ds_read_b128 v[156:159], v156
	ds_read_b128 v[160:163], v160
	s_add_u32 s44, s80, 0x18000
	s_addc_u32 s45, s81, 0
	s_mov_b32 m0, s65
	v_lshl_add_u64 v[230:231], s[44:45], 0, v[172:173]
	ds_read_b128 v[164:167], v211 offset:32768
	ds_read_b128 v[190:193], v211 offset:34816
	ds_read_b128 v[194:197], v212 offset:32768
	ds_read_b128 v[198:201], v212 offset:34816
	ds_read_b128 v[202:205], v211 offset:36864
	ds_read_b128 v[214:217], v211 offset:38912
	ds_read_b128 v[218:221], v212 offset:36864
	ds_read_b128 v[222:225], v212 offset:38912
	global_load_lds_dwordx4 v[230:231], off
	v_lshl_add_u64 v[230:231], s[44:45], 0, v[174:175]
	s_mov_b32 m0, s82
	s_nop 0
	global_load_lds_dwordx4 v[230:231], off
	s_waitcnt vmcnt(8)
	s_waitcnt lgkmcnt(0)
	s_barrier
	s_setprio 1
	s_waitcnt lgkmcnt(0)
	v_mfma_f32_16x16x32_bf16 v[126:129], v[132:135], v[164:167], v[126:129]
	v_mfma_f32_16x16x32_bf16 v[122:125], v[140:143], v[164:167], v[122:125]
	v_mfma_f32_16x16x32_bf16 v[110:113], v[132:135], v[190:193], v[110:113]
	v_mfma_f32_16x16x32_bf16 v[106:109], v[140:143], v[190:193], v[106:109]
	v_mfma_f32_16x16x32_bf16 v[94:97], v[132:135], v[202:205], v[94:97]
	v_mfma_f32_16x16x32_bf16 v[90:93], v[140:143], v[202:205], v[90:93]
	v_mfma_f32_16x16x32_bf16 v[78:81], v[132:135], v[214:217], v[78:81]
	v_mfma_f32_16x16x32_bf16 v[74:77], v[140:143], v[214:217], v[74:77]
	v_mfma_f32_16x16x32_bf16 v[126:129], v[136:139], v[194:197], v[126:129]
	v_mfma_f32_16x16x32_bf16 v[122:125], v[144:147], v[194:197], v[122:125]
	v_mfma_f32_16x16x32_bf16 v[110:113], v[136:139], v[198:201], v[110:113]
	v_mfma_f32_16x16x32_bf16 v[106:109], v[144:147], v[198:201], v[106:109]
	v_mfma_f32_16x16x32_bf16 v[94:97], v[136:139], v[218:221], v[94:97]
	v_mfma_f32_16x16x32_bf16 v[90:93], v[144:147], v[218:221], v[90:93]
	v_mfma_f32_16x16x32_bf16 v[78:81], v[136:139], v[222:225], v[78:81]
	v_mfma_f32_16x16x32_bf16 v[74:77], v[144:147], v[222:225], v[74:77]
	s_setprio 0
	s_setprio 1
	v_mfma_f32_16x16x32_bf16 v[118:121], v[148:151], v[164:167], v[118:121]
	v_mfma_f32_16x16x32_bf16 v[114:117], v[156:159], v[164:167], v[114:117]
	v_mfma_f32_16x16x32_bf16 v[102:105], v[148:151], v[190:193], v[102:105]
	v_mfma_f32_16x16x32_bf16 v[98:101], v[156:159], v[190:193], v[98:101]
	v_mfma_f32_16x16x32_bf16 v[86:89], v[148:151], v[202:205], v[86:89]
	v_mfma_f32_16x16x32_bf16 v[82:85], v[156:159], v[202:205], v[82:85]
	v_mfma_f32_16x16x32_bf16 v[70:73], v[148:151], v[214:217], v[70:73]
	v_mfma_f32_16x16x32_bf16 v[66:69], v[156:159], v[214:217], v[66:69]
	v_mfma_f32_16x16x32_bf16 v[118:121], v[152:155], v[194:197], v[118:121]
	v_mfma_f32_16x16x32_bf16 v[114:117], v[160:163], v[194:197], v[114:117]
	v_mfma_f32_16x16x32_bf16 v[102:105], v[152:155], v[198:201], v[102:105]
	v_mfma_f32_16x16x32_bf16 v[98:101], v[160:163], v[198:201], v[98:101]
	v_mfma_f32_16x16x32_bf16 v[86:89], v[152:155], v[218:221], v[86:89]
	v_mfma_f32_16x16x32_bf16 v[82:85], v[160:163], v[218:221], v[82:85]
	v_mfma_f32_16x16x32_bf16 v[70:73], v[152:155], v[222:225], v[70:73]
	v_mfma_f32_16x16x32_bf16 v[66:69], v[160:163], v[222:225], v[66:69]
	s_setprio 0
	s_barrier
	s_add_i32 s43, s43, s62
	v_lshl_add_u64 v[168:169], v[168:169], 0, s[14:15]
	s_mov_b32 m0, s43
	ds_read_b128 v[164:167], v211 offset:49152
	ds_read_b128 v[190:193], v211 offset:51200
	ds_read_b128 v[194:197], v212 offset:49152
	ds_read_b128 v[198:201], v212 offset:51200
	ds_read_b128 v[202:205], v211 offset:53248
	ds_read_b128 v[214:217], v211 offset:55296
	ds_read_b128 v[218:221], v212 offset:53248
	ds_read_b128 v[222:225], v212 offset:55296
	global_load_lds_dwordx4 v[168:169], off
	s_add_i32 m0, s43, 0x2000
	s_add_u32 s44, s78, 0x18080
	v_lshl_add_u64 v[168:169], v[206:207], 0, s[14:15]
	s_addc_u32 s45, s79, 0
	s_add_i32 s43, s46, s62
	global_load_lds_dwordx4 v[168:169], off
	v_lshl_add_u64 v[168:169], s[44:45], 0, v[170:171]
	s_mov_b32 m0, s43
	s_nop 0
	global_load_lds_dwordx4 v[168:169], off
	v_lshl_add_u64 v[168:169], s[44:45], 0, v[176:177]
	s_add_i32 m0, s43, 0x2000
	s_nop 0
	global_load_lds_dwordx4 v[168:169], off
	v_lshl_add_u64 v[168:169], v[226:227], 0, s[14:15]
	s_mov_b32 m0, s89
	s_nop 0
	global_load_lds_dwordx4 v[168:169], off
	v_lshl_add_u64 v[168:169], v[228:229], 0, s[14:15]
	s_mov_b32 m0, s91
	s_nop 0
	global_load_lds_dwordx4 v[168:169], off
	s_waitcnt vmcnt(8)
	s_waitcnt lgkmcnt(0)
	s_barrier
	s_setprio 1
	s_waitcnt lgkmcnt(0)
	v_mfma_f32_16x16x32_bf16 v[62:65], v[132:135], v[164:167], v[62:65]
	v_mfma_f32_16x16x32_bf16 v[58:61], v[140:143], v[164:167], v[58:61]
	v_mfma_f32_16x16x32_bf16 v[46:49], v[132:135], v[190:193], v[46:49]
	v_mfma_f32_16x16x32_bf16 v[42:45], v[140:143], v[190:193], v[42:45]
	v_mfma_f32_16x16x32_bf16 v[30:33], v[132:135], v[202:205], v[30:33]
	v_mfma_f32_16x16x32_bf16 v[26:29], v[140:143], v[202:205], v[26:29]
	v_mfma_f32_16x16x32_bf16 v[14:17], v[132:135], v[214:217], v[14:17]
	v_mfma_f32_16x16x32_bf16 v[10:13], v[140:143], v[214:217], v[10:13]
	v_mfma_f32_16x16x32_bf16 v[62:65], v[136:139], v[194:197], v[62:65]
	v_mfma_f32_16x16x32_bf16 v[58:61], v[144:147], v[194:197], v[58:61]
	v_mfma_f32_16x16x32_bf16 v[46:49], v[136:139], v[198:201], v[46:49]
	v_mfma_f32_16x16x32_bf16 v[42:45], v[144:147], v[198:201], v[42:45]
	v_mfma_f32_16x16x32_bf16 v[30:33], v[136:139], v[218:221], v[30:33]
	v_mfma_f32_16x16x32_bf16 v[26:29], v[144:147], v[218:221], v[26:29]
	v_mfma_f32_16x16x32_bf16 v[14:17], v[136:139], v[222:225], v[14:17]
	v_mfma_f32_16x16x32_bf16 v[10:13], v[144:147], v[222:225], v[10:13]
	s_setprio 0
	s_setprio 1
	v_mfma_f32_16x16x32_bf16 v[54:57], v[148:151], v[164:167], v[54:57]
	v_mfma_f32_16x16x32_bf16 v[50:53], v[156:159], v[164:167], v[50:53]
	v_mfma_f32_16x16x32_bf16 v[38:41], v[148:151], v[190:193], v[38:41]
	v_mfma_f32_16x16x32_bf16 v[34:37], v[156:159], v[190:193], v[34:37]
	v_mfma_f32_16x16x32_bf16 v[22:25], v[148:151], v[202:205], v[22:25]
	v_mfma_f32_16x16x32_bf16 v[18:21], v[156:159], v[202:205], v[18:21]
	v_mfma_f32_16x16x32_bf16 v[6:9], v[148:151], v[214:217], v[6:9]
	v_mfma_f32_16x16x32_bf16 v[2:5], v[156:159], v[214:217], v[2:5]
	v_mfma_f32_16x16x32_bf16 v[54:57], v[152:155], v[194:197], v[54:57]
	v_mfma_f32_16x16x32_bf16 v[50:53], v[160:163], v[194:197], v[50:53]
	v_mfma_f32_16x16x32_bf16 v[38:41], v[152:155], v[198:201], v[38:41]
	v_mfma_f32_16x16x32_bf16 v[34:37], v[160:163], v[198:201], v[34:37]
	v_mfma_f32_16x16x32_bf16 v[22:25], v[152:155], v[218:221], v[22:25]
	v_mfma_f32_16x16x32_bf16 v[18:21], v[160:163], v[218:221], v[18:21]
	v_mfma_f32_16x16x32_bf16 v[6:9], v[152:155], v[222:225], v[6:9]
	v_mfma_f32_16x16x32_bf16 v[2:5], v[160:163], v[222:225], v[2:5]
	s_setprio 0
	s_barrier
	s_add_u32 s12, s12, 0x100
	s_addc_u32 s13, s13, 0
	s_add_u32 s48, s48, 0x100
	s_addc_u32 s72, s72, 0
	s_cmp_ge_i32 s42, s39
	s_cbranch_scc1 .LBB0_1320

.Lpeel_3:
	s_mov_b32 s100, 0
	v_add_u32_e32 v132, s96, v209
	v_add_u32_e32 v136, s96, v210
	v_add_u32_e32 v140, s97, v209
	v_add_u32_e32 v144, s97, v210
	v_add_u32_e32 v148, s83, v209
	v_add_u32_e32 v152, s83, v210
	v_add_u32_e32 v156, s88, v209
	v_add_u32_e32 v160, s88, v210
	ds_read_b128 v[132:135], v132
	ds_read_b128 v[136:139], v136
	ds_read_b128 v[140:143], v140
	ds_read_b128 v[144:147], v144
	ds_read_b128 v[148:151], v148
	ds_read_b128 v[152:155], v152
	ds_read_b128 v[156:159], v156
	ds_read_b128 v[160:163], v160
	s_add_i32 s42, s42, 2
	s_add_u32 s43, s12, 0xfffe8080
	s_addc_u32 s46, s13, -1
	s_and_b64 s[44:45], s[78:79], exec
	s_cselect_b32 s81, s75, s46
	s_cselect_b32 s80, s74, s43
	s_cselect_b32 s79, s77, s72
	s_cselect_b32 s78, s76, s48
	v_lshl_add_u64 v[168:169], s[12:13], 0, v[178:179]
	s_add_i32 m0, s63, 0xc000
	ds_read_b128 v[164:167], v211
	ds_read_b128 v[190:193], v211 offset:2048
	s_waitcnt lgkmcnt(0)
	ds_read_b128 v[194:197], v212
	ds_read_b128 v[198:201], v212 offset:2048
	ds_read_b128 v[202:205], v211 offset:4096
	ds_read_b128 v[214:217], v211 offset:6144
	ds_read_b128 v[218:221], v212 offset:4096
	ds_read_b128 v[222:225], v212 offset:6144
	global_load_lds_dwordx4 v[168:169], off
	v_lshl_add_u64 v[168:169], s[12:13], 0, v[182:183]
	s_add_i32 m0, s63, 0xe000
	s_nop 0
	global_load_lds_dwordx4 v[168:169], off
	s_waitcnt vmcnt(8)
	s_waitcnt lgkmcnt(0)
	s_barrier
	s_setprio 1
	s_waitcnt lgkmcnt(0)
	v_mfma_f32_16x16x32_bf16 v[126:129], v[132:135], v[164:167], 0
	v_mfma_f32_16x16x32_bf16 v[122:125], v[140:143], v[164:167], 0
	v_mfma_f32_16x16x32_bf16 v[110:113], v[132:135], v[190:193], 0
	v_mfma_f32_16x16x32_bf16 v[106:109], v[140:143], v[190:193], 0
	v_mfma_f32_16x16x32_bf16 v[94:97], v[132:135], v[202:205], 0
	v_mfma_f32_16x16x32_bf16 v[90:93], v[140:143], v[202:205], 0
	v_mfma_f32_16x16x32_bf16 v[78:81], v[132:135], v[214:217], 0
	v_mfma_f32_16x16x32_bf16 v[74:77], v[140:143], v[214:217], 0
	v_mfma_f32_16x16x32_bf16 v[126:129], v[136:139], v[194:197], v[126:129]
	v_mfma_f32_16x16x32_bf16 v[122:125], v[144:147], v[194:197], v[122:125]
	v_mfma_f32_16x16x32_bf16 v[110:113], v[136:139], v[198:201], v[110:113]
	v_mfma_f32_16x16x32_bf16 v[106:109], v[144:147], v[198:201], v[106:109]
	v_mfma_f32_16x16x32_bf16 v[94:97], v[136:139], v[218:221], v[94:97]
	v_mfma_f32_16x16x32_bf16 v[90:93], v[144:147], v[218:221], v[90:93]
	v_mfma_f32_16x16x32_bf16 v[78:81], v[136:139], v[222:225], v[78:81]
	v_mfma_f32_16x16x32_bf16 v[74:77], v[144:147], v[222:225], v[74:77]
	s_setprio 0
	s_setprio 1
	v_mfma_f32_16x16x32_bf16 v[118:121], v[148:151], v[164:167], 0
	v_mfma_f32_16x16x32_bf16 v[114:117], v[156:159], v[164:167], 0
	v_mfma_f32_16x16x32_bf16 v[102:105], v[148:151], v[190:193], 0
	v_mfma_f32_16x16x32_bf16 v[98:101], v[156:159], v[190:193], 0
	v_mfma_f32_16x16x32_bf16 v[86:89], v[148:151], v[202:205], 0
	v_mfma_f32_16x16x32_bf16 v[82:85], v[156:159], v[202:205], 0
	v_mfma_f32_16x16x32_bf16 v[70:73], v[148:151], v[214:217], 0
	v_mfma_f32_16x16x32_bf16 v[66:69], v[156:159], v[214:217], 0
	v_mfma_f32_16x16x32_bf16 v[118:121], v[152:155], v[194:197], v[118:121]
	v_mfma_f32_16x16x32_bf16 v[114:117], v[160:163], v[194:197], v[114:117]
	v_mfma_f32_16x16x32_bf16 v[102:105], v[152:155], v[198:201], v[102:105]
	v_mfma_f32_16x16x32_bf16 v[98:101], v[160:163], v[198:201], v[98:101]
	v_mfma_f32_16x16x32_bf16 v[86:89], v[152:155], v[218:221], v[86:89]
	v_mfma_f32_16x16x32_bf16 v[82:85], v[160:163], v[218:221], v[82:85]
	v_mfma_f32_16x16x32_bf16 v[70:73], v[152:155], v[222:225], v[70:73]
	v_mfma_f32_16x16x32_bf16 v[66:69], v[160:163], v[222:225], v[66:69]
	s_setprio 0
	s_barrier
	s_add_i32 s43, s96, s62
	v_lshl_add_u64 v[168:169], s[78:79], 0, v[170:171]
	s_mov_b32 m0, s43
	ds_read_b128 v[164:167], v211 offset:16384
	ds_read_b128 v[190:193], v211 offset:18432
	ds_read_b128 v[194:197], v212 offset:16384
	ds_read_b128 v[198:201], v212 offset:18432
	ds_read_b128 v[202:205], v211 offset:20480
	ds_read_b128 v[214:217], v211 offset:22528
	ds_read_b128 v[218:221], v212 offset:20480
	ds_read_b128 v[222:225], v212 offset:22528
	global_load_lds_dwordx4 v[168:169], off
	s_add_i32 m0, s43, 0x2000
	s_add_u32 s44, s78, 0x18000
	v_lshl_add_u64 v[206:207], s[78:79], 0, v[176:177]
	s_addc_u32 s45, s79, 0
	s_add_i32 s43, s83, s62
	global_load_lds_dwordx4 v[206:207], off
	v_lshl_add_u64 v[226:227], s[44:45], 0, v[170:171]
	s_mov_b32 m0, s43
	v_lshl_add_u64 v[228:229], s[80:81], 0, v[174:175]
	global_load_lds_dwordx4 v[226:227], off
	v_lshl_add_u64 v[226:227], s[44:45], 0, v[176:177]
	s_add_i32 m0, s43, 0x2000
	s_nop 0
	global_load_lds_dwordx4 v[226:227], off
	v_lshl_add_u64 v[226:227], s[80:81], 0, v[172:173]
	s_mov_b32 m0, s63
	s_nop 0
	global_load_lds_dwordx4 v[226:227], off
	s_mov_b32 m0, s64
	s_nop 0
	global_load_lds_dwordx4 v[228:229], off
	s_waitcnt vmcnt(8)
	s_waitcnt lgkmcnt(0)
	s_barrier
	s_setprio 1
	s_waitcnt lgkmcnt(0)
	v_mfma_f32_16x16x32_bf16 v[62:65], v[132:135], v[164:167], 0
	v_mfma_f32_16x16x32_bf16 v[58:61], v[140:143], v[164:167], 0
	v_mfma_f32_16x16x32_bf16 v[46:49], v[132:135], v[190:193], 0
	v_mfma_f32_16x16x32_bf16 v[42:45], v[140:143], v[190:193], 0
	v_mfma_f32_16x16x32_bf16 v[30:33], v[132:135], v[202:205], 0
	v_mfma_f32_16x16x32_bf16 v[26:29], v[140:143], v[202:205], 0
	v_mfma_f32_16x16x32_bf16 v[14:17], v[132:135], v[214:217], 0
	v_mfma_f32_16x16x32_bf16 v[10:13], v[140:143], v[214:217], 0
	v_mfma_f32_16x16x32_bf16 v[62:65], v[136:139], v[194:197], v[62:65]
	v_mfma_f32_16x16x32_bf16 v[58:61], v[144:147], v[194:197], v[58:61]
	v_mfma_f32_16x16x32_bf16 v[46:49], v[136:139], v[198:201], v[46:49]
	v_mfma_f32_16x16x32_bf16 v[42:45], v[144:147], v[198:201], v[42:45]
	v_mfma_f32_16x16x32_bf16 v[30:33], v[136:139], v[218:221], v[30:33]
	v_mfma_f32_16x16x32_bf16 v[26:29], v[144:147], v[218:221], v[26:29]
	v_mfma_f32_16x16x32_bf16 v[14:17], v[136:139], v[222:225], v[14:17]
	v_mfma_f32_16x16x32_bf16 v[10:13], v[144:147], v[222:225], v[10:13]
	s_setprio 0
	s_setprio 1
	v_mfma_f32_16x16x32_bf16 v[54:57], v[148:151], v[164:167], 0
	v_mfma_f32_16x16x32_bf16 v[50:53], v[156:159], v[164:167], 0
	v_mfma_f32_16x16x32_bf16 v[38:41], v[148:151], v[190:193], 0
	v_mfma_f32_16x16x32_bf16 v[34:37], v[156:159], v[190:193], 0
	v_mfma_f32_16x16x32_bf16 v[22:25], v[148:151], v[202:205], 0
	v_mfma_f32_16x16x32_bf16 v[18:21], v[156:159], v[202:205], 0
	v_mfma_f32_16x16x32_bf16 v[6:9], v[148:151], v[214:217], 0
	v_mfma_f32_16x16x32_bf16 v[2:5], v[156:159], v[214:217], 0
	v_mfma_f32_16x16x32_bf16 v[54:57], v[152:155], v[194:197], v[54:57]
	v_mfma_f32_16x16x32_bf16 v[50:53], v[160:163], v[194:197], v[50:53]
	v_mfma_f32_16x16x32_bf16 v[38:41], v[152:155], v[198:201], v[38:41]
	v_mfma_f32_16x16x32_bf16 v[34:37], v[160:163], v[198:201], v[34:37]
	v_mfma_f32_16x16x32_bf16 v[22:25], v[152:155], v[218:221], v[22:25]
	v_mfma_f32_16x16x32_bf16 v[18:21], v[160:163], v[218:221], v[18:21]
	v_mfma_f32_16x16x32_bf16 v[6:9], v[152:155], v[222:225], v[6:9]
	v_mfma_f32_16x16x32_bf16 v[2:5], v[160:163], v[222:225], v[2:5]
	s_setprio 0
	s_barrier
	s_add_i32 s43, 0, 0x18000
	s_add_i32 s46, 0, 0x1c000
	v_add_u32_e32 v132, s43, v209
	v_add_u32_e32 v136, s43, v210
	v_add_u32_e32 v140, s26, v209
	v_add_u32_e32 v144, s26, v210
	v_add_u32_e32 v148, s46, v209
	v_add_u32_e32 v152, s46, v210
	v_add_u32_e32 v156, s27, v209
	v_add_u32_e32 v160, s27, v210
	ds_read_b128 v[132:135], v132
	ds_read_b128 v[136:139], v136
	ds_read_b128 v[140:143], v140
	ds_read_b128 v[144:147], v144
	ds_read_b128 v[148:151], v148
	ds_read_b128 v[152:155], v152
	ds_read_b128 v[156:159], v156
	ds_read_b128 v[160:163], v160
	s_add_u32 s44, s80, 0x18000
	s_addc_u32 s45, s81, 0
	s_mov_b32 m0, s65
	v_lshl_add_u64 v[230:231], s[44:45], 0, v[172:173]
	ds_read_b128 v[164:167], v211 offset:32768
	ds_read_b128 v[190:193], v211 offset:34816
	ds_read_b128 v[194:197], v212 offset:32768
	ds_read_b128 v[198:201], v212 offset:34816
	ds_read_b128 v[202:205], v211 offset:36864
	ds_read_b128 v[214:217], v211 offset:38912
	ds_read_b128 v[218:221], v212 offset:36864
	ds_read_b128 v[222:225], v212 offset:38912
	global_load_lds_dwordx4 v[230:231], off
	v_lshl_add_u64 v[230:231], s[44:45], 0, v[174:175]
	s_mov_b32 m0, s82
	s_nop 0
	global_load_lds_dwordx4 v[230:231], off
	s_waitcnt vmcnt(8)
	s_waitcnt lgkmcnt(0)
	s_barrier
	s_setprio 1
	s_waitcnt lgkmcnt(0)
	v_mfma_f32_16x16x32_bf16 v[126:129], v[132:135], v[164:167], v[126:129]
	v_mfma_f32_16x16x32_bf16 v[122:125], v[140:143], v[164:167], v[122:125]
	v_mfma_f32_16x16x32_bf16 v[110:113], v[132:135], v[190:193], v[110:113]
	v_mfma_f32_16x16x32_bf16 v[106:109], v[140:143], v[190:193], v[106:109]
	v_mfma_f32_16x16x32_bf16 v[94:97], v[132:135], v[202:205], v[94:97]
	v_mfma_f32_16x16x32_bf16 v[90:93], v[140:143], v[202:205], v[90:93]
	v_mfma_f32_16x16x32_bf16 v[78:81], v[132:135], v[214:217], v[78:81]
	v_mfma_f32_16x16x32_bf16 v[74:77], v[140:143], v[214:217], v[74:77]
	v_mfma_f32_16x16x32_bf16 v[126:129], v[136:139], v[194:197], v[126:129]
	v_mfma_f32_16x16x32_bf16 v[122:125], v[144:147], v[194:197], v[122:125]
	v_mfma_f32_16x16x32_bf16 v[110:113], v[136:139], v[198:201], v[110:113]
	v_mfma_f32_16x16x32_bf16 v[106:109], v[144:147], v[198:201], v[106:109]
	v_mfma_f32_16x16x32_bf16 v[94:97], v[136:139], v[218:221], v[94:97]
	v_mfma_f32_16x16x32_bf16 v[90:93], v[144:147], v[218:221], v[90:93]
	v_mfma_f32_16x16x32_bf16 v[78:81], v[136:139], v[222:225], v[78:81]
	v_mfma_f32_16x16x32_bf16 v[74:77], v[144:147], v[222:225], v[74:77]
	s_setprio 0
	s_setprio 1
	v_mfma_f32_16x16x32_bf16 v[118:121], v[148:151], v[164:167], v[118:121]
	v_mfma_f32_16x16x32_bf16 v[114:117], v[156:159], v[164:167], v[114:117]
	v_mfma_f32_16x16x32_bf16 v[102:105], v[148:151], v[190:193], v[102:105]
	v_mfma_f32_16x16x32_bf16 v[98:101], v[156:159], v[190:193], v[98:101]
	v_mfma_f32_16x16x32_bf16 v[86:89], v[148:151], v[202:205], v[86:89]
	v_mfma_f32_16x16x32_bf16 v[82:85], v[156:159], v[202:205], v[82:85]
	v_mfma_f32_16x16x32_bf16 v[70:73], v[148:151], v[214:217], v[70:73]
	v_mfma_f32_16x16x32_bf16 v[66:69], v[156:159], v[214:217], v[66:69]
	v_mfma_f32_16x16x32_bf16 v[118:121], v[152:155], v[194:197], v[118:121]
	v_mfma_f32_16x16x32_bf16 v[114:117], v[160:163], v[194:197], v[114:117]
	v_mfma_f32_16x16x32_bf16 v[102:105], v[152:155], v[198:201], v[102:105]
	v_mfma_f32_16x16x32_bf16 v[98:101], v[160:163], v[198:201], v[98:101]
	v_mfma_f32_16x16x32_bf16 v[86:89], v[152:155], v[218:221], v[86:89]
	v_mfma_f32_16x16x32_bf16 v[82:85], v[160:163], v[218:221], v[82:85]
	v_mfma_f32_16x16x32_bf16 v[70:73], v[152:155], v[222:225], v[70:73]
	v_mfma_f32_16x16x32_bf16 v[66:69], v[160:163], v[222:225], v[66:69]
	s_setprio 0
	s_barrier
	s_add_i32 s43, s43, s62
	v_lshl_add_u64 v[168:169], v[168:169], 0, s[14:15]
	s_mov_b32 m0, s43
	ds_read_b128 v[164:167], v211 offset:49152
	ds_read_b128 v[190:193], v211 offset:51200
	ds_read_b128 v[194:197], v212 offset:49152
	ds_read_b128 v[198:201], v212 offset:51200
	ds_read_b128 v[202:205], v211 offset:53248
	ds_read_b128 v[214:217], v211 offset:55296
	ds_read_b128 v[218:221], v212 offset:53248
	ds_read_b128 v[222:225], v212 offset:55296
	global_load_lds_dwordx4 v[168:169], off
	s_add_i32 m0, s43, 0x2000
	s_add_u32 s44, s78, 0x18080
	v_lshl_add_u64 v[168:169], v[206:207], 0, s[14:15]
	s_addc_u32 s45, s79, 0
	s_add_i32 s43, s46, s62
	global_load_lds_dwordx4 v[168:169], off
	v_lshl_add_u64 v[168:169], s[44:45], 0, v[170:171]
	s_mov_b32 m0, s43
	s_nop 0
	global_load_lds_dwordx4 v[168:169], off
	v_lshl_add_u64 v[168:169], s[44:45], 0, v[176:177]
	s_add_i32 m0, s43, 0x2000
	s_nop 0
	global_load_lds_dwordx4 v[168:169], off
	v_lshl_add_u64 v[168:169], v[226:227], 0, s[14:15]
	s_mov_b32 m0, s89
	s_nop 0
	global_load_lds_dwordx4 v[168:169], off
	v_lshl_add_u64 v[168:169], v[228:229], 0, s[14:15]
	s_mov_b32 m0, s91
	s_nop 0
	global_load_lds_dwordx4 v[168:169], off
	s_waitcnt vmcnt(8)
	s_waitcnt lgkmcnt(0)
	s_barrier
	s_setprio 1
	s_waitcnt lgkmcnt(0)
	v_mfma_f32_16x16x32_bf16 v[62:65], v[132:135], v[164:167], v[62:65]
	v_mfma_f32_16x16x32_bf16 v[58:61], v[140:143], v[164:167], v[58:61]
	v_mfma_f32_16x16x32_bf16 v[46:49], v[132:135], v[190:193], v[46:49]
	v_mfma_f32_16x16x32_bf16 v[42:45], v[140:143], v[190:193], v[42:45]
	v_mfma_f32_16x16x32_bf16 v[30:33], v[132:135], v[202:205], v[30:33]
	v_mfma_f32_16x16x32_bf16 v[26:29], v[140:143], v[202:205], v[26:29]
	v_mfma_f32_16x16x32_bf16 v[14:17], v[132:135], v[214:217], v[14:17]
	v_mfma_f32_16x16x32_bf16 v[10:13], v[140:143], v[214:217], v[10:13]
	v_mfma_f32_16x16x32_bf16 v[62:65], v[136:139], v[194:197], v[62:65]
	v_mfma_f32_16x16x32_bf16 v[58:61], v[144:147], v[194:197], v[58:61]
	v_mfma_f32_16x16x32_bf16 v[46:49], v[136:139], v[198:201], v[46:49]
	v_mfma_f32_16x16x32_bf16 v[42:45], v[144:147], v[198:201], v[42:45]
	v_mfma_f32_16x16x32_bf16 v[30:33], v[136:139], v[218:221], v[30:33]
	v_mfma_f32_16x16x32_bf16 v[26:29], v[144:147], v[218:221], v[26:29]
	v_mfma_f32_16x16x32_bf16 v[14:17], v[136:139], v[222:225], v[14:17]
	v_mfma_f32_16x16x32_bf16 v[10:13], v[144:147], v[222:225], v[10:13]
	s_setprio 0
	s_setprio 1
	v_mfma_f32_16x16x32_bf16 v[54:57], v[148:151], v[164:167], v[54:57]
	v_mfma_f32_16x16x32_bf16 v[50:53], v[156:159], v[164:167], v[50:53]
	v_mfma_f32_16x16x32_bf16 v[38:41], v[148:151], v[190:193], v[38:41]
	v_mfma_f32_16x16x32_bf16 v[34:37], v[156:159], v[190:193], v[34:37]
	v_mfma_f32_16x16x32_bf16 v[22:25], v[148:151], v[202:205], v[22:25]
	v_mfma_f32_16x16x32_bf16 v[18:21], v[156:159], v[202:205], v[18:21]
	v_mfma_f32_16x16x32_bf16 v[6:9], v[148:151], v[214:217], v[6:9]
	v_mfma_f32_16x16x32_bf16 v[2:5], v[156:159], v[214:217], v[2:5]
	v_mfma_f32_16x16x32_bf16 v[54:57], v[152:155], v[194:197], v[54:57]
	v_mfma_f32_16x16x32_bf16 v[50:53], v[160:163], v[194:197], v[50:53]
	v_mfma_f32_16x16x32_bf16 v[38:41], v[152:155], v[198:201], v[38:41]
	v_mfma_f32_16x16x32_bf16 v[34:37], v[160:163], v[198:201], v[34:37]
	v_mfma_f32_16x16x32_bf16 v[22:25], v[152:155], v[218:221], v[22:25]
	v_mfma_f32_16x16x32_bf16 v[18:21], v[160:163], v[218:221], v[18:21]
	v_mfma_f32_16x16x32_bf16 v[6:9], v[152:155], v[222:225], v[6:9]
	v_mfma_f32_16x16x32_bf16 v[2:5], v[160:163], v[222:225], v[2:5]
	s_setprio 0
	s_barrier
	s_add_u32 s12, s12, 0x100
	s_addc_u32 s13, s13, 0
	s_add_u32 s48, s48, 0x100
	s_addc_u32 s72, s72, 0
	s_cmp_ge_i32 s42, s39
	s_cbranch_scc1 .LBB0_1320
	s_branch .LBB0_1317

.LBB0_1628:
	s_ashr_i32 s15, s14, 31
	s_lshl_b64 s[16:17], s[14:15], 19
	s_add_u32 s16, s3, s16
	s_addc_u32 s17, s90, s17
	s_and_b64 s[18:19], s[6:7], exec
	s_cselect_b32 s15, s17, s25
	s_cselect_b32 s21, s16, s24
	s_ashr_i32 s13, s12, 31
	s_lshl_b64 s[18:19], s[12:13], 19
	s_add_u32 s18, s38, s18
	s_addc_u32 s19, s39, s19
	s_and_b64 s[28:29], s[6:7], exec
	s_cselect_b32 s13, s19, s27
	s_cselect_b32 s23, s18, s26
	s_add_u32 s24, s24, 0x40080
	s_addc_u32 s25, s25, 0
	s_add_u32 s55, s26, 0x100
	s_mov_b32 s100, 1
	s_addc_u32 s56, s27, 0
	s_mov_b32 s57, -2
	s_waitcnt vmcnt(0)
.LBB0_1629:
	s_cmp_lg_u32 s100, 0
	s_cbranch_scc1 .Lpeel_4
	ds_read_b128 v[90:93], v211
	ds_read_b128 v[102:105], v212
	ds_read_b128 v[114:117], v213
	ds_read_b128 v[126:129], v214
	ds_read_b128 v[138:141], v215
	ds_read_b128 v[150:153], v216
	ds_read_b128 v[154:157], v217
	ds_read_b128 v[158:161], v218
	s_add_u32 s26, s24, 0xfffc0080
	s_addc_u32 s27, s25, -1
	s_cmp_eq_u32 s57, 12
	s_cselect_b32 s29, s15, s27
	s_cselect_b32 s28, s21, s26
	s_cselect_b32 s27, s13, s56
	s_cselect_b32 s26, s23, s55
	v_lshl_add_u64 v[230:231], s[24:25], 0, v[196:197]
	s_add_i32 m0, s41, 0xc000
	ds_read_b128 v[162:165], v219
	ds_read_b128 v[166:169], v219 offset:2048
	ds_read_b128 v[170:173], v220
	ds_read_b128 v[174:177], v220 offset:2048
	ds_read_b128 v[178:181], v219 offset:4096
	ds_read_b128 v[182:185], v219 offset:6144
	ds_read_b128 v[204:207], v220 offset:4096
	ds_read_b128 v[226:229], v220 offset:6144
	global_load_lds_dwordx4 v[230:231], off
	v_lshl_add_u64 v[230:231], s[24:25], 0, v[198:199]
	s_add_i32 m0, s41, 0xe000
	s_nop 0
	global_load_lds_dwordx4 v[230:231], off
	s_waitcnt vmcnt(8)
	s_waitcnt lgkmcnt(0)
	s_barrier
	s_setprio 1
	s_waitcnt lgkmcnt(0)
	v_mfma_f32_16x16x32_bf16 v[146:149], v[90:93], v[162:165], v[146:149]
	v_mfma_f32_16x16x32_bf16 v[142:145], v[114:117], v[162:165], v[142:145]
	v_mfma_f32_16x16x32_bf16 v[122:125], v[90:93], v[166:169], v[122:125]
	v_mfma_f32_16x16x32_bf16 v[118:121], v[114:117], v[166:169], v[118:121]
	v_mfma_f32_16x16x32_bf16 v[98:101], v[90:93], v[178:181], v[98:101]
	v_mfma_f32_16x16x32_bf16 v[94:97], v[114:117], v[178:181], v[94:97]
	v_mfma_f32_16x16x32_bf16 v[78:81], v[90:93], v[182:185], v[78:81]
	v_mfma_f32_16x16x32_bf16 v[74:77], v[114:117], v[182:185], v[74:77]
	v_mfma_f32_16x16x32_bf16 v[146:149], v[102:105], v[170:173], v[146:149]
	v_mfma_f32_16x16x32_bf16 v[142:145], v[126:129], v[170:173], v[142:145]
	v_mfma_f32_16x16x32_bf16 v[122:125], v[102:105], v[174:177], v[122:125]
	v_mfma_f32_16x16x32_bf16 v[118:121], v[126:129], v[174:177], v[118:121]
	v_mfma_f32_16x16x32_bf16 v[98:101], v[102:105], v[204:207], v[98:101]
	v_mfma_f32_16x16x32_bf16 v[94:97], v[126:129], v[204:207], v[94:97]
	v_mfma_f32_16x16x32_bf16 v[78:81], v[102:105], v[226:229], v[78:81]
	v_mfma_f32_16x16x32_bf16 v[74:77], v[126:129], v[226:229], v[74:77]
	s_setprio 0
	s_setprio 1
	v_mfma_f32_16x16x32_bf16 v[134:137], v[138:141], v[162:165], v[134:137]
	v_mfma_f32_16x16x32_bf16 v[130:133], v[154:157], v[162:165], v[130:133]
	v_mfma_f32_16x16x32_bf16 v[110:113], v[138:141], v[166:169], v[110:113]
	v_mfma_f32_16x16x32_bf16 v[106:109], v[154:157], v[166:169], v[106:109]
	v_mfma_f32_16x16x32_bf16 v[86:89], v[138:141], v[178:181], v[86:89]
	v_mfma_f32_16x16x32_bf16 v[82:85], v[154:157], v[178:181], v[82:85]
	v_mfma_f32_16x16x32_bf16 v[70:73], v[138:141], v[182:185], v[70:73]
	v_mfma_f32_16x16x32_bf16 v[66:69], v[154:157], v[182:185], v[66:69]
	v_mfma_f32_16x16x32_bf16 v[134:137], v[150:153], v[170:173], v[134:137]
	v_mfma_f32_16x16x32_bf16 v[130:133], v[158:161], v[170:173], v[130:133]
	v_mfma_f32_16x16x32_bf16 v[110:113], v[150:153], v[174:177], v[110:113]
	v_mfma_f32_16x16x32_bf16 v[106:109], v[158:161], v[174:177], v[106:109]
	v_mfma_f32_16x16x32_bf16 v[86:89], v[150:153], v[204:207], v[86:89]
	v_mfma_f32_16x16x32_bf16 v[82:85], v[158:161], v[204:207], v[82:85]
	v_mfma_f32_16x16x32_bf16 v[70:73], v[150:153], v[226:229], v[70:73]
	v_mfma_f32_16x16x32_bf16 v[66:69], v[158:161], v[226:229], v[66:69]
	s_setprio 0
	s_barrier
	s_add_i32 s58, s53, s40
	v_lshl_add_u64 v[230:231], s[26:27], 0, v[188:189]
	s_mov_b32 m0, s58
	ds_read_b128 v[162:165], v219 offset:16384
	ds_read_b128 v[166:169], v219 offset:18432
	ds_read_b128 v[170:173], v220 offset:16384
	ds_read_b128 v[174:177], v220 offset:18432
	ds_read_b128 v[178:181], v219 offset:20480
	ds_read_b128 v[182:185], v219 offset:22528
	ds_read_b128 v[204:207], v220 offset:20480
	ds_read_b128 v[226:229], v220 offset:22528
	global_load_lds_dwordx4 v[230:231], off
	s_add_i32 m0, s58, 0x2000
	s_add_u32 s58, s26, 0x40000
	v_lshl_add_u64 v[232:233], s[26:27], 0, v[192:193]
	s_addc_u32 s59, s27, 0
	s_add_i32 s60, s54, s40
	global_load_lds_dwordx4 v[232:233], off
	v_lshl_add_u64 v[234:235], s[58:59], 0, v[188:189]
	s_mov_b32 m0, s60
	v_lshl_add_u64 v[236:237], s[28:29], 0, v[190:191]
	global_load_lds_dwordx4 v[234:235], off
	v_lshl_add_u64 v[234:235], s[58:59], 0, v[192:193]
	s_add_i32 m0, s60, 0x2000
	s_nop 0
	global_load_lds_dwordx4 v[234:235], off
	v_lshl_add_u64 v[234:235], s[28:29], 0, v[186:187]
	s_mov_b32 m0, s41
	s_nop 0
	global_load_lds_dwordx4 v[234:235], off
	s_mov_b32 m0, s42
	s_nop 0
	global_load_lds_dwordx4 v[236:237], off
	s_waitcnt vmcnt(8)
	s_waitcnt lgkmcnt(0)
	s_barrier
	s_setprio 1
	s_waitcnt lgkmcnt(0)
	v_mfma_f32_16x16x32_bf16 v[62:65], v[90:93], v[162:165], v[62:65]
	v_mfma_f32_16x16x32_bf16 v[58:61], v[114:117], v[162:165], v[58:61]
	v_mfma_f32_16x16x32_bf16 v[46:49], v[90:93], v[166:169], v[46:49]
	v_mfma_f32_16x16x32_bf16 v[42:45], v[114:117], v[166:169], v[42:45]
	v_mfma_f32_16x16x32_bf16 v[30:33], v[90:93], v[178:181], v[30:33]
	v_mfma_f32_16x16x32_bf16 v[26:29], v[114:117], v[178:181], v[26:29]
	v_mfma_f32_16x16x32_bf16 v[14:17], v[90:93], v[182:185], v[14:17]
	v_mfma_f32_16x16x32_bf16 v[10:13], v[114:117], v[182:185], v[10:13]
	v_mfma_f32_16x16x32_bf16 v[62:65], v[102:105], v[170:173], v[62:65]
	v_mfma_f32_16x16x32_bf16 v[58:61], v[126:129], v[170:173], v[58:61]
	v_mfma_f32_16x16x32_bf16 v[46:49], v[102:105], v[174:177], v[46:49]
	v_mfma_f32_16x16x32_bf16 v[42:45], v[126:129], v[174:177], v[42:45]
	v_mfma_f32_16x16x32_bf16 v[30:33], v[102:105], v[204:207], v[30:33]
	v_mfma_f32_16x16x32_bf16 v[26:29], v[126:129], v[204:207], v[26:29]
	v_mfma_f32_16x16x32_bf16 v[14:17], v[102:105], v[226:229], v[14:17]
	v_mfma_f32_16x16x32_bf16 v[10:13], v[126:129], v[226:229], v[10:13]
	s_setprio 0
	s_setprio 1
	v_mfma_f32_16x16x32_bf16 v[54:57], v[138:141], v[162:165], v[54:57]
	v_mfma_f32_16x16x32_bf16 v[50:53], v[154:157], v[162:165], v[50:53]
	v_mfma_f32_16x16x32_bf16 v[38:41], v[138:141], v[166:169], v[38:41]
	v_mfma_f32_16x16x32_bf16 v[34:37], v[154:157], v[166:169], v[34:37]
	v_mfma_f32_16x16x32_bf16 v[22:25], v[138:141], v[178:181], v[22:25]
	v_mfma_f32_16x16x32_bf16 v[18:21], v[154:157], v[178:181], v[18:21]
	v_mfma_f32_16x16x32_bf16 v[6:9], v[138:141], v[182:185], v[6:9]
	v_mfma_f32_16x16x32_bf16 v[2:5], v[154:157], v[182:185], v[2:5]
	v_mfma_f32_16x16x32_bf16 v[54:57], v[150:153], v[170:173], v[54:57]
	v_mfma_f32_16x16x32_bf16 v[50:53], v[158:161], v[170:173], v[50:53]
	v_mfma_f32_16x16x32_bf16 v[38:41], v[150:153], v[174:177], v[38:41]
	v_mfma_f32_16x16x32_bf16 v[34:37], v[158:161], v[174:177], v[34:37]
	v_mfma_f32_16x16x32_bf16 v[22:25], v[150:153], v[204:207], v[22:25]
	v_mfma_f32_16x16x32_bf16 v[18:21], v[158:161], v[204:207], v[18:21]
	v_mfma_f32_16x16x32_bf16 v[6:9], v[150:153], v[226:229], v[6:9]
	v_mfma_f32_16x16x32_bf16 v[2:5], v[158:161], v[226:229], v[2:5]
	s_setprio 0
	s_barrier
	s_add_i32 s58, 0, 0x18000
	s_add_i32 s59, 0, 0x1c000
	v_add_u32_e32 v90, s58, v209
	v_add_u32_e32 v102, s58, v210
	v_add_u32_e32 v138, s59, v209
	v_add_u32_e32 v150, s59, v210
	ds_read_b128 v[90:93], v90
	ds_read_b128 v[102:105], v102
	ds_read_b128 v[114:117], v221
	ds_read_b128 v[126:129], v222
	ds_read_b128 v[138:141], v138
	ds_read_b128 v[150:153], v150
	ds_read_b128 v[154:157], v223
	ds_read_b128 v[158:161], v224
	s_add_u32 s28, s28, 0x40000
	s_addc_u32 s29, s29, 0
	s_mov_b32 m0, s43
	v_lshl_add_u64 v[238:239], s[28:29], 0, v[186:187]
	ds_read_b128 v[162:165], v219 offset:32768
	ds_read_b128 v[166:169], v219 offset:34816
	ds_read_b128 v[170:173], v220 offset:32768
	ds_read_b128 v[174:177], v220 offset:34816
	ds_read_b128 v[178:181], v219 offset:36864
	ds_read_b128 v[182:185], v219 offset:38912
	ds_read_b128 v[204:207], v220 offset:36864
	ds_read_b128 v[226:229], v220 offset:38912
	global_load_lds_dwordx4 v[238:239], off
	v_lshl_add_u64 v[238:239], s[28:29], 0, v[190:191]
	s_mov_b32 m0, s44
	s_nop 0
	global_load_lds_dwordx4 v[238:239], off
	s_waitcnt vmcnt(8)
	s_waitcnt lgkmcnt(0)
	s_barrier
	s_setprio 1
	s_waitcnt lgkmcnt(0)
	v_mfma_f32_16x16x32_bf16 v[146:149], v[90:93], v[162:165], v[146:149]
	v_mfma_f32_16x16x32_bf16 v[142:145], v[114:117], v[162:165], v[142:145]
	v_mfma_f32_16x16x32_bf16 v[122:125], v[90:93], v[166:169], v[122:125]
	v_mfma_f32_16x16x32_bf16 v[118:121], v[114:117], v[166:169], v[118:121]
	v_mfma_f32_16x16x32_bf16 v[98:101], v[90:93], v[178:181], v[98:101]
	v_mfma_f32_16x16x32_bf16 v[94:97], v[114:117], v[178:181], v[94:97]
	v_mfma_f32_16x16x32_bf16 v[78:81], v[90:93], v[182:185], v[78:81]
	v_mfma_f32_16x16x32_bf16 v[74:77], v[114:117], v[182:185], v[74:77]
	v_mfma_f32_16x16x32_bf16 v[146:149], v[102:105], v[170:173], v[146:149]
	v_mfma_f32_16x16x32_bf16 v[142:145], v[126:129], v[170:173], v[142:145]
	v_mfma_f32_16x16x32_bf16 v[122:125], v[102:105], v[174:177], v[122:125]
	v_mfma_f32_16x16x32_bf16 v[118:121], v[126:129], v[174:177], v[118:121]
	v_mfma_f32_16x16x32_bf16 v[98:101], v[102:105], v[204:207], v[98:101]
	v_mfma_f32_16x16x32_bf16 v[94:97], v[126:129], v[204:207], v[94:97]
	v_mfma_f32_16x16x32_bf16 v[78:81], v[102:105], v[226:229], v[78:81]
	v_mfma_f32_16x16x32_bf16 v[74:77], v[126:129], v[226:229], v[74:77]
	s_setprio 0
	s_setprio 1
	v_mfma_f32_16x16x32_bf16 v[134:137], v[138:141], v[162:165], v[134:137]
	v_mfma_f32_16x16x32_bf16 v[130:133], v[154:157], v[162:165], v[130:133]
	v_mfma_f32_16x16x32_bf16 v[110:113], v[138:141], v[166:169], v[110:113]
	v_mfma_f32_16x16x32_bf16 v[106:109], v[154:157], v[166:169], v[106:109]
	v_mfma_f32_16x16x32_bf16 v[86:89], v[138:141], v[178:181], v[86:89]
	v_mfma_f32_16x16x32_bf16 v[82:85], v[154:157], v[178:181], v[82:85]
	v_mfma_f32_16x16x32_bf16 v[70:73], v[138:141], v[182:185], v[70:73]
	v_mfma_f32_16x16x32_bf16 v[66:69], v[154:157], v[182:185], v[66:69]
	v_mfma_f32_16x16x32_bf16 v[134:137], v[150:153], v[170:173], v[134:137]
	v_mfma_f32_16x16x32_bf16 v[130:133], v[158:161], v[170:173], v[130:133]
	v_mfma_f32_16x16x32_bf16 v[110:113], v[150:153], v[174:177], v[110:113]
	v_mfma_f32_16x16x32_bf16 v[106:109], v[158:161], v[174:177], v[106:109]
	v_mfma_f32_16x16x32_bf16 v[86:89], v[150:153], v[204:207], v[86:89]
	v_mfma_f32_16x16x32_bf16 v[82:85], v[158:161], v[204:207], v[82:85]
	v_mfma_f32_16x16x32_bf16 v[70:73], v[150:153], v[226:229], v[70:73]
	v_mfma_f32_16x16x32_bf16 v[66:69], v[158:161], v[226:229], v[66:69]
	s_setprio 0
	s_barrier
	s_add_i32 s28, s58, s40
	v_lshl_add_u64 v[230:231], v[230:231], 0, s[8:9]
	s_mov_b32 m0, s28
	ds_read_b128 v[162:165], v219 offset:49152
	ds_read_b128 v[166:169], v219 offset:51200
	ds_read_b128 v[170:173], v220 offset:49152
	ds_read_b128 v[174:177], v220 offset:51200
	ds_read_b128 v[178:181], v219 offset:53248
	ds_read_b128 v[182:185], v219 offset:55296
	ds_read_b128 v[204:207], v220 offset:53248
	ds_read_b128 v[226:229], v220 offset:55296
	global_load_lds_dwordx4 v[230:231], off
	s_add_i32 m0, s28, 0x2000
	s_add_u32 s26, s26, 0x40080
	v_lshl_add_u64 v[230:231], v[232:233], 0, s[8:9]
	s_addc_u32 s27, s27, 0
	s_add_i32 s28, s59, s40
	global_load_lds_dwordx4 v[230:231], off
	v_lshl_add_u64 v[230:231], s[26:27], 0, v[188:189]
	s_mov_b32 m0, s28
	s_nop 0
	global_load_lds_dwordx4 v[230:231], off
	v_lshl_add_u64 v[230:231], s[26:27], 0, v[192:193]
	s_add_i32 m0, s28, 0x2000
	s_nop 0
	global_load_lds_dwordx4 v[230:231], off
	v_lshl_add_u64 v[230:231], v[234:235], 0, s[8:9]
	s_mov_b32 m0, s48
	s_nop 0
	global_load_lds_dwordx4 v[230:231], off
	v_lshl_add_u64 v[230:231], v[236:237], 0, s[8:9]
	s_mov_b32 m0, s49
	s_nop 0
	global_load_lds_dwordx4 v[230:231], off
	s_waitcnt vmcnt(8)
	s_waitcnt lgkmcnt(0)
	s_barrier
	s_setprio 1
	s_waitcnt lgkmcnt(0)
	v_mfma_f32_16x16x32_bf16 v[62:65], v[90:93], v[162:165], v[62:65]
	v_mfma_f32_16x16x32_bf16 v[58:61], v[114:117], v[162:165], v[58:61]
	v_mfma_f32_16x16x32_bf16 v[46:49], v[90:93], v[166:169], v[46:49]
	v_mfma_f32_16x16x32_bf16 v[42:45], v[114:117], v[166:169], v[42:45]
	v_mfma_f32_16x16x32_bf16 v[30:33], v[90:93], v[178:181], v[30:33]
	v_mfma_f32_16x16x32_bf16 v[26:29], v[114:117], v[178:181], v[26:29]
	v_mfma_f32_16x16x32_bf16 v[14:17], v[90:93], v[182:185], v[14:17]
	v_mfma_f32_16x16x32_bf16 v[10:13], v[114:117], v[182:185], v[10:13]
	v_mfma_f32_16x16x32_bf16 v[62:65], v[102:105], v[170:173], v[62:65]
	v_mfma_f32_16x16x32_bf16 v[58:61], v[126:129], v[170:173], v[58:61]
	v_mfma_f32_16x16x32_bf16 v[46:49], v[102:105], v[174:177], v[46:49]
	v_mfma_f32_16x16x32_bf16 v[42:45], v[126:129], v[174:177], v[42:45]
	v_mfma_f32_16x16x32_bf16 v[30:33], v[102:105], v[204:207], v[30:33]
	v_mfma_f32_16x16x32_bf16 v[26:29], v[126:129], v[204:207], v[26:29]
	v_mfma_f32_16x16x32_bf16 v[14:17], v[102:105], v[226:229], v[14:17]
	v_mfma_f32_16x16x32_bf16 v[10:13], v[126:129], v[226:229], v[10:13]
	s_setprio 0
	s_setprio 1
	v_mfma_f32_16x16x32_bf16 v[54:57], v[138:141], v[162:165], v[54:57]
	v_mfma_f32_16x16x32_bf16 v[50:53], v[154:157], v[162:165], v[50:53]
	v_mfma_f32_16x16x32_bf16 v[38:41], v[138:141], v[166:169], v[38:41]
	v_mfma_f32_16x16x32_bf16 v[34:37], v[154:157], v[166:169], v[34:37]
	v_mfma_f32_16x16x32_bf16 v[22:25], v[138:141], v[178:181], v[22:25]
	v_mfma_f32_16x16x32_bf16 v[18:21], v[154:157], v[178:181], v[18:21]
	v_mfma_f32_16x16x32_bf16 v[6:9], v[138:141], v[182:185], v[6:9]
	v_mfma_f32_16x16x32_bf16 v[2:5], v[154:157], v[182:185], v[2:5]
	v_mfma_f32_16x16x32_bf16 v[54:57], v[150:153], v[170:173], v[54:57]
	v_mfma_f32_16x16x32_bf16 v[50:53], v[158:161], v[170:173], v[50:53]
	v_mfma_f32_16x16x32_bf16 v[38:41], v[150:153], v[174:177], v[38:41]
	v_mfma_f32_16x16x32_bf16 v[34:37], v[158:161], v[174:177], v[34:37]
	v_mfma_f32_16x16x32_bf16 v[22:25], v[150:153], v[204:207], v[22:25]
	v_mfma_f32_16x16x32_bf16 v[18:21], v[158:161], v[204:207], v[18:21]
	v_mfma_f32_16x16x32_bf16 v[6:9], v[150:153], v[226:229], v[6:9]
	v_mfma_f32_16x16x32_bf16 v[2:5], v[158:161], v[226:229], v[2:5]
	s_setprio 0
	s_barrier
	s_add_i32 s57, s57, 2
	s_add_u32 s24, s24, 0x100
	s_addc_u32 s25, s25, 0
	s_add_u32 s55, s55, 0x100
	s_addc_u32 s56, s56, 0
	s_cmp_gt_u32 s57, 13
	s_cbranch_scc0 .LBB0_1629
	s_branch .Lpx_4
.Lpeel_4:
	s_mov_b32 s100, 0
	ds_read_b128 v[90:93], v211
	ds_read_b128 v[102:105], v212
	ds_read_b128 v[114:117], v213
	ds_read_b128 v[126:129], v214
	ds_read_b128 v[138:141], v215
	ds_read_b128 v[150:153], v216
	ds_read_b128 v[154:157], v217
	ds_read_b128 v[158:161], v218
	s_add_u32 s26, s24, 0xfffc0080
	s_addc_u32 s27, s25, -1
	s_cmp_eq_u32 s57, 12
	s_cselect_b32 s29, s15, s27
	s_cselect_b32 s28, s21, s26
	s_cselect_b32 s27, s13, s56
	s_cselect_b32 s26, s23, s55
	v_lshl_add_u64 v[230:231], s[24:25], 0, v[196:197]
	s_add_i32 m0, s41, 0xc000
	ds_read_b128 v[162:165], v219
	ds_read_b128 v[166:169], v219 offset:2048
	ds_read_b128 v[170:173], v220
	ds_read_b128 v[174:177], v220 offset:2048
	ds_read_b128 v[178:181], v219 offset:4096
	ds_read_b128 v[182:185], v219 offset:6144
	ds_read_b128 v[204:207], v220 offset:4096
	ds_read_b128 v[226:229], v220 offset:6144
	global_load_lds_dwordx4 v[230:231], off
	v_lshl_add_u64 v[230:231], s[24:25], 0, v[198:199]
	s_add_i32 m0, s41, 0xe000
	s_nop 0
	global_load_lds_dwordx4 v[230:231], off
	s_waitcnt vmcnt(8)
	s_waitcnt lgkmcnt(0)
	s_barrier
	s_setprio 1
	s_waitcnt lgkmcnt(0)
	v_mfma_f32_16x16x32_bf16 v[146:149], v[90:93], v[162:165], 0
	v_mfma_f32_16x16x32_bf16 v[142:145], v[114:117], v[162:165], 0
	v_mfma_f32_16x16x32_bf16 v[122:125], v[90:93], v[166:169], 0
	v_mfma_f32_16x16x32_bf16 v[118:121], v[114:117], v[166:169], 0
	v_mfma_f32_16x16x32_bf16 v[98:101], v[90:93], v[178:181], 0
	v_mfma_f32_16x16x32_bf16 v[94:97], v[114:117], v[178:181], 0
	v_mfma_f32_16x16x32_bf16 v[78:81], v[90:93], v[182:185], 0
	v_mfma_f32_16x16x32_bf16 v[74:77], v[114:117], v[182:185], 0
	v_mfma_f32_16x16x32_bf16 v[146:149], v[102:105], v[170:173], v[146:149]
	v_mfma_f32_16x16x32_bf16 v[142:145], v[126:129], v[170:173], v[142:145]
	v_mfma_f32_16x16x32_bf16 v[122:125], v[102:105], v[174:177], v[122:125]
	v_mfma_f32_16x16x32_bf16 v[118:121], v[126:129], v[174:177], v[118:121]
	v_mfma_f32_16x16x32_bf16 v[98:101], v[102:105], v[204:207], v[98:101]
	v_mfma_f32_16x16x32_bf16 v[94:97], v[126:129], v[204:207], v[94:97]
	v_mfma_f32_16x16x32_bf16 v[78:81], v[102:105], v[226:229], v[78:81]
	v_mfma_f32_16x16x32_bf16 v[74:77], v[126:129], v[226:229], v[74:77]
	s_setprio 0
	s_setprio 1
	v_mfma_f32_16x16x32_bf16 v[134:137], v[138:141], v[162:165], 0
	v_mfma_f32_16x16x32_bf16 v[130:133], v[154:157], v[162:165], 0
	v_mfma_f32_16x16x32_bf16 v[110:113], v[138:141], v[166:169], 0
	v_mfma_f32_16x16x32_bf16 v[106:109], v[154:157], v[166:169], 0
	v_mfma_f32_16x16x32_bf16 v[86:89], v[138:141], v[178:181], 0
	v_mfma_f32_16x16x32_bf16 v[82:85], v[154:157], v[178:181], 0
	v_mfma_f32_16x16x32_bf16 v[70:73], v[138:141], v[182:185], 0
	v_mfma_f32_16x16x32_bf16 v[66:69], v[154:157], v[182:185], 0
	v_mfma_f32_16x16x32_bf16 v[134:137], v[150:153], v[170:173], v[134:137]
	v_mfma_f32_16x16x32_bf16 v[130:133], v[158:161], v[170:173], v[130:133]
	v_mfma_f32_16x16x32_bf16 v[110:113], v[150:153], v[174:177], v[110:113]
	v_mfma_f32_16x16x32_bf16 v[106:109], v[158:161], v[174:177], v[106:109]
	v_mfma_f32_16x16x32_bf16 v[86:89], v[150:153], v[204:207], v[86:89]
	v_mfma_f32_16x16x32_bf16 v[82:85], v[158:161], v[204:207], v[82:85]
	v_mfma_f32_16x16x32_bf16 v[70:73], v[150:153], v[226:229], v[70:73]
	v_mfma_f32_16x16x32_bf16 v[66:69], v[158:161], v[226:229], v[66:69]
	s_setprio 0
	s_barrier
	s_add_i32 s58, s53, s40
	v_lshl_add_u64 v[230:231], s[26:27], 0, v[188:189]
	s_mov_b32 m0, s58
	ds_read_b128 v[162:165], v219 offset:16384
	ds_read_b128 v[166:169], v219 offset:18432
	ds_read_b128 v[170:173], v220 offset:16384
	ds_read_b128 v[174:177], v220 offset:18432
	ds_read_b128 v[178:181], v219 offset:20480
	ds_read_b128 v[182:185], v219 offset:22528
	ds_read_b128 v[204:207], v220 offset:20480
	ds_read_b128 v[226:229], v220 offset:22528
	global_load_lds_dwordx4 v[230:231], off
	s_add_i32 m0, s58, 0x2000
	s_add_u32 s58, s26, 0x40000
	v_lshl_add_u64 v[232:233], s[26:27], 0, v[192:193]
	s_addc_u32 s59, s27, 0
	s_add_i32 s60, s54, s40
	global_load_lds_dwordx4 v[232:233], off
	v_lshl_add_u64 v[234:235], s[58:59], 0, v[188:189]
	s_mov_b32 m0, s60
	v_lshl_add_u64 v[236:237], s[28:29], 0, v[190:191]
	global_load_lds_dwordx4 v[234:235], off
	v_lshl_add_u64 v[234:235], s[58:59], 0, v[192:193]
	s_add_i32 m0, s60, 0x2000
	s_nop 0
	global_load_lds_dwordx4 v[234:235], off
	v_lshl_add_u64 v[234:235], s[28:29], 0, v[186:187]
	s_mov_b32 m0, s41
	s_nop 0
	global_load_lds_dwordx4 v[234:235], off
	s_mov_b32 m0, s42
	s_nop 0
	global_load_lds_dwordx4 v[236:237], off
	s_waitcnt vmcnt(8)
	s_waitcnt lgkmcnt(0)
	s_barrier
	s_setprio 1
	s_waitcnt lgkmcnt(0)
	v_mfma_f32_16x16x32_bf16 v[62:65], v[90:93], v[162:165], 0
	v_mfma_f32_16x16x32_bf16 v[58:61], v[114:117], v[162:165], 0
	v_mfma_f32_16x16x32_bf16 v[46:49], v[90:93], v[166:169], 0
	v_mfma_f32_16x16x32_bf16 v[42:45], v[114:117], v[166:169], 0
	v_mfma_f32_16x16x32_bf16 v[30:33], v[90:93], v[178:181], 0
	v_mfma_f32_16x16x32_bf16 v[26:29], v[114:117], v[178:181], 0
	v_mfma_f32_16x16x32_bf16 v[14:17], v[90:93], v[182:185], 0
	v_mfma_f32_16x16x32_bf16 v[10:13], v[114:117], v[182:185], 0
	v_mfma_f32_16x16x32_bf16 v[62:65], v[102:105], v[170:173], v[62:65]
	v_mfma_f32_16x16x32_bf16 v[58:61], v[126:129], v[170:173], v[58:61]
	v_mfma_f32_16x16x32_bf16 v[46:49], v[102:105], v[174:177], v[46:49]
	v_mfma_f32_16x16x32_bf16 v[42:45], v[126:129], v[174:177], v[42:45]
	v_mfma_f32_16x16x32_bf16 v[30:33], v[102:105], v[204:207], v[30:33]
	v_mfma_f32_16x16x32_bf16 v[26:29], v[126:129], v[204:207], v[26:29]
	v_mfma_f32_16x16x32_bf16 v[14:17], v[102:105], v[226:229], v[14:17]
	v_mfma_f32_16x16x32_bf16 v[10:13], v[126:129], v[226:229], v[10:13]
	s_setprio 0
	s_setprio 1
	v_mfma_f32_16x16x32_bf16 v[54:57], v[138:141], v[162:165], 0
	v_mfma_f32_16x16x32_bf16 v[50:53], v[154:157], v[162:165], 0
	v_mfma_f32_16x16x32_bf16 v[38:41], v[138:141], v[166:169], 0
	v_mfma_f32_16x16x32_bf16 v[34:37], v[154:157], v[166:169], 0
	v_mfma_f32_16x16x32_bf16 v[22:25], v[138:141], v[178:181], 0
	v_mfma_f32_16x16x32_bf16 v[18:21], v[154:157], v[178:181], 0
	v_mfma_f32_16x16x32_bf16 v[6:9], v[138:141], v[182:185], 0
	v_mfma_f32_16x16x32_bf16 v[2:5], v[154:157], v[182:185], 0
	v_mfma_f32_16x16x32_bf16 v[54:57], v[150:153], v[170:173], v[54:57]
	v_mfma_f32_16x16x32_bf16 v[50:53], v[158:161], v[170:173], v[50:53]
	v_mfma_f32_16x16x32_bf16 v[38:41], v[150:153], v[174:177], v[38:41]
	v_mfma_f32_16x16x32_bf16 v[34:37], v[158:161], v[174:177], v[34:37]
	v_mfma_f32_16x16x32_bf16 v[22:25], v[150:153], v[204:207], v[22:25]
	v_mfma_f32_16x16x32_bf16 v[18:21], v[158:161], v[204:207], v[18:21]
	v_mfma_f32_16x16x32_bf16 v[6:9], v[150:153], v[226:229], v[6:9]
	v_mfma_f32_16x16x32_bf16 v[2:5], v[158:161], v[226:229], v[2:5]
	s_setprio 0
	s_barrier
	s_add_i32 s58, 0, 0x18000
	s_add_i32 s59, 0, 0x1c000
	v_add_u32_e32 v90, s58, v209
	v_add_u32_e32 v102, s58, v210
	v_add_u32_e32 v138, s59, v209
	v_add_u32_e32 v150, s59, v210
	ds_read_b128 v[90:93], v90
	ds_read_b128 v[102:105], v102
	ds_read_b128 v[114:117], v221
	ds_read_b128 v[126:129], v222
	ds_read_b128 v[138:141], v138
	ds_read_b128 v[150:153], v150
	ds_read_b128 v[154:157], v223
	ds_read_b128 v[158:161], v224
	s_add_u32 s28, s28, 0x40000
	s_addc_u32 s29, s29, 0
	s_mov_b32 m0, s43
	v_lshl_add_u64 v[238:239], s[28:29], 0, v[186:187]
	ds_read_b128 v[162:165], v219 offset:32768
	ds_read_b128 v[166:169], v219 offset:34816
	ds_read_b128 v[170:173], v220 offset:32768
	ds_read_b128 v[174:177], v220 offset:34816
	ds_read_b128 v[178:181], v219 offset:36864
	ds_read_b128 v[182:185], v219 offset:38912
	ds_read_b128 v[204:207], v220 offset:36864
	ds_read_b128 v[226:229], v220 offset:38912
	global_load_lds_dwordx4 v[238:239], off
	v_lshl_add_u64 v[238:239], s[28:29], 0, v[190:191]
	s_mov_b32 m0, s44
	s_nop 0
	global_load_lds_dwordx4 v[238:239], off
	s_waitcnt vmcnt(8)
	s_waitcnt lgkmcnt(0)
	s_barrier
	s_setprio 1
	s_waitcnt lgkmcnt(0)
	v_mfma_f32_16x16x32_bf16 v[146:149], v[90:93], v[162:165], v[146:149]
	v_mfma_f32_16x16x32_bf16 v[142:145], v[114:117], v[162:165], v[142:145]
	v_mfma_f32_16x16x32_bf16 v[122:125], v[90:93], v[166:169], v[122:125]
	v_mfma_f32_16x16x32_bf16 v[118:121], v[114:117], v[166:169], v[118:121]
	v_mfma_f32_16x16x32_bf16 v[98:101], v[90:93], v[178:181], v[98:101]
	v_mfma_f32_16x16x32_bf16 v[94:97], v[114:117], v[178:181], v[94:97]
	v_mfma_f32_16x16x32_bf16 v[78:81], v[90:93], v[182:185], v[78:81]
	v_mfma_f32_16x16x32_bf16 v[74:77], v[114:117], v[182:185], v[74:77]
	v_mfma_f32_16x16x32_bf16 v[146:149], v[102:105], v[170:173], v[146:149]
	v_mfma_f32_16x16x32_bf16 v[142:145], v[126:129], v[170:173], v[142:145]
	v_mfma_f32_16x16x32_bf16 v[122:125], v[102:105], v[174:177], v[122:125]
	v_mfma_f32_16x16x32_bf16 v[118:121], v[126:129], v[174:177], v[118:121]
	v_mfma_f32_16x16x32_bf16 v[98:101], v[102:105], v[204:207], v[98:101]
	v_mfma_f32_16x16x32_bf16 v[94:97], v[126:129], v[204:207], v[94:97]
	v_mfma_f32_16x16x32_bf16 v[78:81], v[102:105], v[226:229], v[78:81]
	v_mfma_f32_16x16x32_bf16 v[74:77], v[126:129], v[226:229], v[74:77]
	s_setprio 0
	s_setprio 1
	v_mfma_f32_16x16x32_bf16 v[134:137], v[138:141], v[162:165], v[134:137]
	v_mfma_f32_16x16x32_bf16 v[130:133], v[154:157], v[162:165], v[130:133]
	v_mfma_f32_16x16x32_bf16 v[110:113], v[138:141], v[166:169], v[110:113]
	v_mfma_f32_16x16x32_bf16 v[106:109], v[154:157], v[166:169], v[106:109]
	v_mfma_f32_16x16x32_bf16 v[86:89], v[138:141], v[178:181], v[86:89]
	v_mfma_f32_16x16x32_bf16 v[82:85], v[154:157], v[178:181], v[82:85]
	v_mfma_f32_16x16x32_bf16 v[70:73], v[138:141], v[182:185], v[70:73]
	v_mfma_f32_16x16x32_bf16 v[66:69], v[154:157], v[182:185], v[66:69]
	v_mfma_f32_16x16x32_bf16 v[134:137], v[150:153], v[170:173], v[134:137]
	v_mfma_f32_16x16x32_bf16 v[130:133], v[158:161], v[170:173], v[130:133]
	v_mfma_f32_16x16x32_bf16 v[110:113], v[150:153], v[174:177], v[110:113]
	v_mfma_f32_16x16x32_bf16 v[106:109], v[158:161], v[174:177], v[106:109]
	v_mfma_f32_16x16x32_bf16 v[86:89], v[150:153], v[204:207], v[86:89]
	v_mfma_f32_16x16x32_bf16 v[82:85], v[158:161], v[204:207], v[82:85]
	v_mfma_f32_16x16x32_bf16 v[70:73], v[150:153], v[226:229], v[70:73]
	v_mfma_f32_16x16x32_bf16 v[66:69], v[158:161], v[226:229], v[66:69]
	s_setprio 0
	s_barrier
	s_add_i32 s28, s58, s40
	v_lshl_add_u64 v[230:231], v[230:231], 0, s[8:9]
	s_mov_b32 m0, s28
	ds_read_b128 v[162:165], v219 offset:49152
	ds_read_b128 v[166:169], v219 offset:51200
	ds_read_b128 v[170:173], v220 offset:49152
	ds_read_b128 v[174:177], v220 offset:51200
	ds_read_b128 v[178:181], v219 offset:53248
	ds_read_b128 v[182:185], v219 offset:55296
	ds_read_b128 v[204:207], v220 offset:53248
	ds_read_b128 v[226:229], v220 offset:55296
	global_load_lds_dwordx4 v[230:231], off
	s_add_i32 m0, s28, 0x2000
	s_add_u32 s26, s26, 0x40080
	v_lshl_add_u64 v[230:231], v[232:233], 0, s[8:9]
	s_addc_u32 s27, s27, 0
	s_add_i32 s28, s59, s40
	global_load_lds_dwordx4 v[230:231], off
	v_lshl_add_u64 v[230:231], s[26:27], 0, v[188:189]
	s_mov_b32 m0, s28
	s_nop 0
	global_load_lds_dwordx4 v[230:231], off
	v_lshl_add_u64 v[230:231], s[26:27], 0, v[192:193]
	s_add_i32 m0, s28, 0x2000
	s_nop 0
	global_load_lds_dwordx4 v[230:231], off
	v_lshl_add_u64 v[230:231], v[234:235], 0, s[8:9]
	s_mov_b32 m0, s48
	s_nop 0
	global_load_lds_dwordx4 v[230:231], off
	v_lshl_add_u64 v[230:231], v[236:237], 0, s[8:9]
	s_mov_b32 m0, s49
	s_nop 0
	global_load_lds_dwordx4 v[230:231], off
	s_waitcnt vmcnt(8)
	s_waitcnt lgkmcnt(0)
	s_barrier
	s_setprio 1
	s_waitcnt lgkmcnt(0)
	v_mfma_f32_16x16x32_bf16 v[62:65], v[90:93], v[162:165], v[62:65]
	v_mfma_f32_16x16x32_bf16 v[58:61], v[114:117], v[162:165], v[58:61]
	v_mfma_f32_16x16x32_bf16 v[46:49], v[90:93], v[166:169], v[46:49]
	v_mfma_f32_16x16x32_bf16 v[42:45], v[114:117], v[166:169], v[42:45]
	v_mfma_f32_16x16x32_bf16 v[30:33], v[90:93], v[178:181], v[30:33]
	v_mfma_f32_16x16x32_bf16 v[26:29], v[114:117], v[178:181], v[26:29]
	v_mfma_f32_16x16x32_bf16 v[14:17], v[90:93], v[182:185], v[14:17]
	v_mfma_f32_16x16x32_bf16 v[10:13], v[114:117], v[182:185], v[10:13]
	v_mfma_f32_16x16x32_bf16 v[62:65], v[102:105], v[170:173], v[62:65]
	v_mfma_f32_16x16x32_bf16 v[58:61], v[126:129], v[170:173], v[58:61]
	v_mfma_f32_16x16x32_bf16 v[46:49], v[102:105], v[174:177], v[46:49]
	v_mfma_f32_16x16x32_bf16 v[42:45], v[126:129], v[174:177], v[42:45]
	v_mfma_f32_16x16x32_bf16 v[30:33], v[102:105], v[204:207], v[30:33]
	v_mfma_f32_16x16x32_bf16 v[26:29], v[126:129], v[204:207], v[26:29]
	v_mfma_f32_16x16x32_bf16 v[14:17], v[102:105], v[226:229], v[14:17]
	v_mfma_f32_16x16x32_bf16 v[10:13], v[126:129], v[226:229], v[10:13]
	s_setprio 0
	s_setprio 1
	v_mfma_f32_16x16x32_bf16 v[54:57], v[138:141], v[162:165], v[54:57]
	v_mfma_f32_16x16x32_bf16 v[50:53], v[154:157], v[162:165], v[50:53]
	v_mfma_f32_16x16x32_bf16 v[38:41], v[138:141], v[166:169], v[38:41]
	v_mfma_f32_16x16x32_bf16 v[34:37], v[154:157], v[166:169], v[34:37]
	v_mfma_f32_16x16x32_bf16 v[22:25], v[138:141], v[178:181], v[22:25]
	v_mfma_f32_16x16x32_bf16 v[18:21], v[154:157], v[178:181], v[18:21]
	v_mfma_f32_16x16x32_bf16 v[6:9], v[138:141], v[182:185], v[6:9]
	v_mfma_f32_16x16x32_bf16 v[2:5], v[154:157], v[182:185], v[2:5]
	v_mfma_f32_16x16x32_bf16 v[54:57], v[150:153], v[170:173], v[54:57]
	v_mfma_f32_16x16x32_bf16 v[50:53], v[158:161], v[170:173], v[50:53]
	v_mfma_f32_16x16x32_bf16 v[38:41], v[150:153], v[174:177], v[38:41]
	v_mfma_f32_16x16x32_bf16 v[34:37], v[158:161], v[174:177], v[34:37]
	v_mfma_f32_16x16x32_bf16 v[22:25], v[150:153], v[204:207], v[22:25]
	v_mfma_f32_16x16x32_bf16 v[18:21], v[158:161], v[204:207], v[18:21]
	v_mfma_f32_16x16x32_bf16 v[6:9], v[150:153], v[226:229], v[6:9]
	v_mfma_f32_16x16x32_bf16 v[2:5], v[158:161], v[226:229], v[2:5]
	s_setprio 0
	s_barrier
	s_add_i32 s57, s57, 2
	s_add_u32 s24, s24, 0x100
	s_addc_u32 s25, s25, 0
	s_add_u32 s55, s55, 0x100
	s_addc_u32 s56, s56, 0
	s_cmp_gt_u32 s57, 13
	s_cbranch_scc0 .LBB0_1629
.Lpx_4:
	s_and_b64 vcc, exec, s[10:11]
	s_cbranch_vccz .LBB0_1632
	s_barrier
.LBB0_1632:
	s_lshl_b32 s15, s20, 8
	v_mov_b32_e32 v206, v1
	v_mov_b32_e32 v205, v208
	s_or_b32 s20, s15, s47
	s_lshl_b32 s13, s22, 8
	v_lshl_add_u32 v207, v205, 4, v206
	s_ashr_i32 s21, s20, 31
	s_add_i32 s13, s13, s46
	v_ashrrev_i32_e32 v227, 2, v207
	v_lshlrev_b32_e32 v90, 3, v206
	s_lshl_b64 s[22:23], s[20:21], 1
	v_and_b32_e32 v91, 24, v90
	v_add_u32_e32 v90, s13, v227
	s_add_u32 s24, s80, s22
	s_addc_u32 s25, s81, s23
	v_lshlrev_b32_e32 v194, 1, v91
	v_ashrrev_i32_e32 v91, 31, v90
	v_lshl_add_u64 v[92:93], s[24:25], 0, v[194:195]
	v_lshlrev_b64 v[102:103], 11, v[90:91]
	v_lshl_add_u64 v[102:103], v[92:93], 0, v[102:103]
	global_load_dwordx4 v[228:231], v[102:103], off
	global_load_dwordx4 v[232:235], v[102:103], off offset:256
	v_add_u32_e32 v102, 16, v90
	v_ashrrev_i32_e32 v103, 31, v102
	v_lshlrev_b64 v[102:103], 11, v[102:103]
	v_lshl_add_u64 v[102:103], v[92:93], 0, v[102:103]
	global_load_dwordx4 v[182:185], v[102:103], off
	global_load_dwordx4 v[178:181], v[102:103], off offset:256
	v_add_u32_e32 v102, 32, v90
	v_ashrrev_i32_e32 v103, 31, v102
	v_lshlrev_b64 v[102:103], 11, v[102:103]
	v_lshl_add_u64 v[102:103], v[92:93], 0, v[102:103]
	global_load_dwordx4 v[174:177], v[102:103], off
	global_load_dwordx4 v[170:173], v[102:103], off offset:256
	v_add_u32_e32 v102, 48, v90
	v_ashrrev_i32_e32 v103, 31, v102
	v_lshlrev_b64 v[102:103], 11, v[102:103]
	v_lshl_add_u64 v[102:103], v[92:93], 0, v[102:103]
	global_load_dwordx4 v[166:169], v[102:103], off
	global_load_dwordx4 v[162:165], v[102:103], off offset:256
	v_add_u32_e32 v102, 0x80, v90
	v_ashrrev_i32_e32 v103, 31, v102
	v_lshlrev_b64 v[102:103], 11, v[102:103]
	v_lshl_add_u64 v[102:103], v[92:93], 0, v[102:103]
	global_load_dwordx4 v[158:161], v[102:103], off
	global_load_dwordx4 v[154:157], v[102:103], off offset:256
	v_add_u32_e32 v102, 0x90, v90
	v_ashrrev_i32_e32 v103, 31, v102
	v_lshlrev_b64 v[102:103], 11, v[102:103]
	v_lshl_add_u64 v[102:103], v[92:93], 0, v[102:103]
	global_load_dwordx4 v[150:153], v[102:103], off
	global_load_dwordx4 v[138:141], v[102:103], off offset:256
	v_add_u32_e32 v102, 0xa0, v90
	v_add_u32_e32 v90, 0xb0, v90
	v_ashrrev_i32_e32 v103, 31, v102
	v_ashrrev_i32_e32 v91, 31, v90
	v_lshlrev_b64 v[102:103], 11, v[102:103]
	v_lshlrev_b64 v[90:91], 11, v[90:91]
	v_lshl_add_u64 v[102:103], v[92:93], 0, v[102:103]
	v_lshl_add_u64 v[90:91], v[92:93], 0, v[90:91]
	global_load_dwordx4 v[126:129], v[102:103], off
	global_load_dwordx4 v[114:117], v[102:103], off offset:256
	s_nop 0
	global_load_dwordx4 v[102:105], v[90:91], off
	s_nop 0
	global_load_dwordx4 v[90:93], v[90:91], off offset:256
	v_lshrrev_b32_e32 v225, 1, v206
	v_lshrrev_b32_e32 v207, 3, v207
	v_cmp_eq_u32_e32 vcc, 0, v205
	v_bitop3_b32 v205, v225, v205, 3 bitop3:0x6c
	v_xor_b32_e32 v207, v207, v206
	v_lshlrev_b32_e32 v226, 6, v206
	v_lshl_add_u32 v205, v205, 4, s52
	v_lshlrev_b32_e32 v207, 4, v207
	v_add_u32_e32 v225, v205, v226
	v_and_b32_e32 v205, 48, v207
	v_lshlrev_b32_e32 v236, 6, v227
	v_add_u32_e32 v205, s52, v205
	v_add_u32_e32 v226, v205, v236
	v_add_u32_e32 v204, s13, v206
	v_ashrrev_i32_e32 v205, 31, v204
	v_sub_u32_e32 v206, v227, v206
	v_ashrrev_i32_e32 v207, 31, v206
	v_lshlrev_b64 v[206:207], 11, v[206:207]
	s_waitcnt vmcnt(0)
	ds_write_b128 v226, v[228:231] offset:49152
	ds_read_b128 v[228:231], v225 offset:49152
	s_waitcnt lgkmcnt(0)
	v_lshlrev_b32_e32 v236, 16, v228
	v_and_b32_e32 v237, 0xffff0000, v228
	v_pk_add_f32 v[236:237], v[146:147], v[236:237]
	v_lshlrev_b64 v[146:147], 11, v[204:205]
	v_lshlrev_b32_e32 v228, 16, v229
	v_and_b32_e32 v229, 0xffff0000, v229
	v_lshlrev_b32_e32 v238, 16, v230
	v_and_b32_e32 v239, 0xffff0000, v230
	v_lshlrev_b32_e32 v230, 16, v231
	v_and_b32_e32 v231, 0xffff0000, v231
	v_lshl_add_u64 v[146:147], s[80:81], 0, v[146:147]
	v_pk_add_f32 v[228:229], v[148:149], v[228:229]
	v_pk_add_f32 v[230:231], v[144:145], v[230:231]
	v_pk_add_f32 v[238:239], v[142:143], v[238:239]
	v_cvt_pk_bf16_f32 v142, v236, v237
	v_cvt_pk_bf16_f32 v143, v228, v229
	v_lshl_add_u64 v[146:147], v[146:147], 0, s[22:23]
	v_cvt_pk_bf16_f32 v144, v238, v239
	v_cvt_pk_bf16_f32 v145, v230, v231
	ds_write_b128 v225, v[142:145] offset:49152
	ds_read_b128 v[142:145], v226 offset:49152
	v_lshl_add_u64 v[146:147], v[146:147], 0, v[206:207]
	ds_write_b128 v226, v[232:235] offset:57344
	v_lshl_add_u64 v[240:241], v[146:147], 0, v[194:195]
	ds_read_b128 v[146:149], v225 offset:57344
	s_waitcnt lgkmcnt(2)
	global_store_dwordx4 v[240:241], v[142:145], off
	s_nop 1
	v_pk_mul_f32 v[144:145], v[230:231], v[230:231]
	s_waitcnt lgkmcnt(0)
	v_lshlrev_b32_e32 v230, 16, v148
	v_pk_fma_f32 v[144:145], v[228:229], v[228:229], v[144:145]
	v_lshlrev_b32_e32 v228, 16, v146
	v_and_b32_e32 v229, 0xffff0000, v146
	v_lshlrev_b32_e32 v146, 16, v147
	v_and_b32_e32 v147, 0xffff0000, v147
	v_and_b32_e32 v231, 0xffff0000, v148
	v_lshlrev_b32_e32 v148, 16, v149
	v_and_b32_e32 v149, 0xffff0000, v149
	v_pk_add_f32 v[136:137], v[136:137], v[146:147]
	v_pk_add_f32 v[134:135], v[134:135], v[228:229]
	v_pk_add_f32 v[146:147], v[132:133], v[148:149]
	v_pk_add_f32 v[148:149], v[130:131], v[230:231]
	v_cvt_pk_bf16_f32 v130, v134, v135
	v_cvt_pk_bf16_f32 v131, v136, v137
	v_pk_mul_f32 v[142:143], v[238:239], v[238:239]
	v_cvt_pk_bf16_f32 v132, v148, v149
	v_cvt_pk_bf16_f32 v133, v146, v147
	ds_write_b128 v225, v[130:133] offset:57344
	ds_read_b128 v[130:133], v226 offset:57344
	v_pk_fma_f32 v[142:143], v[236:237], v[236:237], v[142:143]
	s_waitcnt lgkmcnt(0)
	global_store_dwordx4 v[240:241], v[130:133], off offset:256
	s_nop 1
	v_pk_mul_f32 v[130:131], v[148:149], v[148:149]
	v_pk_mul_f32 v[132:133], v[146:147], v[146:147]
	v_pk_fma_f32 v[130:131], v[134:135], v[134:135], v[130:131]
	v_pk_fma_f32 v[132:133], v[136:137], v[136:137], v[132:133]
	v_add_f32_e32 v142, v142, v143
	v_add_f32_e32 v143, v144, v145
	v_add_f32_e32 v142, v142, v143
	v_add_f32_e32 v130, v130, v131
	v_add_f32_e32 v131, v132, v133
	v_add_f32_e32 v142, 0, v142
	v_add_f32_e32 v130, v130, v131
	v_add_f32_e32 v130, v142, v130
	v_mov_b32_e32 v131, v130
	s_nop 1
	v_permlane32_swap_b32_e32 v130, v131
	v_add_f32_e32 v130, v130, v131
	v_mov_b32_e32 v131, v130
	s_nop 1
	v_permlane16_swap_b32_e32 v130, v131
	s_and_saveexec_b64 s[22:23], vcc
	s_cbranch_execz .LBB0_1634
	v_lshl_add_u64 v[132:133], v[204:205], 2, s[4:5]
	v_add_f32_e32 v130, v130, v131
	global_atomic_add_f32 v[132:133], v130, off

.LBB0_1720:
	s_ashr_i32 s13, s12, 31
	s_lshl_b64 s[14:15], s[12:13], 19
	s_add_u32 s14, s80, s14
	s_addc_u32 s15, s81, s15
	s_and_b64 s[16:17], s[6:7], exec
	s_cselect_b32 s13, s15, s23
	s_cselect_b32 s58, s14, s22
	s_ashr_i32 s5, s4, 31
	s_lshl_b64 s[16:17], s[4:5], 19
	s_add_u32 s16, s28, s16
	s_addc_u32 s17, s29, s17
	s_and_b64 s[26:27], s[6:7], exec
	s_cselect_b32 s5, s17, s25
	s_cselect_b32 s59, s16, s24
	s_lshl_b32 s60, s57, 10
	s_lshl_b32 s26, s12, 8
	s_add_i32 s60, s60, 0
	s_ashr_i32 s27, s26, 31
	s_add_i32 s60, s60, 0x20800
	s_add_u32 s22, s22, 0x40080
	s_addc_u32 s23, s23, 0
	s_add_u32 s61, s24, 0x100
	s_mov_b32 s100, 1
	v_lshl_add_u64 v[148:149], s[26:27], 2, v[138:139]
	s_addc_u32 s62, s25, 0
	s_mov_b32 s63, -2
	s_branch .LBB0_1722
.LBB0_1721:
	s_cmp_lg_u32 s100, 0
	s_cbranch_scc1 .Lpeel_5
	v_add_u32_e32 v150, s49, v155
	v_add_u32_e32 v160, s49, v156
	v_add_u32_e32 v164, s50, v155
	v_add_u32_e32 v168, s50, v156
	v_add_u32_e32 v172, s51, v155
	v_add_u32_e32 v176, s51, v156
	v_add_u32_e32 v180, s52, v155
	v_add_u32_e32 v184, s52, v156
	ds_read_b128 v[150:153], v150
	ds_read_b128 v[160:163], v160
	ds_read_b128 v[164:167], v164
	ds_read_b128 v[168:171], v168
	ds_read_b128 v[172:175], v172
	ds_read_b128 v[176:179], v176
	ds_read_b128 v[180:183], v180
	ds_read_b128 v[184:187], v184
	s_add_u32 s26, s22, 0xfffc0080
	s_addc_u32 s27, s23, -1
	s_and_b64 s[24:25], s[24:25], exec
	s_cselect_b32 s27, s13, s27
	s_cselect_b32 s26, s58, s26
	s_cselect_b32 s25, s5, s62
	s_cselect_b32 s24, s59, s61
	v_lshl_add_u64 v[220:221], s[22:23], 0, v[140:141]
	s_add_i32 m0, s38, 0xc000
	ds_read_b128 v[188:191], v157
	s_waitcnt lgkmcnt(0)
	ds_read_b128 v[192:195], v157 offset:2048
	ds_read_b128 v[196:199], v158
	ds_read_b128 v[200:203], v158 offset:2048
	ds_read_b128 v[204:207], v157 offset:4096
	ds_read_b128 v[208:211], v157 offset:6144
	ds_read_b128 v[212:215], v158 offset:4096
	ds_read_b128 v[216:219], v158 offset:6144
	global_load_lds_dwordx4 v[220:221], off
	v_lshl_add_u64 v[220:221], s[22:23], 0, v[142:143]
	s_add_i32 m0, s38, 0xe000
	s_nop 0
	global_load_lds_dwordx4 v[220:221], off
	s_waitcnt vmcnt(8)
	s_waitcnt lgkmcnt(0)
	s_barrier
	s_setprio 1
	v_mfma_f32_16x16x32_bf16 v[126:129], v[150:153], v[188:191], v[126:129]
	v_mfma_f32_16x16x32_bf16 v[118:121], v[164:167], v[188:191], v[118:121]
	s_waitcnt lgkmcnt(0)
	v_mfma_f32_16x16x32_bf16 v[110:113], v[150:153], v[192:195], v[110:113]
	v_mfma_f32_16x16x32_bf16 v[102:105], v[164:167], v[192:195], v[102:105]
	v_mfma_f32_16x16x32_bf16 v[94:97], v[150:153], v[204:207], v[94:97]
	v_mfma_f32_16x16x32_bf16 v[86:89], v[164:167], v[204:207], v[86:89]
	v_mfma_f32_16x16x32_bf16 v[78:81], v[150:153], v[208:211], v[78:81]
	v_mfma_f32_16x16x32_bf16 v[70:73], v[164:167], v[208:211], v[70:73]
	v_mfma_f32_16x16x32_bf16 v[126:129], v[160:163], v[196:199], v[126:129]
	v_mfma_f32_16x16x32_bf16 v[118:121], v[168:171], v[196:199], v[118:121]
	v_mfma_f32_16x16x32_bf16 v[110:113], v[160:163], v[200:203], v[110:113]
	v_mfma_f32_16x16x32_bf16 v[102:105], v[168:171], v[200:203], v[102:105]
	v_mfma_f32_16x16x32_bf16 v[94:97], v[160:163], v[212:215], v[94:97]
	v_mfma_f32_16x16x32_bf16 v[86:89], v[168:171], v[212:215], v[86:89]
	v_mfma_f32_16x16x32_bf16 v[78:81], v[160:163], v[216:219], v[78:81]
	v_mfma_f32_16x16x32_bf16 v[70:73], v[168:171], v[216:219], v[70:73]
	s_setprio 0
	s_setprio 1
	v_mfma_f32_16x16x32_bf16 v[122:125], v[172:175], v[188:191], v[122:125]
	v_mfma_f32_16x16x32_bf16 v[114:117], v[180:183], v[188:191], v[114:117]
	v_mfma_f32_16x16x32_bf16 v[106:109], v[172:175], v[192:195], v[106:109]
	v_mfma_f32_16x16x32_bf16 v[98:101], v[180:183], v[192:195], v[98:101]
	v_mfma_f32_16x16x32_bf16 v[90:93], v[172:175], v[204:207], v[90:93]
	v_mfma_f32_16x16x32_bf16 v[82:85], v[180:183], v[204:207], v[82:85]
	v_mfma_f32_16x16x32_bf16 v[74:77], v[172:175], v[208:211], v[74:77]
	v_mfma_f32_16x16x32_bf16 v[66:69], v[180:183], v[208:211], v[66:69]
	v_mfma_f32_16x16x32_bf16 v[122:125], v[176:179], v[196:199], v[122:125]
	v_mfma_f32_16x16x32_bf16 v[114:117], v[184:187], v[196:199], v[114:117]
	v_mfma_f32_16x16x32_bf16 v[106:109], v[176:179], v[200:203], v[106:109]
	v_mfma_f32_16x16x32_bf16 v[98:101], v[184:187], v[200:203], v[98:101]
	v_mfma_f32_16x16x32_bf16 v[90:93], v[176:179], v[212:215], v[90:93]
	v_mfma_f32_16x16x32_bf16 v[82:85], v[184:187], v[212:215], v[82:85]
	v_mfma_f32_16x16x32_bf16 v[74:77], v[176:179], v[216:219], v[74:77]
	v_mfma_f32_16x16x32_bf16 v[66:69], v[184:187], v[216:219], v[66:69]
	s_setprio 0
	s_barrier
	s_add_i32 s64, s49, s21
	v_lshl_add_u64 v[220:221], s[24:25], 0, v[132:133]
	s_mov_b32 m0, s64
	ds_read_b128 v[188:191], v157 offset:16384
	ds_read_b128 v[192:195], v157 offset:18432
	ds_read_b128 v[196:199], v158 offset:16384
	ds_read_b128 v[200:203], v158 offset:18432
	ds_read_b128 v[204:207], v157 offset:20480
	ds_read_b128 v[208:211], v157 offset:22528
	ds_read_b128 v[212:215], v158 offset:20480
	ds_read_b128 v[216:219], v158 offset:22528
	global_load_lds_dwordx4 v[220:221], off
	s_add_i32 m0, s64, 0x2000
	s_add_u32 s64, s24, 0x40000
	v_lshl_add_u64 v[222:223], s[24:25], 0, v[136:137]
	s_addc_u32 s65, s25, 0
	s_add_i32 s66, s51, s21
	global_load_lds_dwordx4 v[222:223], off
	v_lshl_add_u64 v[224:225], s[64:65], 0, v[132:133]
	s_mov_b32 m0, s66
	v_lshl_add_u64 v[226:227], s[26:27], 0, v[134:135]
	global_load_lds_dwordx4 v[224:225], off
	v_lshl_add_u64 v[224:225], s[64:65], 0, v[136:137]
	s_add_i32 m0, s66, 0x2000
	s_nop 0
	global_load_lds_dwordx4 v[224:225], off
	v_lshl_add_u64 v[224:225], s[26:27], 0, v[130:131]
	s_mov_b32 m0, s38
	s_nop 0
	global_load_lds_dwordx4 v[224:225], off
	s_mov_b32 m0, s39
	s_nop 0
	global_load_lds_dwordx4 v[226:227], off
	s_waitcnt vmcnt(8)
	s_waitcnt lgkmcnt(0)
	s_barrier
	s_setprio 1
	s_waitcnt lgkmcnt(0)
	v_mfma_f32_16x16x32_bf16 v[62:65], v[150:153], v[188:191], v[62:65]
	v_mfma_f32_16x16x32_bf16 v[54:57], v[164:167], v[188:191], v[54:57]
	v_mfma_f32_16x16x32_bf16 v[46:49], v[150:153], v[192:195], v[46:49]
	v_mfma_f32_16x16x32_bf16 v[38:41], v[164:167], v[192:195], v[38:41]
	v_mfma_f32_16x16x32_bf16 v[30:33], v[150:153], v[204:207], v[30:33]
	v_mfma_f32_16x16x32_bf16 v[22:25], v[164:167], v[204:207], v[22:25]
	v_mfma_f32_16x16x32_bf16 v[14:17], v[150:153], v[208:211], v[14:17]
	v_mfma_f32_16x16x32_bf16 v[6:9], v[164:167], v[208:211], v[6:9]
	v_mfma_f32_16x16x32_bf16 v[62:65], v[160:163], v[196:199], v[62:65]
	v_mfma_f32_16x16x32_bf16 v[54:57], v[168:171], v[196:199], v[54:57]
	v_mfma_f32_16x16x32_bf16 v[46:49], v[160:163], v[200:203], v[46:49]
	v_mfma_f32_16x16x32_bf16 v[38:41], v[168:171], v[200:203], v[38:41]
	v_mfma_f32_16x16x32_bf16 v[30:33], v[160:163], v[212:215], v[30:33]
	v_mfma_f32_16x16x32_bf16 v[22:25], v[168:171], v[212:215], v[22:25]
	v_mfma_f32_16x16x32_bf16 v[14:17], v[160:163], v[216:219], v[14:17]
	v_mfma_f32_16x16x32_bf16 v[6:9], v[168:171], v[216:219], v[6:9]
	s_setprio 0
	s_setprio 1
	v_mfma_f32_16x16x32_bf16 v[58:61], v[172:175], v[188:191], v[58:61]
	v_mfma_f32_16x16x32_bf16 v[50:53], v[180:183], v[188:191], v[50:53]
	v_mfma_f32_16x16x32_bf16 v[42:45], v[172:175], v[192:195], v[42:45]
	v_mfma_f32_16x16x32_bf16 v[34:37], v[180:183], v[192:195], v[34:37]
	v_mfma_f32_16x16x32_bf16 v[26:29], v[172:175], v[204:207], v[26:29]
	v_mfma_f32_16x16x32_bf16 v[18:21], v[180:183], v[204:207], v[18:21]
	v_mfma_f32_16x16x32_bf16 v[10:13], v[172:175], v[208:211], v[10:13]
	v_mfma_f32_16x16x32_bf16 v[2:5], v[180:183], v[208:211], v[2:5]
	v_mfma_f32_16x16x32_bf16 v[58:61], v[176:179], v[196:199], v[58:61]
	v_mfma_f32_16x16x32_bf16 v[50:53], v[184:187], v[196:199], v[50:53]
	v_mfma_f32_16x16x32_bf16 v[42:45], v[176:179], v[200:203], v[42:45]
	v_mfma_f32_16x16x32_bf16 v[34:37], v[184:187], v[200:203], v[34:37]
	v_mfma_f32_16x16x32_bf16 v[26:29], v[176:179], v[212:215], v[26:29]
	v_mfma_f32_16x16x32_bf16 v[18:21], v[184:187], v[212:215], v[18:21]
	v_mfma_f32_16x16x32_bf16 v[10:13], v[176:179], v[216:219], v[10:13]
	v_mfma_f32_16x16x32_bf16 v[2:5], v[184:187], v[216:219], v[2:5]
	s_setprio 0
	s_barrier
	s_add_i32 s64, 0, 0x18000
	s_add_i32 s65, 0, 0x1c000
	v_add_u32_e32 v150, s64, v155
	v_add_u32_e32 v160, s64, v156
	v_add_u32_e32 v164, s53, v155
	v_add_u32_e32 v168, s53, v156
	v_add_u32_e32 v172, s65, v155
	v_add_u32_e32 v176, s65, v156
	v_add_u32_e32 v180, s54, v155
	v_add_u32_e32 v184, s54, v156
	ds_read_b128 v[150:153], v150
	ds_read_b128 v[160:163], v160
	ds_read_b128 v[164:167], v164
	ds_read_b128 v[168:171], v168
	ds_read_b128 v[172:175], v172
	ds_read_b128 v[176:179], v176
	ds_read_b128 v[180:183], v180
	ds_read_b128 v[184:187], v184
	s_add_u32 s26, s26, 0x40000
	s_addc_u32 s27, s27, 0
	s_mov_b32 m0, s40
	v_lshl_add_u64 v[228:229], s[26:27], 0, v[130:131]
	ds_read_b128 v[188:191], v157 offset:32768
	ds_read_b128 v[192:195], v157 offset:34816
	ds_read_b128 v[196:199], v158 offset:32768
	ds_read_b128 v[200:203], v158 offset:34816
	ds_read_b128 v[204:207], v157 offset:36864
	ds_read_b128 v[208:211], v157 offset:38912
	ds_read_b128 v[212:215], v158 offset:36864
	ds_read_b128 v[216:219], v158 offset:38912
	global_load_lds_dwordx4 v[228:229], off
	v_lshl_add_u64 v[228:229], s[26:27], 0, v[134:135]
	s_mov_b32 m0, s41
	s_nop 0
	global_load_lds_dwordx4 v[228:229], off
	s_waitcnt vmcnt(8)
	s_waitcnt lgkmcnt(0)
	s_barrier
	s_setprio 1
	s_waitcnt lgkmcnt(0)
	v_mfma_f32_16x16x32_bf16 v[126:129], v[150:153], v[188:191], v[126:129]
	v_mfma_f32_16x16x32_bf16 v[118:121], v[164:167], v[188:191], v[118:121]
	v_mfma_f32_16x16x32_bf16 v[110:113], v[150:153], v[192:195], v[110:113]
	v_mfma_f32_16x16x32_bf16 v[102:105], v[164:167], v[192:195], v[102:105]
	v_mfma_f32_16x16x32_bf16 v[94:97], v[150:153], v[204:207], v[94:97]
	v_mfma_f32_16x16x32_bf16 v[86:89], v[164:167], v[204:207], v[86:89]
	v_mfma_f32_16x16x32_bf16 v[78:81], v[150:153], v[208:211], v[78:81]
	v_mfma_f32_16x16x32_bf16 v[70:73], v[164:167], v[208:211], v[70:73]
	v_mfma_f32_16x16x32_bf16 v[126:129], v[160:163], v[196:199], v[126:129]
	v_mfma_f32_16x16x32_bf16 v[118:121], v[168:171], v[196:199], v[118:121]
	v_mfma_f32_16x16x32_bf16 v[110:113], v[160:163], v[200:203], v[110:113]
	v_mfma_f32_16x16x32_bf16 v[102:105], v[168:171], v[200:203], v[102:105]
	v_mfma_f32_16x16x32_bf16 v[94:97], v[160:163], v[212:215], v[94:97]
	v_mfma_f32_16x16x32_bf16 v[86:89], v[168:171], v[212:215], v[86:89]
	v_mfma_f32_16x16x32_bf16 v[78:81], v[160:163], v[216:219], v[78:81]
	v_mfma_f32_16x16x32_bf16 v[70:73], v[168:171], v[216:219], v[70:73]
	s_setprio 0
	s_setprio 1
	v_mfma_f32_16x16x32_bf16 v[122:125], v[172:175], v[188:191], v[122:125]
	v_mfma_f32_16x16x32_bf16 v[114:117], v[180:183], v[188:191], v[114:117]
	v_mfma_f32_16x16x32_bf16 v[106:109], v[172:175], v[192:195], v[106:109]
	v_mfma_f32_16x16x32_bf16 v[98:101], v[180:183], v[192:195], v[98:101]
	v_mfma_f32_16x16x32_bf16 v[90:93], v[172:175], v[204:207], v[90:93]
	v_mfma_f32_16x16x32_bf16 v[82:85], v[180:183], v[204:207], v[82:85]
	v_mfma_f32_16x16x32_bf16 v[74:77], v[172:175], v[208:211], v[74:77]
	v_mfma_f32_16x16x32_bf16 v[66:69], v[180:183], v[208:211], v[66:69]
	v_mfma_f32_16x16x32_bf16 v[122:125], v[176:179], v[196:199], v[122:125]
	v_mfma_f32_16x16x32_bf16 v[114:117], v[184:187], v[196:199], v[114:117]
	v_mfma_f32_16x16x32_bf16 v[106:109], v[176:179], v[200:203], v[106:109]
	v_mfma_f32_16x16x32_bf16 v[98:101], v[184:187], v[200:203], v[98:101]
	v_mfma_f32_16x16x32_bf16 v[90:93], v[176:179], v[212:215], v[90:93]
	v_mfma_f32_16x16x32_bf16 v[82:85], v[184:187], v[212:215], v[82:85]
	v_mfma_f32_16x16x32_bf16 v[74:77], v[176:179], v[216:219], v[74:77]
	v_mfma_f32_16x16x32_bf16 v[66:69], v[184:187], v[216:219], v[66:69]
	s_setprio 0
	s_barrier
	s_add_i32 s26, s64, s21
	v_lshl_add_u64 v[220:221], v[220:221], 0, s[8:9]
	s_mov_b32 m0, s26
	ds_read_b128 v[188:191], v157 offset:49152
	ds_read_b128 v[192:195], v157 offset:51200
	ds_read_b128 v[196:199], v158 offset:49152
	ds_read_b128 v[200:203], v158 offset:51200
	ds_read_b128 v[204:207], v157 offset:53248
	ds_read_b128 v[208:211], v157 offset:55296
	ds_read_b128 v[212:215], v158 offset:53248
	ds_read_b128 v[216:219], v158 offset:55296
	global_load_lds_dwordx4 v[220:221], off
	s_add_i32 m0, s26, 0x2000
	s_add_u32 s24, s24, 0x40080
	v_lshl_add_u64 v[220:221], v[222:223], 0, s[8:9]
	s_addc_u32 s25, s25, 0
	s_add_i32 s26, s65, s21
	global_load_lds_dwordx4 v[220:221], off
	v_lshl_add_u64 v[220:221], s[24:25], 0, v[132:133]
	s_mov_b32 m0, s26
	s_nop 0
	global_load_lds_dwordx4 v[220:221], off
	v_lshl_add_u64 v[220:221], s[24:25], 0, v[136:137]
	s_add_i32 m0, s26, 0x2000
	s_nop 0
	global_load_lds_dwordx4 v[220:221], off
	v_lshl_add_u64 v[220:221], v[224:225], 0, s[8:9]
	s_mov_b32 m0, s44
	s_nop 0
	global_load_lds_dwordx4 v[220:221], off
	v_lshl_add_u64 v[220:221], v[226:227], 0, s[8:9]
	s_mov_b32 m0, s45
	s_nop 0
	global_load_lds_dwordx4 v[220:221], off
	s_waitcnt vmcnt(8)
	s_waitcnt lgkmcnt(0)
	s_barrier
	s_setprio 1
	s_waitcnt lgkmcnt(0)
	v_mfma_f32_16x16x32_bf16 v[62:65], v[150:153], v[188:191], v[62:65]
	v_mfma_f32_16x16x32_bf16 v[54:57], v[164:167], v[188:191], v[54:57]
	v_mfma_f32_16x16x32_bf16 v[46:49], v[150:153], v[192:195], v[46:49]
	v_mfma_f32_16x16x32_bf16 v[38:41], v[164:167], v[192:195], v[38:41]
	v_mfma_f32_16x16x32_bf16 v[30:33], v[150:153], v[204:207], v[30:33]
	v_mfma_f32_16x16x32_bf16 v[22:25], v[164:167], v[204:207], v[22:25]
	v_mfma_f32_16x16x32_bf16 v[14:17], v[150:153], v[208:211], v[14:17]
	v_mfma_f32_16x16x32_bf16 v[6:9], v[164:167], v[208:211], v[6:9]
	v_mfma_f32_16x16x32_bf16 v[62:65], v[160:163], v[196:199], v[62:65]
	v_mfma_f32_16x16x32_bf16 v[54:57], v[168:171], v[196:199], v[54:57]
	v_mfma_f32_16x16x32_bf16 v[46:49], v[160:163], v[200:203], v[46:49]
	v_mfma_f32_16x16x32_bf16 v[38:41], v[168:171], v[200:203], v[38:41]
	v_mfma_f32_16x16x32_bf16 v[30:33], v[160:163], v[212:215], v[30:33]
	v_mfma_f32_16x16x32_bf16 v[22:25], v[168:171], v[212:215], v[22:25]
	v_mfma_f32_16x16x32_bf16 v[14:17], v[160:163], v[216:219], v[14:17]
	v_mfma_f32_16x16x32_bf16 v[6:9], v[168:171], v[216:219], v[6:9]
	s_setprio 0
	s_setprio 1
	v_mfma_f32_16x16x32_bf16 v[58:61], v[172:175], v[188:191], v[58:61]
	v_mfma_f32_16x16x32_bf16 v[50:53], v[180:183], v[188:191], v[50:53]
	v_mfma_f32_16x16x32_bf16 v[42:45], v[172:175], v[192:195], v[42:45]
	v_mfma_f32_16x16x32_bf16 v[34:37], v[180:183], v[192:195], v[34:37]
	v_mfma_f32_16x16x32_bf16 v[26:29], v[172:175], v[204:207], v[26:29]
	v_mfma_f32_16x16x32_bf16 v[18:21], v[180:183], v[204:207], v[18:21]
	v_mfma_f32_16x16x32_bf16 v[10:13], v[172:175], v[208:211], v[10:13]
	v_mfma_f32_16x16x32_bf16 v[2:5], v[180:183], v[208:211], v[2:5]
	v_mfma_f32_16x16x32_bf16 v[58:61], v[176:179], v[196:199], v[58:61]
	v_mfma_f32_16x16x32_bf16 v[50:53], v[184:187], v[196:199], v[50:53]
	v_mfma_f32_16x16x32_bf16 v[42:45], v[176:179], v[200:203], v[42:45]
	v_mfma_f32_16x16x32_bf16 v[34:37], v[184:187], v[200:203], v[34:37]
	v_mfma_f32_16x16x32_bf16 v[26:29], v[176:179], v[212:215], v[26:29]
	v_mfma_f32_16x16x32_bf16 v[18:21], v[184:187], v[212:215], v[18:21]
	v_mfma_f32_16x16x32_bf16 v[10:13], v[176:179], v[216:219], v[10:13]
	v_mfma_f32_16x16x32_bf16 v[2:5], v[184:187], v[216:219], v[2:5]
	s_setprio 0
	s_barrier
	s_add_i32 s63, s63, 2
	s_add_u32 s22, s22, 0x100
	s_addc_u32 s23, s23, 0
	s_add_u32 s61, s61, 0x100
	s_addc_u32 s62, s62, 0
	s_cmp_gt_u32 s63, 13
	s_cbranch_scc1 .LBB0_1725

.Lpeel_5:
	s_mov_b32 s100, 0
	v_add_u32_e32 v150, s49, v155
	v_add_u32_e32 v160, s49, v156
	v_add_u32_e32 v164, s50, v155
	v_add_u32_e32 v168, s50, v156
	v_add_u32_e32 v172, s51, v155
	v_add_u32_e32 v176, s51, v156
	v_add_u32_e32 v180, s52, v155
	v_add_u32_e32 v184, s52, v156
	ds_read_b128 v[150:153], v150
	ds_read_b128 v[160:163], v160
	ds_read_b128 v[164:167], v164
	ds_read_b128 v[168:171], v168
	ds_read_b128 v[172:175], v172
	ds_read_b128 v[176:179], v176
	ds_read_b128 v[180:183], v180
	ds_read_b128 v[184:187], v184
	s_add_u32 s26, s22, 0xfffc0080
	s_addc_u32 s27, s23, -1
	s_and_b64 s[24:25], s[24:25], exec
	s_cselect_b32 s27, s13, s27
	s_cselect_b32 s26, s58, s26
	s_cselect_b32 s25, s5, s62
	s_cselect_b32 s24, s59, s61
	v_lshl_add_u64 v[220:221], s[22:23], 0, v[140:141]
	s_add_i32 m0, s38, 0xc000
	ds_read_b128 v[188:191], v157
	s_waitcnt lgkmcnt(0)
	ds_read_b128 v[192:195], v157 offset:2048
	ds_read_b128 v[196:199], v158
	ds_read_b128 v[200:203], v158 offset:2048
	ds_read_b128 v[204:207], v157 offset:4096
	ds_read_b128 v[208:211], v157 offset:6144
	ds_read_b128 v[212:215], v158 offset:4096
	ds_read_b128 v[216:219], v158 offset:6144
	global_load_lds_dwordx4 v[220:221], off
	v_lshl_add_u64 v[220:221], s[22:23], 0, v[142:143]
	s_add_i32 m0, s38, 0xe000
	s_nop 0
	global_load_lds_dwordx4 v[220:221], off
	s_waitcnt vmcnt(8)
	s_waitcnt lgkmcnt(0)
	s_barrier
	s_setprio 1
	v_mfma_f32_16x16x32_bf16 v[126:129], v[150:153], v[188:191], 0
	v_mfma_f32_16x16x32_bf16 v[118:121], v[164:167], v[188:191], 0
	s_waitcnt lgkmcnt(0)
	v_mfma_f32_16x16x32_bf16 v[110:113], v[150:153], v[192:195], 0
	v_mfma_f32_16x16x32_bf16 v[102:105], v[164:167], v[192:195], 0
	v_mfma_f32_16x16x32_bf16 v[94:97], v[150:153], v[204:207], 0
	v_mfma_f32_16x16x32_bf16 v[86:89], v[164:167], v[204:207], 0
	v_mfma_f32_16x16x32_bf16 v[78:81], v[150:153], v[208:211], 0
	v_mfma_f32_16x16x32_bf16 v[70:73], v[164:167], v[208:211], 0
	v_mfma_f32_16x16x32_bf16 v[126:129], v[160:163], v[196:199], v[126:129]
	v_mfma_f32_16x16x32_bf16 v[118:121], v[168:171], v[196:199], v[118:121]
	v_mfma_f32_16x16x32_bf16 v[110:113], v[160:163], v[200:203], v[110:113]
	v_mfma_f32_16x16x32_bf16 v[102:105], v[168:171], v[200:203], v[102:105]
	v_mfma_f32_16x16x32_bf16 v[94:97], v[160:163], v[212:215], v[94:97]
	v_mfma_f32_16x16x32_bf16 v[86:89], v[168:171], v[212:215], v[86:89]
	v_mfma_f32_16x16x32_bf16 v[78:81], v[160:163], v[216:219], v[78:81]
	v_mfma_f32_16x16x32_bf16 v[70:73], v[168:171], v[216:219], v[70:73]
	s_setprio 0
	s_setprio 1
	v_mfma_f32_16x16x32_bf16 v[122:125], v[172:175], v[188:191], 0
	v_mfma_f32_16x16x32_bf16 v[114:117], v[180:183], v[188:191], 0
	v_mfma_f32_16x16x32_bf16 v[106:109], v[172:175], v[192:195], 0
	v_mfma_f32_16x16x32_bf16 v[98:101], v[180:183], v[192:195], 0
	v_mfma_f32_16x16x32_bf16 v[90:93], v[172:175], v[204:207], 0
	v_mfma_f32_16x16x32_bf16 v[82:85], v[180:183], v[204:207], 0
	v_mfma_f32_16x16x32_bf16 v[74:77], v[172:175], v[208:211], 0
	v_mfma_f32_16x16x32_bf16 v[66:69], v[180:183], v[208:211], 0
	v_mfma_f32_16x16x32_bf16 v[122:125], v[176:179], v[196:199], v[122:125]
	v_mfma_f32_16x16x32_bf16 v[114:117], v[184:187], v[196:199], v[114:117]
	v_mfma_f32_16x16x32_bf16 v[106:109], v[176:179], v[200:203], v[106:109]
	v_mfma_f32_16x16x32_bf16 v[98:101], v[184:187], v[200:203], v[98:101]
	v_mfma_f32_16x16x32_bf16 v[90:93], v[176:179], v[212:215], v[90:93]
	v_mfma_f32_16x16x32_bf16 v[82:85], v[184:187], v[212:215], v[82:85]
	v_mfma_f32_16x16x32_bf16 v[74:77], v[176:179], v[216:219], v[74:77]
	v_mfma_f32_16x16x32_bf16 v[66:69], v[184:187], v[216:219], v[66:69]
	s_setprio 0
	s_barrier
	s_add_i32 s64, s49, s21
	v_lshl_add_u64 v[220:221], s[24:25], 0, v[132:133]
	s_mov_b32 m0, s64
	ds_read_b128 v[188:191], v157 offset:16384
	ds_read_b128 v[192:195], v157 offset:18432
	ds_read_b128 v[196:199], v158 offset:16384
	ds_read_b128 v[200:203], v158 offset:18432
	ds_read_b128 v[204:207], v157 offset:20480
	ds_read_b128 v[208:211], v157 offset:22528
	ds_read_b128 v[212:215], v158 offset:20480
	ds_read_b128 v[216:219], v158 offset:22528
	global_load_lds_dwordx4 v[220:221], off
	s_add_i32 m0, s64, 0x2000
	s_add_u32 s64, s24, 0x40000
	v_lshl_add_u64 v[222:223], s[24:25], 0, v[136:137]
	s_addc_u32 s65, s25, 0
	s_add_i32 s66, s51, s21
	global_load_lds_dwordx4 v[222:223], off
	v_lshl_add_u64 v[224:225], s[64:65], 0, v[132:133]
	s_mov_b32 m0, s66
	v_lshl_add_u64 v[226:227], s[26:27], 0, v[134:135]
	global_load_lds_dwordx4 v[224:225], off
	v_lshl_add_u64 v[224:225], s[64:65], 0, v[136:137]
	s_add_i32 m0, s66, 0x2000
	s_nop 0
	global_load_lds_dwordx4 v[224:225], off
	v_lshl_add_u64 v[224:225], s[26:27], 0, v[130:131]
	s_mov_b32 m0, s38
	s_nop 0
	global_load_lds_dwordx4 v[224:225], off
	s_mov_b32 m0, s39
	s_nop 0
	global_load_lds_dwordx4 v[226:227], off
	s_waitcnt vmcnt(8)
	s_waitcnt lgkmcnt(0)
	s_barrier
	s_setprio 1
	s_waitcnt lgkmcnt(0)
	v_mfma_f32_16x16x32_bf16 v[62:65], v[150:153], v[188:191], 0
	v_mfma_f32_16x16x32_bf16 v[54:57], v[164:167], v[188:191], 0
	v_mfma_f32_16x16x32_bf16 v[46:49], v[150:153], v[192:195], 0
	v_mfma_f32_16x16x32_bf16 v[38:41], v[164:167], v[192:195], 0
	v_mfma_f32_16x16x32_bf16 v[30:33], v[150:153], v[204:207], 0
	v_mfma_f32_16x16x32_bf16 v[22:25], v[164:167], v[204:207], 0
	v_mfma_f32_16x16x32_bf16 v[14:17], v[150:153], v[208:211], 0
	v_mfma_f32_16x16x32_bf16 v[6:9], v[164:167], v[208:211], 0
	v_mfma_f32_16x16x32_bf16 v[62:65], v[160:163], v[196:199], v[62:65]
	v_mfma_f32_16x16x32_bf16 v[54:57], v[168:171], v[196:199], v[54:57]
	v_mfma_f32_16x16x32_bf16 v[46:49], v[160:163], v[200:203], v[46:49]
	v_mfma_f32_16x16x32_bf16 v[38:41], v[168:171], v[200:203], v[38:41]
	v_mfma_f32_16x16x32_bf16 v[30:33], v[160:163], v[212:215], v[30:33]
	v_mfma_f32_16x16x32_bf16 v[22:25], v[168:171], v[212:215], v[22:25]
	v_mfma_f32_16x16x32_bf16 v[14:17], v[160:163], v[216:219], v[14:17]
	v_mfma_f32_16x16x32_bf16 v[6:9], v[168:171], v[216:219], v[6:9]
	s_setprio 0
	s_setprio 1
	v_mfma_f32_16x16x32_bf16 v[58:61], v[172:175], v[188:191], 0
	v_mfma_f32_16x16x32_bf16 v[50:53], v[180:183], v[188:191], 0
	v_mfma_f32_16x16x32_bf16 v[42:45], v[172:175], v[192:195], 0
	v_mfma_f32_16x16x32_bf16 v[34:37], v[180:183], v[192:195], 0
	v_mfma_f32_16x16x32_bf16 v[26:29], v[172:175], v[204:207], 0
	v_mfma_f32_16x16x32_bf16 v[18:21], v[180:183], v[204:207], 0
	v_mfma_f32_16x16x32_bf16 v[10:13], v[172:175], v[208:211], 0
	v_mfma_f32_16x16x32_bf16 v[2:5], v[180:183], v[208:211], 0
	v_mfma_f32_16x16x32_bf16 v[58:61], v[176:179], v[196:199], v[58:61]
	v_mfma_f32_16x16x32_bf16 v[50:53], v[184:187], v[196:199], v[50:53]
	v_mfma_f32_16x16x32_bf16 v[42:45], v[176:179], v[200:203], v[42:45]
	v_mfma_f32_16x16x32_bf16 v[34:37], v[184:187], v[200:203], v[34:37]
	v_mfma_f32_16x16x32_bf16 v[26:29], v[176:179], v[212:215], v[26:29]
	v_mfma_f32_16x16x32_bf16 v[18:21], v[184:187], v[212:215], v[18:21]
	v_mfma_f32_16x16x32_bf16 v[10:13], v[176:179], v[216:219], v[10:13]
	v_mfma_f32_16x16x32_bf16 v[2:5], v[184:187], v[216:219], v[2:5]
	s_setprio 0
	s_barrier
	s_add_i32 s64, 0, 0x18000
	s_add_i32 s65, 0, 0x1c000
	v_add_u32_e32 v150, s64, v155
	v_add_u32_e32 v160, s64, v156
	v_add_u32_e32 v164, s53, v155
	v_add_u32_e32 v168, s53, v156
	v_add_u32_e32 v172, s65, v155
	v_add_u32_e32 v176, s65, v156
	v_add_u32_e32 v180, s54, v155
	v_add_u32_e32 v184, s54, v156
	ds_read_b128 v[150:153], v150
	ds_read_b128 v[160:163], v160
	ds_read_b128 v[164:167], v164
	ds_read_b128 v[168:171], v168
	ds_read_b128 v[172:175], v172
	ds_read_b128 v[176:179], v176
	ds_read_b128 v[180:183], v180
	ds_read_b128 v[184:187], v184
	s_add_u32 s26, s26, 0x40000
	s_addc_u32 s27, s27, 0
	s_mov_b32 m0, s40
	v_lshl_add_u64 v[228:229], s[26:27], 0, v[130:131]
	ds_read_b128 v[188:191], v157 offset:32768
	ds_read_b128 v[192:195], v157 offset:34816
	ds_read_b128 v[196:199], v158 offset:32768
	ds_read_b128 v[200:203], v158 offset:34816
	ds_read_b128 v[204:207], v157 offset:36864
	ds_read_b128 v[208:211], v157 offset:38912
	ds_read_b128 v[212:215], v158 offset:36864
	ds_read_b128 v[216:219], v158 offset:38912
	global_load_lds_dwordx4 v[228:229], off
	v_lshl_add_u64 v[228:229], s[26:27], 0, v[134:135]
	s_mov_b32 m0, s41
	s_nop 0
	global_load_lds_dwordx4 v[228:229], off
	s_waitcnt vmcnt(8)
	s_waitcnt lgkmcnt(0)
	s_barrier
	s_setprio 1
	s_waitcnt lgkmcnt(0)
	v_mfma_f32_16x16x32_bf16 v[126:129], v[150:153], v[188:191], v[126:129]
	v_mfma_f32_16x16x32_bf16 v[118:121], v[164:167], v[188:191], v[118:121]
	v_mfma_f32_16x16x32_bf16 v[110:113], v[150:153], v[192:195], v[110:113]
	v_mfma_f32_16x16x32_bf16 v[102:105], v[164:167], v[192:195], v[102:105]
	v_mfma_f32_16x16x32_bf16 v[94:97], v[150:153], v[204:207], v[94:97]
	v_mfma_f32_16x16x32_bf16 v[86:89], v[164:167], v[204:207], v[86:89]
	v_mfma_f32_16x16x32_bf16 v[78:81], v[150:153], v[208:211], v[78:81]
	v_mfma_f32_16x16x32_bf16 v[70:73], v[164:167], v[208:211], v[70:73]
	v_mfma_f32_16x16x32_bf16 v[126:129], v[160:163], v[196:199], v[126:129]
	v_mfma_f32_16x16x32_bf16 v[118:121], v[168:171], v[196:199], v[118:121]
	v_mfma_f32_16x16x32_bf16 v[110:113], v[160:163], v[200:203], v[110:113]
	v_mfma_f32_16x16x32_bf16 v[102:105], v[168:171], v[200:203], v[102:105]
	v_mfma_f32_16x16x32_bf16 v[94:97], v[160:163], v[212:215], v[94:97]
	v_mfma_f32_16x16x32_bf16 v[86:89], v[168:171], v[212:215], v[86:89]
	v_mfma_f32_16x16x32_bf16 v[78:81], v[160:163], v[216:219], v[78:81]
	v_mfma_f32_16x16x32_bf16 v[70:73], v[168:171], v[216:219], v[70:73]
	s_setprio 0
	s_setprio 1
	v_mfma_f32_16x16x32_bf16 v[122:125], v[172:175], v[188:191], v[122:125]
	v_mfma_f32_16x16x32_bf16 v[114:117], v[180:183], v[188:191], v[114:117]
	v_mfma_f32_16x16x32_bf16 v[106:109], v[172:175], v[192:195], v[106:109]
	v_mfma_f32_16x16x32_bf16 v[98:101], v[180:183], v[192:195], v[98:101]
	v_mfma_f32_16x16x32_bf16 v[90:93], v[172:175], v[204:207], v[90:93]
	v_mfma_f32_16x16x32_bf16 v[82:85], v[180:183], v[204:207], v[82:85]
	v_mfma_f32_16x16x32_bf16 v[74:77], v[172:175], v[208:211], v[74:77]
	v_mfma_f32_16x16x32_bf16 v[66:69], v[180:183], v[208:211], v[66:69]
	v_mfma_f32_16x16x32_bf16 v[122:125], v[176:179], v[196:199], v[122:125]
	v_mfma_f32_16x16x32_bf16 v[114:117], v[184:187], v[196:199], v[114:117]
	v_mfma_f32_16x16x32_bf16 v[106:109], v[176:179], v[200:203], v[106:109]
	v_mfma_f32_16x16x32_bf16 v[98:101], v[184:187], v[200:203], v[98:101]
	v_mfma_f32_16x16x32_bf16 v[90:93], v[176:179], v[212:215], v[90:93]
	v_mfma_f32_16x16x32_bf16 v[82:85], v[184:187], v[212:215], v[82:85]
	v_mfma_f32_16x16x32_bf16 v[74:77], v[176:179], v[216:219], v[74:77]
	v_mfma_f32_16x16x32_bf16 v[66:69], v[184:187], v[216:219], v[66:69]
	s_setprio 0
	s_barrier
	s_add_i32 s26, s64, s21
	v_lshl_add_u64 v[220:221], v[220:221], 0, s[8:9]
	s_mov_b32 m0, s26
	ds_read_b128 v[188:191], v157 offset:49152
	ds_read_b128 v[192:195], v157 offset:51200
	ds_read_b128 v[196:199], v158 offset:49152
	ds_read_b128 v[200:203], v158 offset:51200
	ds_read_b128 v[204:207], v157 offset:53248
	ds_read_b128 v[208:211], v157 offset:55296
	ds_read_b128 v[212:215], v158 offset:53248
	ds_read_b128 v[216:219], v158 offset:55296
	global_load_lds_dwordx4 v[220:221], off
	s_add_i32 m0, s26, 0x2000
	s_add_u32 s24, s24, 0x40080
	v_lshl_add_u64 v[220:221], v[222:223], 0, s[8:9]
	s_addc_u32 s25, s25, 0
	s_add_i32 s26, s65, s21
	global_load_lds_dwordx4 v[220:221], off
	v_lshl_add_u64 v[220:221], s[24:25], 0, v[132:133]
	s_mov_b32 m0, s26
	s_nop 0
	global_load_lds_dwordx4 v[220:221], off
	v_lshl_add_u64 v[220:221], s[24:25], 0, v[136:137]
	s_add_i32 m0, s26, 0x2000
	s_nop 0
	global_load_lds_dwordx4 v[220:221], off
	v_lshl_add_u64 v[220:221], v[224:225], 0, s[8:9]
	s_mov_b32 m0, s44
	s_nop 0
	global_load_lds_dwordx4 v[220:221], off
	v_lshl_add_u64 v[220:221], v[226:227], 0, s[8:9]
	s_mov_b32 m0, s45
	s_nop 0
	global_load_lds_dwordx4 v[220:221], off
	s_waitcnt vmcnt(8)
	s_waitcnt lgkmcnt(0)
	s_barrier
	s_setprio 1
	s_waitcnt lgkmcnt(0)
	v_mfma_f32_16x16x32_bf16 v[62:65], v[150:153], v[188:191], v[62:65]
	v_mfma_f32_16x16x32_bf16 v[54:57], v[164:167], v[188:191], v[54:57]
	v_mfma_f32_16x16x32_bf16 v[46:49], v[150:153], v[192:195], v[46:49]
	v_mfma_f32_16x16x32_bf16 v[38:41], v[164:167], v[192:195], v[38:41]
	v_mfma_f32_16x16x32_bf16 v[30:33], v[150:153], v[204:207], v[30:33]
	v_mfma_f32_16x16x32_bf16 v[22:25], v[164:167], v[204:207], v[22:25]
	v_mfma_f32_16x16x32_bf16 v[14:17], v[150:153], v[208:211], v[14:17]
	v_mfma_f32_16x16x32_bf16 v[6:9], v[164:167], v[208:211], v[6:9]
	v_mfma_f32_16x16x32_bf16 v[62:65], v[160:163], v[196:199], v[62:65]
	v_mfma_f32_16x16x32_bf16 v[54:57], v[168:171], v[196:199], v[54:57]
	v_mfma_f32_16x16x32_bf16 v[46:49], v[160:163], v[200:203], v[46:49]
	v_mfma_f32_16x16x32_bf16 v[38:41], v[168:171], v[200:203], v[38:41]
	v_mfma_f32_16x16x32_bf16 v[30:33], v[160:163], v[212:215], v[30:33]
	v_mfma_f32_16x16x32_bf16 v[22:25], v[168:171], v[212:215], v[22:25]
	v_mfma_f32_16x16x32_bf16 v[14:17], v[160:163], v[216:219], v[14:17]
	v_mfma_f32_16x16x32_bf16 v[6:9], v[168:171], v[216:219], v[6:9]
	s_setprio 0
	s_setprio 1
	v_mfma_f32_16x16x32_bf16 v[58:61], v[172:175], v[188:191], v[58:61]
	v_mfma_f32_16x16x32_bf16 v[50:53], v[180:183], v[188:191], v[50:53]
	v_mfma_f32_16x16x32_bf16 v[42:45], v[172:175], v[192:195], v[42:45]
	v_mfma_f32_16x16x32_bf16 v[34:37], v[180:183], v[192:195], v[34:37]
	v_mfma_f32_16x16x32_bf16 v[26:29], v[172:175], v[204:207], v[26:29]
	v_mfma_f32_16x16x32_bf16 v[18:21], v[180:183], v[204:207], v[18:21]
	v_mfma_f32_16x16x32_bf16 v[10:13], v[172:175], v[208:211], v[10:13]
	v_mfma_f32_16x16x32_bf16 v[2:5], v[180:183], v[208:211], v[2:5]
	v_mfma_f32_16x16x32_bf16 v[58:61], v[176:179], v[196:199], v[58:61]
	v_mfma_f32_16x16x32_bf16 v[50:53], v[184:187], v[196:199], v[50:53]
	v_mfma_f32_16x16x32_bf16 v[42:45], v[176:179], v[200:203], v[42:45]
	v_mfma_f32_16x16x32_bf16 v[34:37], v[184:187], v[200:203], v[34:37]
	v_mfma_f32_16x16x32_bf16 v[26:29], v[176:179], v[212:215], v[26:29]
	v_mfma_f32_16x16x32_bf16 v[18:21], v[184:187], v[212:215], v[18:21]
	v_mfma_f32_16x16x32_bf16 v[10:13], v[176:179], v[216:219], v[10:13]
	v_mfma_f32_16x16x32_bf16 v[2:5], v[184:187], v[216:219], v[2:5]
	s_setprio 0
	s_barrier
	s_add_i32 s63, s63, 2
	s_add_u32 s22, s22, 0x100
	s_addc_u32 s23, s23, 0
	s_add_u32 s61, s61, 0x100
	s_addc_u32 s62, s62, 0
	s_cmp_gt_u32 s63, 13
	s_cbranch_scc1 .LBB0_1725
	s_branch .LBB0_1722

.LBB0_1826:
	s_add_u32 s4, s42, 0xb0080
	s_addc_u32 s5, s43, 0
	s_add_u32 s64, s40, 0x100
	s_mov_b32 s100, 1
	s_addc_u32 s65, s41, 0
	s_mov_b32 s66, -2
	s_waitcnt lgkmcnt(0)
	s_waitcnt vmcnt(0)
.LBB0_1827:
	s_cmp_lg_u32 s100, 0
	s_cbranch_scc1 .Lpeel_6
	ds_read_b128 v[120:123], v220
	ds_read_b128 v[128:131], v221
	ds_read_b128 v[136:139], v222
	ds_read_b128 v[140:143], v223
	ds_read_b128 v[144:147], v224
	ds_read_b128 v[148:151], v225
	ds_read_b128 v[152:155], v226
	ds_read_b128 v[156:159], v227
	s_add_u32 s40, s4, 0xfff50080
	s_addc_u32 s41, s5, -1
	s_cmp_eq_u32 s66, 40
	s_cselect_b32 s43, s29, s41
	s_cselect_b32 s42, s28, s40
	s_cselect_b32 s41, s35, s65
	s_cselect_b32 s40, s34, s64
	v_lshl_add_u64 v[210:211], s[4:5], 0, v[202:203]
	s_add_i32 m0, s44, 0xc000
	ds_read_b128 v[160:163], v228
	ds_read_b128 v[164:167], v228 offset:2048
	ds_read_b128 v[168:171], v229
	ds_read_b128 v[172:175], v229 offset:2048
	ds_read_b128 v[176:179], v228 offset:4096
	ds_read_b128 v[180:183], v228 offset:6144
	ds_read_b128 v[184:187], v229 offset:4096
	ds_read_b128 v[188:191], v229 offset:6144
	global_load_lds_dwordx4 v[210:211], off
	v_lshl_add_u64 v[210:211], s[4:5], 0, v[204:205]
	s_add_i32 m0, s44, 0xe000
	s_nop 0
	global_load_lds_dwordx4 v[210:211], off
	s_waitcnt vmcnt(8)
	s_waitcnt lgkmcnt(0)
	s_barrier
	s_setprio 1
	s_waitcnt lgkmcnt(0)
	v_mfma_f32_16x16x32_bf16 v[132:135], v[120:123], v[160:163], v[132:135]
	v_mfma_f32_16x16x32_bf16 v[124:127], v[136:139], v[160:163], v[124:127]
	v_mfma_f32_16x16x32_bf16 v[108:111], v[120:123], v[164:167], v[108:111]
	v_mfma_f32_16x16x32_bf16 v[104:107], v[136:139], v[164:167], v[104:107]
	v_mfma_f32_16x16x32_bf16 v[92:95], v[120:123], v[176:179], v[92:95]
	v_mfma_f32_16x16x32_bf16 v[88:91], v[136:139], v[176:179], v[88:91]
	v_mfma_f32_16x16x32_bf16 v[76:79], v[120:123], v[180:183], v[76:79]
	v_mfma_f32_16x16x32_bf16 v[72:75], v[136:139], v[180:183], v[72:75]
	v_mfma_f32_16x16x32_bf16 v[132:135], v[128:131], v[168:171], v[132:135]
	v_mfma_f32_16x16x32_bf16 v[124:127], v[140:143], v[168:171], v[124:127]
	v_mfma_f32_16x16x32_bf16 v[108:111], v[128:131], v[172:175], v[108:111]
	v_mfma_f32_16x16x32_bf16 v[104:107], v[140:143], v[172:175], v[104:107]
	v_mfma_f32_16x16x32_bf16 v[92:95], v[128:131], v[184:187], v[92:95]
	v_mfma_f32_16x16x32_bf16 v[88:91], v[140:143], v[184:187], v[88:91]
	v_mfma_f32_16x16x32_bf16 v[76:79], v[128:131], v[188:191], v[76:79]
	v_mfma_f32_16x16x32_bf16 v[72:75], v[140:143], v[188:191], v[72:75]
	s_setprio 0
	s_setprio 1
	v_mfma_f32_16x16x32_bf16 v[116:119], v[144:147], v[160:163], v[116:119]
	v_mfma_f32_16x16x32_bf16 v[112:115], v[152:155], v[160:163], v[112:115]
	v_mfma_f32_16x16x32_bf16 v[100:103], v[144:147], v[164:167], v[100:103]
	v_mfma_f32_16x16x32_bf16 v[96:99], v[152:155], v[164:167], v[96:99]
	v_mfma_f32_16x16x32_bf16 v[84:87], v[144:147], v[176:179], v[84:87]
	v_mfma_f32_16x16x32_bf16 v[80:83], v[152:155], v[176:179], v[80:83]
	v_mfma_f32_16x16x32_bf16 v[68:71], v[144:147], v[180:183], v[68:71]
	v_mfma_f32_16x16x32_bf16 v[64:67], v[152:155], v[180:183], v[64:67]
	v_mfma_f32_16x16x32_bf16 v[116:119], v[148:151], v[168:171], v[116:119]
	v_mfma_f32_16x16x32_bf16 v[112:115], v[156:159], v[168:171], v[112:115]
	v_mfma_f32_16x16x32_bf16 v[100:103], v[148:151], v[172:175], v[100:103]
	v_mfma_f32_16x16x32_bf16 v[96:99], v[156:159], v[172:175], v[96:99]
	v_mfma_f32_16x16x32_bf16 v[84:87], v[148:151], v[184:187], v[84:87]
	v_mfma_f32_16x16x32_bf16 v[80:83], v[156:159], v[184:187], v[80:83]
	v_mfma_f32_16x16x32_bf16 v[68:71], v[148:151], v[188:191], v[68:71]
	v_mfma_f32_16x16x32_bf16 v[64:67], v[156:159], v[188:191], v[64:67]
	s_setprio 0
	s_barrier
	s_add_i32 s67, s58, s39
	v_lshl_add_u64 v[210:211], s[40:41], 0, v[194:195]
	s_mov_b32 m0, s67
	ds_read_b128 v[160:163], v228 offset:16384
	ds_read_b128 v[164:167], v228 offset:18432
	ds_read_b128 v[168:171], v229 offset:16384
	ds_read_b128 v[172:175], v229 offset:18432
	ds_read_b128 v[176:179], v228 offset:20480
	ds_read_b128 v[180:183], v228 offset:22528
	ds_read_b128 v[184:187], v229 offset:20480
	ds_read_b128 v[188:191], v229 offset:22528
	global_load_lds_dwordx4 v[210:211], off
	s_add_i32 m0, s67, 0x2000
	s_add_u32 s68, s40, 0xb0000
	v_lshl_add_u64 v[212:213], s[40:41], 0, v[198:199]
	s_addc_u32 s69, s41, 0
	s_add_i32 s67, s59, s39
	global_load_lds_dwordx4 v[212:213], off
	v_lshl_add_u64 v[214:215], s[68:69], 0, v[194:195]
	s_mov_b32 m0, s67
	v_lshl_add_u64 v[234:235], s[42:43], 0, v[196:197]
	global_load_lds_dwordx4 v[214:215], off
	v_lshl_add_u64 v[214:215], s[68:69], 0, v[198:199]
	s_add_i32 m0, s67, 0x2000
	s_nop 0
	global_load_lds_dwordx4 v[214:215], off
	v_lshl_add_u64 v[214:215], s[42:43], 0, v[192:193]
	s_mov_b32 m0, s44
	s_nop 0
	global_load_lds_dwordx4 v[214:215], off
	s_mov_b32 m0, s45
	s_nop 0
	global_load_lds_dwordx4 v[234:235], off
	s_waitcnt vmcnt(8)
	s_waitcnt lgkmcnt(0)
	s_barrier
	s_setprio 1
	s_waitcnt lgkmcnt(0)
	v_mfma_f32_16x16x32_bf16 v[60:63], v[120:123], v[160:163], v[60:63]
	v_mfma_f32_16x16x32_bf16 v[56:59], v[136:139], v[160:163], v[56:59]
	v_mfma_f32_16x16x32_bf16 v[44:47], v[120:123], v[164:167], v[44:47]
	v_mfma_f32_16x16x32_bf16 v[40:43], v[136:139], v[164:167], v[40:43]
	v_mfma_f32_16x16x32_bf16 v[28:31], v[120:123], v[176:179], v[28:31]
	v_mfma_f32_16x16x32_bf16 v[24:27], v[136:139], v[176:179], v[24:27]
	v_mfma_f32_16x16x32_bf16 v[12:15], v[120:123], v[180:183], v[12:15]
	v_mfma_f32_16x16x32_bf16 v[8:11], v[136:139], v[180:183], v[8:11]
	v_mfma_f32_16x16x32_bf16 v[60:63], v[128:131], v[168:171], v[60:63]
	v_mfma_f32_16x16x32_bf16 v[56:59], v[140:143], v[168:171], v[56:59]
	v_mfma_f32_16x16x32_bf16 v[44:47], v[128:131], v[172:175], v[44:47]
	v_mfma_f32_16x16x32_bf16 v[40:43], v[140:143], v[172:175], v[40:43]
	v_mfma_f32_16x16x32_bf16 v[28:31], v[128:131], v[184:187], v[28:31]
	v_mfma_f32_16x16x32_bf16 v[24:27], v[140:143], v[184:187], v[24:27]
	v_mfma_f32_16x16x32_bf16 v[12:15], v[128:131], v[188:191], v[12:15]
	v_mfma_f32_16x16x32_bf16 v[8:11], v[140:143], v[188:191], v[8:11]
	s_setprio 0
	s_setprio 1
	v_mfma_f32_16x16x32_bf16 v[52:55], v[144:147], v[160:163], v[52:55]
	v_mfma_f32_16x16x32_bf16 v[48:51], v[152:155], v[160:163], v[48:51]
	v_mfma_f32_16x16x32_bf16 v[36:39], v[144:147], v[164:167], v[36:39]
	v_mfma_f32_16x16x32_bf16 v[32:35], v[152:155], v[164:167], v[32:35]
	v_mfma_f32_16x16x32_bf16 v[20:23], v[144:147], v[176:179], v[20:23]
	v_mfma_f32_16x16x32_bf16 v[16:19], v[152:155], v[176:179], v[16:19]
	v_mfma_f32_16x16x32_bf16 v[4:7], v[144:147], v[180:183], v[4:7]
	v_mfma_f32_16x16x32_bf16 v[0:3], v[152:155], v[180:183], v[0:3]
	v_mfma_f32_16x16x32_bf16 v[52:55], v[148:151], v[168:171], v[52:55]
	v_mfma_f32_16x16x32_bf16 v[48:51], v[156:159], v[168:171], v[48:51]
	v_mfma_f32_16x16x32_bf16 v[36:39], v[148:151], v[172:175], v[36:39]
	v_mfma_f32_16x16x32_bf16 v[32:35], v[156:159], v[172:175], v[32:35]
	v_mfma_f32_16x16x32_bf16 v[20:23], v[148:151], v[184:187], v[20:23]
	v_mfma_f32_16x16x32_bf16 v[16:19], v[156:159], v[184:187], v[16:19]
	v_mfma_f32_16x16x32_bf16 v[4:7], v[148:151], v[188:191], v[4:7]
	v_mfma_f32_16x16x32_bf16 v[0:3], v[156:159], v[188:191], v[0:3]
	s_setprio 0
	s_barrier
	s_add_i32 s67, 0, 0x18000
	s_add_i32 s68, 0, 0x1c000
	v_add_u32_e32 v120, s67, v218
	v_add_u32_e32 v128, s67, v219
	v_add_u32_e32 v144, s68, v218
	v_add_u32_e32 v148, s68, v219
	ds_read_b128 v[120:123], v120
	ds_read_b128 v[128:131], v128
	ds_read_b128 v[136:139], v230
	ds_read_b128 v[140:143], v231
	ds_read_b128 v[144:147], v144
	ds_read_b128 v[148:151], v148
	ds_read_b128 v[152:155], v232
	ds_read_b128 v[156:159], v233
	s_add_u32 s42, s42, 0xb0000
	s_addc_u32 s43, s43, 0
	s_mov_b32 m0, s46
	v_lshl_add_u64 v[236:237], s[42:43], 0, v[192:193]
	ds_read_b128 v[160:163], v228 offset:32768
	ds_read_b128 v[164:167], v228 offset:34816
	ds_read_b128 v[168:171], v229 offset:32768
	ds_read_b128 v[172:175], v229 offset:34816
	ds_read_b128 v[176:179], v228 offset:36864
	ds_read_b128 v[180:183], v228 offset:38912
	ds_read_b128 v[184:187], v229 offset:36864
	ds_read_b128 v[188:191], v229 offset:38912
	global_load_lds_dwordx4 v[236:237], off
	v_lshl_add_u64 v[236:237], s[42:43], 0, v[196:197]
	s_mov_b32 m0, s47
	s_nop 0
	global_load_lds_dwordx4 v[236:237], off
	s_waitcnt vmcnt(8)
	s_waitcnt lgkmcnt(0)
	s_barrier
	s_setprio 1
	s_waitcnt lgkmcnt(0)
	v_mfma_f32_16x16x32_bf16 v[132:135], v[120:123], v[160:163], v[132:135]
	v_mfma_f32_16x16x32_bf16 v[124:127], v[136:139], v[160:163], v[124:127]
	v_mfma_f32_16x16x32_bf16 v[108:111], v[120:123], v[164:167], v[108:111]
	v_mfma_f32_16x16x32_bf16 v[104:107], v[136:139], v[164:167], v[104:107]
	v_mfma_f32_16x16x32_bf16 v[92:95], v[120:123], v[176:179], v[92:95]
	v_mfma_f32_16x16x32_bf16 v[88:91], v[136:139], v[176:179], v[88:91]
	v_mfma_f32_16x16x32_bf16 v[76:79], v[120:123], v[180:183], v[76:79]
	v_mfma_f32_16x16x32_bf16 v[72:75], v[136:139], v[180:183], v[72:75]
	v_mfma_f32_16x16x32_bf16 v[132:135], v[128:131], v[168:171], v[132:135]
	v_mfma_f32_16x16x32_bf16 v[124:127], v[140:143], v[168:171], v[124:127]
	v_mfma_f32_16x16x32_bf16 v[108:111], v[128:131], v[172:175], v[108:111]
	v_mfma_f32_16x16x32_bf16 v[104:107], v[140:143], v[172:175], v[104:107]
	v_mfma_f32_16x16x32_bf16 v[92:95], v[128:131], v[184:187], v[92:95]
	v_mfma_f32_16x16x32_bf16 v[88:91], v[140:143], v[184:187], v[88:91]
	v_mfma_f32_16x16x32_bf16 v[76:79], v[128:131], v[188:191], v[76:79]
	v_mfma_f32_16x16x32_bf16 v[72:75], v[140:143], v[188:191], v[72:75]
	s_setprio 0
	s_setprio 1
	v_mfma_f32_16x16x32_bf16 v[116:119], v[144:147], v[160:163], v[116:119]
	v_mfma_f32_16x16x32_bf16 v[112:115], v[152:155], v[160:163], v[112:115]
	v_mfma_f32_16x16x32_bf16 v[100:103], v[144:147], v[164:167], v[100:103]
	v_mfma_f32_16x16x32_bf16 v[96:99], v[152:155], v[164:167], v[96:99]
	v_mfma_f32_16x16x32_bf16 v[84:87], v[144:147], v[176:179], v[84:87]
	v_mfma_f32_16x16x32_bf16 v[80:83], v[152:155], v[176:179], v[80:83]
	v_mfma_f32_16x16x32_bf16 v[68:71], v[144:147], v[180:183], v[68:71]
	v_mfma_f32_16x16x32_bf16 v[64:67], v[152:155], v[180:183], v[64:67]
	v_mfma_f32_16x16x32_bf16 v[116:119], v[148:151], v[168:171], v[116:119]
	v_mfma_f32_16x16x32_bf16 v[112:115], v[156:159], v[168:171], v[112:115]
	v_mfma_f32_16x16x32_bf16 v[100:103], v[148:151], v[172:175], v[100:103]
	v_mfma_f32_16x16x32_bf16 v[96:99], v[156:159], v[172:175], v[96:99]
	v_mfma_f32_16x16x32_bf16 v[84:87], v[148:151], v[184:187], v[84:87]
	v_mfma_f32_16x16x32_bf16 v[80:83], v[156:159], v[184:187], v[80:83]
	v_mfma_f32_16x16x32_bf16 v[68:71], v[148:151], v[188:191], v[68:71]
	v_mfma_f32_16x16x32_bf16 v[64:67], v[156:159], v[188:191], v[64:67]
	s_setprio 0
	s_barrier
	s_add_i32 s42, s67, s39
	v_lshl_add_u64 v[210:211], v[210:211], 0, s[8:9]
	s_mov_b32 m0, s42
	ds_read_b128 v[160:163], v228 offset:49152
	ds_read_b128 v[164:167], v228 offset:51200
	ds_read_b128 v[168:171], v229 offset:49152
	ds_read_b128 v[172:175], v229 offset:51200
	ds_read_b128 v[176:179], v228 offset:53248
	ds_read_b128 v[180:183], v228 offset:55296
	ds_read_b128 v[184:187], v229 offset:53248
	ds_read_b128 v[188:191], v229 offset:55296
	global_load_lds_dwordx4 v[210:211], off
	s_add_i32 m0, s42, 0x2000
	s_add_u32 s40, s40, 0xb0080
	v_lshl_add_u64 v[210:211], v[212:213], 0, s[8:9]
	s_addc_u32 s41, s41, 0
	s_add_i32 s42, s68, s39
	global_load_lds_dwordx4 v[210:211], off
	v_lshl_add_u64 v[210:211], s[40:41], 0, v[194:195]
	s_mov_b32 m0, s42
	s_nop 0
	global_load_lds_dwordx4 v[210:211], off
	v_lshl_add_u64 v[210:211], s[40:41], 0, v[198:199]
	s_add_i32 m0, s42, 0x2000
	s_nop 0
	global_load_lds_dwordx4 v[210:211], off
	v_lshl_add_u64 v[210:211], v[214:215], 0, s[8:9]
	s_mov_b32 m0, s51
	s_nop 0
	global_load_lds_dwordx4 v[210:211], off
	v_lshl_add_u64 v[210:211], v[234:235], 0, s[8:9]
	s_mov_b32 m0, s52
	s_nop 0
	global_load_lds_dwordx4 v[210:211], off
	s_waitcnt vmcnt(8)
	s_waitcnt lgkmcnt(0)
	s_barrier
	s_setprio 1
	s_waitcnt lgkmcnt(0)
	v_mfma_f32_16x16x32_bf16 v[60:63], v[120:123], v[160:163], v[60:63]
	v_mfma_f32_16x16x32_bf16 v[56:59], v[136:139], v[160:163], v[56:59]
	v_mfma_f32_16x16x32_bf16 v[44:47], v[120:123], v[164:167], v[44:47]
	v_mfma_f32_16x16x32_bf16 v[40:43], v[136:139], v[164:167], v[40:43]
	v_mfma_f32_16x16x32_bf16 v[28:31], v[120:123], v[176:179], v[28:31]
	v_mfma_f32_16x16x32_bf16 v[24:27], v[136:139], v[176:179], v[24:27]
	v_mfma_f32_16x16x32_bf16 v[12:15], v[120:123], v[180:183], v[12:15]
	v_mfma_f32_16x16x32_bf16 v[8:11], v[136:139], v[180:183], v[8:11]
	v_mfma_f32_16x16x32_bf16 v[60:63], v[128:131], v[168:171], v[60:63]
	v_mfma_f32_16x16x32_bf16 v[56:59], v[140:143], v[168:171], v[56:59]
	v_mfma_f32_16x16x32_bf16 v[44:47], v[128:131], v[172:175], v[44:47]
	v_mfma_f32_16x16x32_bf16 v[40:43], v[140:143], v[172:175], v[40:43]
	v_mfma_f32_16x16x32_bf16 v[28:31], v[128:131], v[184:187], v[28:31]
	v_mfma_f32_16x16x32_bf16 v[24:27], v[140:143], v[184:187], v[24:27]
	v_mfma_f32_16x16x32_bf16 v[12:15], v[128:131], v[188:191], v[12:15]
	v_mfma_f32_16x16x32_bf16 v[8:11], v[140:143], v[188:191], v[8:11]
	s_setprio 0
	s_setprio 1
	v_mfma_f32_16x16x32_bf16 v[52:55], v[144:147], v[160:163], v[52:55]
	v_mfma_f32_16x16x32_bf16 v[48:51], v[152:155], v[160:163], v[48:51]
	v_mfma_f32_16x16x32_bf16 v[36:39], v[144:147], v[164:167], v[36:39]
	v_mfma_f32_16x16x32_bf16 v[32:35], v[152:155], v[164:167], v[32:35]
	v_mfma_f32_16x16x32_bf16 v[20:23], v[144:147], v[176:179], v[20:23]
	v_mfma_f32_16x16x32_bf16 v[16:19], v[152:155], v[176:179], v[16:19]
	v_mfma_f32_16x16x32_bf16 v[4:7], v[144:147], v[180:183], v[4:7]
	v_mfma_f32_16x16x32_bf16 v[0:3], v[152:155], v[180:183], v[0:3]
	v_mfma_f32_16x16x32_bf16 v[52:55], v[148:151], v[168:171], v[52:55]
	v_mfma_f32_16x16x32_bf16 v[48:51], v[156:159], v[168:171], v[48:51]
	v_mfma_f32_16x16x32_bf16 v[36:39], v[148:151], v[172:175], v[36:39]
	v_mfma_f32_16x16x32_bf16 v[32:35], v[156:159], v[172:175], v[32:35]
	v_mfma_f32_16x16x32_bf16 v[20:23], v[148:151], v[184:187], v[20:23]
	v_mfma_f32_16x16x32_bf16 v[16:19], v[156:159], v[184:187], v[16:19]
	v_mfma_f32_16x16x32_bf16 v[4:7], v[148:151], v[188:191], v[4:7]
	v_mfma_f32_16x16x32_bf16 v[0:3], v[156:159], v[188:191], v[0:3]
	s_setprio 0
	s_barrier
	s_add_i32 s66, s66, 2
	s_add_u32 s4, s4, 0x100
	s_addc_u32 s5, s5, 0
	s_add_u32 s64, s64, 0x100
	s_addc_u32 s65, s65, 0
	s_cmp_gt_u32 s66, 41
	s_cbranch_scc0 .LBB0_1827
	s_branch .Lpx_6
.Lpeel_6:
	s_mov_b32 s100, 0
	ds_read_b128 v[120:123], v220
	ds_read_b128 v[128:131], v221
	ds_read_b128 v[136:139], v222
	ds_read_b128 v[140:143], v223
	ds_read_b128 v[144:147], v224
	ds_read_b128 v[148:151], v225
	ds_read_b128 v[152:155], v226
	ds_read_b128 v[156:159], v227
	s_add_u32 s40, s4, 0xfff50080
	s_addc_u32 s41, s5, -1
	s_cmp_eq_u32 s66, 40
	s_cselect_b32 s43, s29, s41
	s_cselect_b32 s42, s28, s40
	s_cselect_b32 s41, s35, s65
	s_cselect_b32 s40, s34, s64
	v_lshl_add_u64 v[210:211], s[4:5], 0, v[202:203]
	s_add_i32 m0, s44, 0xc000
	ds_read_b128 v[160:163], v228
	ds_read_b128 v[164:167], v228 offset:2048
	ds_read_b128 v[168:171], v229
	ds_read_b128 v[172:175], v229 offset:2048
	ds_read_b128 v[176:179], v228 offset:4096
	ds_read_b128 v[180:183], v228 offset:6144
	ds_read_b128 v[184:187], v229 offset:4096
	ds_read_b128 v[188:191], v229 offset:6144
	global_load_lds_dwordx4 v[210:211], off
	v_lshl_add_u64 v[210:211], s[4:5], 0, v[204:205]
	s_add_i32 m0, s44, 0xe000
	s_nop 0
	global_load_lds_dwordx4 v[210:211], off
	s_waitcnt vmcnt(8)
	s_waitcnt lgkmcnt(0)
	s_barrier
	s_setprio 1
	s_waitcnt lgkmcnt(0)
	v_mfma_f32_16x16x32_bf16 v[132:135], v[120:123], v[160:163], 0
	v_mfma_f32_16x16x32_bf16 v[124:127], v[136:139], v[160:163], 0
	v_mfma_f32_16x16x32_bf16 v[108:111], v[120:123], v[164:167], 0
	v_mfma_f32_16x16x32_bf16 v[104:107], v[136:139], v[164:167], 0
	v_mfma_f32_16x16x32_bf16 v[92:95], v[120:123], v[176:179], 0
	v_mfma_f32_16x16x32_bf16 v[88:91], v[136:139], v[176:179], 0
	v_mfma_f32_16x16x32_bf16 v[76:79], v[120:123], v[180:183], 0
	v_mfma_f32_16x16x32_bf16 v[72:75], v[136:139], v[180:183], 0
	v_mfma_f32_16x16x32_bf16 v[132:135], v[128:131], v[168:171], v[132:135]
	v_mfma_f32_16x16x32_bf16 v[124:127], v[140:143], v[168:171], v[124:127]
	v_mfma_f32_16x16x32_bf16 v[108:111], v[128:131], v[172:175], v[108:111]
	v_mfma_f32_16x16x32_bf16 v[104:107], v[140:143], v[172:175], v[104:107]
	v_mfma_f32_16x16x32_bf16 v[92:95], v[128:131], v[184:187], v[92:95]
	v_mfma_f32_16x16x32_bf16 v[88:91], v[140:143], v[184:187], v[88:91]
	v_mfma_f32_16x16x32_bf16 v[76:79], v[128:131], v[188:191], v[76:79]
	v_mfma_f32_16x16x32_bf16 v[72:75], v[140:143], v[188:191], v[72:75]
	s_setprio 0
	s_setprio 1
	v_mfma_f32_16x16x32_bf16 v[116:119], v[144:147], v[160:163], 0
	v_mfma_f32_16x16x32_bf16 v[112:115], v[152:155], v[160:163], 0
	v_mfma_f32_16x16x32_bf16 v[100:103], v[144:147], v[164:167], 0
	v_mfma_f32_16x16x32_bf16 v[96:99], v[152:155], v[164:167], 0
	v_mfma_f32_16x16x32_bf16 v[84:87], v[144:147], v[176:179], 0
	v_mfma_f32_16x16x32_bf16 v[80:83], v[152:155], v[176:179], 0
	v_mfma_f32_16x16x32_bf16 v[68:71], v[144:147], v[180:183], 0
	v_mfma_f32_16x16x32_bf16 v[64:67], v[152:155], v[180:183], 0
	v_mfma_f32_16x16x32_bf16 v[116:119], v[148:151], v[168:171], v[116:119]
	v_mfma_f32_16x16x32_bf16 v[112:115], v[156:159], v[168:171], v[112:115]
	v_mfma_f32_16x16x32_bf16 v[100:103], v[148:151], v[172:175], v[100:103]
	v_mfma_f32_16x16x32_bf16 v[96:99], v[156:159], v[172:175], v[96:99]
	v_mfma_f32_16x16x32_bf16 v[84:87], v[148:151], v[184:187], v[84:87]
	v_mfma_f32_16x16x32_bf16 v[80:83], v[156:159], v[184:187], v[80:83]
	v_mfma_f32_16x16x32_bf16 v[68:71], v[148:151], v[188:191], v[68:71]
	v_mfma_f32_16x16x32_bf16 v[64:67], v[156:159], v[188:191], v[64:67]
	s_setprio 0
	s_barrier
	s_add_i32 s67, s58, s39
	v_lshl_add_u64 v[210:211], s[40:41], 0, v[194:195]
	s_mov_b32 m0, s67
	ds_read_b128 v[160:163], v228 offset:16384
	ds_read_b128 v[164:167], v228 offset:18432
	ds_read_b128 v[168:171], v229 offset:16384
	ds_read_b128 v[172:175], v229 offset:18432
	ds_read_b128 v[176:179], v228 offset:20480
	ds_read_b128 v[180:183], v228 offset:22528
	ds_read_b128 v[184:187], v229 offset:20480
	ds_read_b128 v[188:191], v229 offset:22528
	global_load_lds_dwordx4 v[210:211], off
	s_add_i32 m0, s67, 0x2000
	s_add_u32 s68, s40, 0xb0000
	v_lshl_add_u64 v[212:213], s[40:41], 0, v[198:199]
	s_addc_u32 s69, s41, 0
	s_add_i32 s67, s59, s39
	global_load_lds_dwordx4 v[212:213], off
	v_lshl_add_u64 v[214:215], s[68:69], 0, v[194:195]
	s_mov_b32 m0, s67
	v_lshl_add_u64 v[234:235], s[42:43], 0, v[196:197]
	global_load_lds_dwordx4 v[214:215], off
	v_lshl_add_u64 v[214:215], s[68:69], 0, v[198:199]
	s_add_i32 m0, s67, 0x2000
	s_nop 0
	global_load_lds_dwordx4 v[214:215], off
	v_lshl_add_u64 v[214:215], s[42:43], 0, v[192:193]
	s_mov_b32 m0, s44
	s_nop 0
	global_load_lds_dwordx4 v[214:215], off
	s_mov_b32 m0, s45
	s_nop 0
	global_load_lds_dwordx4 v[234:235], off
	s_waitcnt vmcnt(8)
	s_waitcnt lgkmcnt(0)
	s_barrier
	s_setprio 1
	s_waitcnt lgkmcnt(0)
	v_mfma_f32_16x16x32_bf16 v[60:63], v[120:123], v[160:163], 0
	v_mfma_f32_16x16x32_bf16 v[56:59], v[136:139], v[160:163], 0
	v_mfma_f32_16x16x32_bf16 v[44:47], v[120:123], v[164:167], 0
	v_mfma_f32_16x16x32_bf16 v[40:43], v[136:139], v[164:167], 0
	v_mfma_f32_16x16x32_bf16 v[28:31], v[120:123], v[176:179], 0
	v_mfma_f32_16x16x32_bf16 v[24:27], v[136:139], v[176:179], 0
	v_mfma_f32_16x16x32_bf16 v[12:15], v[120:123], v[180:183], 0
	v_mfma_f32_16x16x32_bf16 v[8:11], v[136:139], v[180:183], 0
	v_mfma_f32_16x16x32_bf16 v[60:63], v[128:131], v[168:171], v[60:63]
	v_mfma_f32_16x16x32_bf16 v[56:59], v[140:143], v[168:171], v[56:59]
	v_mfma_f32_16x16x32_bf16 v[44:47], v[128:131], v[172:175], v[44:47]
	v_mfma_f32_16x16x32_bf16 v[40:43], v[140:143], v[172:175], v[40:43]
	v_mfma_f32_16x16x32_bf16 v[28:31], v[128:131], v[184:187], v[28:31]
	v_mfma_f32_16x16x32_bf16 v[24:27], v[140:143], v[184:187], v[24:27]
	v_mfma_f32_16x16x32_bf16 v[12:15], v[128:131], v[188:191], v[12:15]
	v_mfma_f32_16x16x32_bf16 v[8:11], v[140:143], v[188:191], v[8:11]
	s_setprio 0
	s_setprio 1
	v_mfma_f32_16x16x32_bf16 v[52:55], v[144:147], v[160:163], 0
	v_mfma_f32_16x16x32_bf16 v[48:51], v[152:155], v[160:163], 0
	v_mfma_f32_16x16x32_bf16 v[36:39], v[144:147], v[164:167], 0
	v_mfma_f32_16x16x32_bf16 v[32:35], v[152:155], v[164:167], 0
	v_mfma_f32_16x16x32_bf16 v[20:23], v[144:147], v[176:179], 0
	v_mfma_f32_16x16x32_bf16 v[16:19], v[152:155], v[176:179], 0
	v_mfma_f32_16x16x32_bf16 v[4:7], v[144:147], v[180:183], 0
	v_mfma_f32_16x16x32_bf16 v[0:3], v[152:155], v[180:183], 0
	v_mfma_f32_16x16x32_bf16 v[52:55], v[148:151], v[168:171], v[52:55]
	v_mfma_f32_16x16x32_bf16 v[48:51], v[156:159], v[168:171], v[48:51]
	v_mfma_f32_16x16x32_bf16 v[36:39], v[148:151], v[172:175], v[36:39]
	v_mfma_f32_16x16x32_bf16 v[32:35], v[156:159], v[172:175], v[32:35]
	v_mfma_f32_16x16x32_bf16 v[20:23], v[148:151], v[184:187], v[20:23]
	v_mfma_f32_16x16x32_bf16 v[16:19], v[156:159], v[184:187], v[16:19]
	v_mfma_f32_16x16x32_bf16 v[4:7], v[148:151], v[188:191], v[4:7]
	v_mfma_f32_16x16x32_bf16 v[0:3], v[156:159], v[188:191], v[0:3]
	s_setprio 0
	s_barrier
	s_add_i32 s67, 0, 0x18000
	s_add_i32 s68, 0, 0x1c000
	v_add_u32_e32 v120, s67, v218
	v_add_u32_e32 v128, s67, v219
	v_add_u32_e32 v144, s68, v218
	v_add_u32_e32 v148, s68, v219
	ds_read_b128 v[120:123], v120
	ds_read_b128 v[128:131], v128
	ds_read_b128 v[136:139], v230
	ds_read_b128 v[140:143], v231
	ds_read_b128 v[144:147], v144
	ds_read_b128 v[148:151], v148
	ds_read_b128 v[152:155], v232
	ds_read_b128 v[156:159], v233
	s_add_u32 s42, s42, 0xb0000
	s_addc_u32 s43, s43, 0
	s_mov_b32 m0, s46
	v_lshl_add_u64 v[236:237], s[42:43], 0, v[192:193]
	ds_read_b128 v[160:163], v228 offset:32768
	ds_read_b128 v[164:167], v228 offset:34816
	ds_read_b128 v[168:171], v229 offset:32768
	ds_read_b128 v[172:175], v229 offset:34816
	ds_read_b128 v[176:179], v228 offset:36864
	ds_read_b128 v[180:183], v228 offset:38912
	ds_read_b128 v[184:187], v229 offset:36864
	ds_read_b128 v[188:191], v229 offset:38912
	global_load_lds_dwordx4 v[236:237], off
	v_lshl_add_u64 v[236:237], s[42:43], 0, v[196:197]
	s_mov_b32 m0, s47
	s_nop 0
	global_load_lds_dwordx4 v[236:237], off
	s_waitcnt vmcnt(8)
	s_waitcnt lgkmcnt(0)
	s_barrier
	s_setprio 1
	s_waitcnt lgkmcnt(0)
	v_mfma_f32_16x16x32_bf16 v[132:135], v[120:123], v[160:163], v[132:135]
	v_mfma_f32_16x16x32_bf16 v[124:127], v[136:139], v[160:163], v[124:127]
	v_mfma_f32_16x16x32_bf16 v[108:111], v[120:123], v[164:167], v[108:111]
	v_mfma_f32_16x16x32_bf16 v[104:107], v[136:139], v[164:167], v[104:107]
	v_mfma_f32_16x16x32_bf16 v[92:95], v[120:123], v[176:179], v[92:95]
	v_mfma_f32_16x16x32_bf16 v[88:91], v[136:139], v[176:179], v[88:91]
	v_mfma_f32_16x16x32_bf16 v[76:79], v[120:123], v[180:183], v[76:79]
	v_mfma_f32_16x16x32_bf16 v[72:75], v[136:139], v[180:183], v[72:75]
	v_mfma_f32_16x16x32_bf16 v[132:135], v[128:131], v[168:171], v[132:135]
	v_mfma_f32_16x16x32_bf16 v[124:127], v[140:143], v[168:171], v[124:127]
	v_mfma_f32_16x16x32_bf16 v[108:111], v[128:131], v[172:175], v[108:111]
	v_mfma_f32_16x16x32_bf16 v[104:107], v[140:143], v[172:175], v[104:107]
	v_mfma_f32_16x16x32_bf16 v[92:95], v[128:131], v[184:187], v[92:95]
	v_mfma_f32_16x16x32_bf16 v[88:91], v[140:143], v[184:187], v[88:91]
	v_mfma_f32_16x16x32_bf16 v[76:79], v[128:131], v[188:191], v[76:79]
	v_mfma_f32_16x16x32_bf16 v[72:75], v[140:143], v[188:191], v[72:75]
	s_setprio 0
	s_setprio 1
	v_mfma_f32_16x16x32_bf16 v[116:119], v[144:147], v[160:163], v[116:119]
	v_mfma_f32_16x16x32_bf16 v[112:115], v[152:155], v[160:163], v[112:115]
	v_mfma_f32_16x16x32_bf16 v[100:103], v[144:147], v[164:167], v[100:103]
	v_mfma_f32_16x16x32_bf16 v[96:99], v[152:155], v[164:167], v[96:99]
	v_mfma_f32_16x16x32_bf16 v[84:87], v[144:147], v[176:179], v[84:87]
	v_mfma_f32_16x16x32_bf16 v[80:83], v[152:155], v[176:179], v[80:83]
	v_mfma_f32_16x16x32_bf16 v[68:71], v[144:147], v[180:183], v[68:71]
	v_mfma_f32_16x16x32_bf16 v[64:67], v[152:155], v[180:183], v[64:67]
	v_mfma_f32_16x16x32_bf16 v[116:119], v[148:151], v[168:171], v[116:119]
	v_mfma_f32_16x16x32_bf16 v[112:115], v[156:159], v[168:171], v[112:115]
	v_mfma_f32_16x16x32_bf16 v[100:103], v[148:151], v[172:175], v[100:103]
	v_mfma_f32_16x16x32_bf16 v[96:99], v[156:159], v[172:175], v[96:99]
	v_mfma_f32_16x16x32_bf16 v[84:87], v[148:151], v[184:187], v[84:87]
	v_mfma_f32_16x16x32_bf16 v[80:83], v[156:159], v[184:187], v[80:83]
	v_mfma_f32_16x16x32_bf16 v[68:71], v[148:151], v[188:191], v[68:71]
	v_mfma_f32_16x16x32_bf16 v[64:67], v[156:159], v[188:191], v[64:67]
	s_setprio 0
	s_barrier
	s_add_i32 s42, s67, s39
	v_lshl_add_u64 v[210:211], v[210:211], 0, s[8:9]
	s_mov_b32 m0, s42
	ds_read_b128 v[160:163], v228 offset:49152
	ds_read_b128 v[164:167], v228 offset:51200
	ds_read_b128 v[168:171], v229 offset:49152
	ds_read_b128 v[172:175], v229 offset:51200
	ds_read_b128 v[176:179], v228 offset:53248
	ds_read_b128 v[180:183], v228 offset:55296
	ds_read_b128 v[184:187], v229 offset:53248
	ds_read_b128 v[188:191], v229 offset:55296
	global_load_lds_dwordx4 v[210:211], off
	s_add_i32 m0, s42, 0x2000
	s_add_u32 s40, s40, 0xb0080
	v_lshl_add_u64 v[210:211], v[212:213], 0, s[8:9]
	s_addc_u32 s41, s41, 0
	s_add_i32 s42, s68, s39
	global_load_lds_dwordx4 v[210:211], off
	v_lshl_add_u64 v[210:211], s[40:41], 0, v[194:195]
	s_mov_b32 m0, s42
	s_nop 0
	global_load_lds_dwordx4 v[210:211], off
	v_lshl_add_u64 v[210:211], s[40:41], 0, v[198:199]
	s_add_i32 m0, s42, 0x2000
	s_nop 0
	global_load_lds_dwordx4 v[210:211], off
	v_lshl_add_u64 v[210:211], v[214:215], 0, s[8:9]
	s_mov_b32 m0, s51
	s_nop 0
	global_load_lds_dwordx4 v[210:211], off
	v_lshl_add_u64 v[210:211], v[234:235], 0, s[8:9]
	s_mov_b32 m0, s52
	s_nop 0
	global_load_lds_dwordx4 v[210:211], off
	s_waitcnt vmcnt(8)
	s_waitcnt lgkmcnt(0)
	s_barrier
	s_setprio 1
	s_waitcnt lgkmcnt(0)
	v_mfma_f32_16x16x32_bf16 v[60:63], v[120:123], v[160:163], v[60:63]
	v_mfma_f32_16x16x32_bf16 v[56:59], v[136:139], v[160:163], v[56:59]
	v_mfma_f32_16x16x32_bf16 v[44:47], v[120:123], v[164:167], v[44:47]
	v_mfma_f32_16x16x32_bf16 v[40:43], v[136:139], v[164:167], v[40:43]
	v_mfma_f32_16x16x32_bf16 v[28:31], v[120:123], v[176:179], v[28:31]
	v_mfma_f32_16x16x32_bf16 v[24:27], v[136:139], v[176:179], v[24:27]
	v_mfma_f32_16x16x32_bf16 v[12:15], v[120:123], v[180:183], v[12:15]
	v_mfma_f32_16x16x32_bf16 v[8:11], v[136:139], v[180:183], v[8:11]
	v_mfma_f32_16x16x32_bf16 v[60:63], v[128:131], v[168:171], v[60:63]
	v_mfma_f32_16x16x32_bf16 v[56:59], v[140:143], v[168:171], v[56:59]
	v_mfma_f32_16x16x32_bf16 v[44:47], v[128:131], v[172:175], v[44:47]
	v_mfma_f32_16x16x32_bf16 v[40:43], v[140:143], v[172:175], v[40:43]
	v_mfma_f32_16x16x32_bf16 v[28:31], v[128:131], v[184:187], v[28:31]
	v_mfma_f32_16x16x32_bf16 v[24:27], v[140:143], v[184:187], v[24:27]
	v_mfma_f32_16x16x32_bf16 v[12:15], v[128:131], v[188:191], v[12:15]
	v_mfma_f32_16x16x32_bf16 v[8:11], v[140:143], v[188:191], v[8:11]
	s_setprio 0
	s_setprio 1
	v_mfma_f32_16x16x32_bf16 v[52:55], v[144:147], v[160:163], v[52:55]
	v_mfma_f32_16x16x32_bf16 v[48:51], v[152:155], v[160:163], v[48:51]
	v_mfma_f32_16x16x32_bf16 v[36:39], v[144:147], v[164:167], v[36:39]
	v_mfma_f32_16x16x32_bf16 v[32:35], v[152:155], v[164:167], v[32:35]
	v_mfma_f32_16x16x32_bf16 v[20:23], v[144:147], v[176:179], v[20:23]
	v_mfma_f32_16x16x32_bf16 v[16:19], v[152:155], v[176:179], v[16:19]
	v_mfma_f32_16x16x32_bf16 v[4:7], v[144:147], v[180:183], v[4:7]
	v_mfma_f32_16x16x32_bf16 v[0:3], v[152:155], v[180:183], v[0:3]
	v_mfma_f32_16x16x32_bf16 v[52:55], v[148:151], v[168:171], v[52:55]
	v_mfma_f32_16x16x32_bf16 v[48:51], v[156:159], v[168:171], v[48:51]
	v_mfma_f32_16x16x32_bf16 v[36:39], v[148:151], v[172:175], v[36:39]
	v_mfma_f32_16x16x32_bf16 v[32:35], v[156:159], v[172:175], v[32:35]
	v_mfma_f32_16x16x32_bf16 v[20:23], v[148:151], v[184:187], v[20:23]
	v_mfma_f32_16x16x32_bf16 v[16:19], v[156:159], v[184:187], v[16:19]
	v_mfma_f32_16x16x32_bf16 v[4:7], v[148:151], v[188:191], v[4:7]
	v_mfma_f32_16x16x32_bf16 v[0:3], v[156:159], v[188:191], v[0:3]
	s_setprio 0
	s_barrier
	s_add_i32 s66, s66, 2
	s_add_u32 s4, s4, 0x100
	s_addc_u32 s5, s5, 0
	s_add_u32 s64, s64, 0x100
	s_addc_u32 s65, s65, 0
	s_cmp_gt_u32 s66, 41
	s_cbranch_scc0 .LBB0_1827
.Lpx_6:
	s_and_b64 vcc, exec, s[10:11]
	s_cbranch_vccz .LBB0_1830
	s_barrier
.LBB0_1830:
	s_lshl_b32 s4, s63, 8
	s_add_i32 s42, s4, s49
	s_lshl_b32 s4, s62, 8
	v_mov_b32_e32 v213, v216
	v_mov_b32_e32 v210, v217
	s_or_b32 s40, s4, s50
	s_ashr_i32 s41, s40, 31
	v_lshl_add_u32 v211, v210, 4, v213
	v_ashrrev_i32_e32 v214, 2, v211
	s_lshl_b64 s[4:5], s[40:41], 1
	v_add_u32_e32 v120, s42, v214
	s_add_u32 s4, s80, s4
	v_lshlrev_b32_e32 v121, 4, v213
	s_addc_u32 s5, s81, s5
	v_and_b32_e32 v200, 48, v121
	v_ashrrev_i32_e32 v121, 31, v120
	v_lshl_add_u64 v[122:123], s[4:5], 0, v[200:201]
	v_lshlrev_b64 v[128:129], 11, v[120:121]
	v_lshl_add_u64 v[128:129], v[122:123], 0, v[128:129]
	global_load_dwordx4 v[188:191], v[128:129], off
	global_load_dwordx4 v[184:187], v[128:129], off offset:256
	v_add_u32_e32 v128, 16, v120
	v_ashrrev_i32_e32 v129, 31, v128
	v_lshlrev_b64 v[128:129], 11, v[128:129]
	v_lshl_add_u64 v[128:129], v[122:123], 0, v[128:129]
	global_load_dwordx4 v[180:183], v[128:129], off
	global_load_dwordx4 v[176:179], v[128:129], off offset:256
	v_add_u32_e32 v128, 32, v120
	v_ashrrev_i32_e32 v129, 31, v128
	v_lshlrev_b64 v[128:129], 11, v[128:129]
	v_lshl_add_u64 v[128:129], v[122:123], 0, v[128:129]
	global_load_dwordx4 v[172:175], v[128:129], off
	global_load_dwordx4 v[168:171], v[128:129], off offset:256
	v_add_u32_e32 v128, 48, v120
	v_ashrrev_i32_e32 v129, 31, v128
	v_lshlrev_b64 v[128:129], 11, v[128:129]
	v_lshl_add_u64 v[128:129], v[122:123], 0, v[128:129]
	global_load_dwordx4 v[164:167], v[128:129], off
	global_load_dwordx4 v[160:163], v[128:129], off offset:256
	v_add_u32_e32 v128, 0x80, v120
	v_ashrrev_i32_e32 v129, 31, v128
	v_lshlrev_b64 v[128:129], 11, v[128:129]
	v_lshl_add_u64 v[128:129], v[122:123], 0, v[128:129]
	global_load_dwordx4 v[156:159], v[128:129], off
	global_load_dwordx4 v[152:155], v[128:129], off offset:256
	v_add_u32_e32 v128, 0x90, v120
	v_ashrrev_i32_e32 v129, 31, v128
	v_lshlrev_b64 v[128:129], 11, v[128:129]
	v_lshl_add_u64 v[128:129], v[122:123], 0, v[128:129]
	global_load_dwordx4 v[148:151], v[128:129], off
	global_load_dwordx4 v[144:147], v[128:129], off offset:256
	v_add_u32_e32 v128, 0xa0, v120
	v_add_u32_e32 v120, 0xb0, v120
	v_ashrrev_i32_e32 v129, 31, v128
	v_ashrrev_i32_e32 v121, 31, v120
	v_lshlrev_b64 v[128:129], 11, v[128:129]
	v_lshlrev_b64 v[120:121], 11, v[120:121]
	v_lshl_add_u64 v[128:129], v[122:123], 0, v[128:129]
	v_lshl_add_u64 v[120:121], v[122:123], 0, v[120:121]
	global_load_dwordx4 v[140:143], v[128:129], off
	global_load_dwordx4 v[136:139], v[128:129], off offset:256
	s_nop 0
	global_load_dwordx4 v[128:131], v[120:121], off
	s_nop 0
	global_load_dwordx4 v[120:123], v[120:121], off offset:256
	v_lshrrev_b32_e32 v200, 1, v213
	v_and_b32_e32 v215, 7, v213
	v_lshlrev_b32_e32 v234, 5, v210
	v_bitop3_b32 v200, v200, v210, 3 bitop3:0x6c
	v_ashrrev_i32_e32 v210, 3, v211
	v_lshlrev_b32_e32 v211, 7, v215
	v_lshlrev_b32_e32 v215, 4, v215
	v_xor_b32_e32 v237, v210, v213
	v_xad_u32 v234, v215, v234, v211
	v_lshlrev_b32_e32 v215, 4, v237
	v_and_b32_e32 v237, 48, v215
	v_lshlrev_b32_e32 v238, 6, v214
	v_add_u32_e32 v237, s55, v237
	v_add_u32_e32 v237, v237, v238
	v_lshlrev_b32_e32 v235, 6, v213
	v_add_u32_e32 v212, s42, v213
	v_and_b32_e32 v236, 8, v213
	v_bitop3_b32 v211, v210, v213, 7 bitop3:0x78
	v_lshlrev_b32_e32 v214, 7, v210
	v_sub_u32_e32 v210, v210, v213
	v_lshlrev_b32_e32 v213, 2, v213
	v_lshl_add_u32 v239, v211, 4, v214
	v_mov_b32_e32 v211, s57
	v_mov_b32_e32 v214, s56
	v_cmp_eq_u32_e32 vcc, 0, v236
	v_and_b32_e32 v241, 28, v213
	v_ashrrev_i32_e32 v213, 31, v212
	v_cndmask_b32_e32 v236, v211, v214, vcc
	v_xor_b32_e32 v240, 16, v234
	v_ashrrev_i32_e32 v211, 31, v210
	v_lshlrev_b64 v[214:215], 10, v[212:213]
	v_lshlrev_b64 v[210:211], 12, v[210:211]
	s_andn2_b64 vcc, exec, s[12:13]
	s_waitcnt vmcnt(0)
	ds_write_b128 v237, v[188:191] offset:49152
	v_lshl_add_u32 v188, v200, 4, s55
	v_add_u32_e32 v238, v188, v235
	ds_read_b128 v[188:191], v238 offset:49152
	v_cndmask_b32_e64 v200, 0, 1, s[12:13]
	v_cmp_ne_u32_e64 s[4:5], 1, v200
	v_add_u32_e32 v235, v236, v234
	v_add_u32_e32 v236, v236, v240
	v_add_u32_e32 v234, s55, v239
	v_lshl_add_u64 v[214:215], v[214:215], 2, s[30:31]
	v_lshlrev_b32_e32 v200, 2, v241
	s_cbranch_vccnz .LBB0_1832
	s_waitcnt lgkmcnt(0)
	v_lshlrev_b32_e32 v240, 16, v188
	v_and_b32_e32 v241, 0xffff0000, v188
	v_lshlrev_b32_e32 v188, 16, v189
	v_and_b32_e32 v189, 0xffff0000, v189
	v_lshlrev_b32_e32 v242, 16, v190
	v_and_b32_e32 v243, 0xffff0000, v190
	v_lshlrev_b32_e32 v190, 16, v191
	v_and_b32_e32 v191, 0xffff0000, v191
	v_pk_fma_f32 v[134:135], v[134:135], 0.5, v[188:189] op_sel_hi:[1,0,1]
	v_pk_fma_f32 v[132:133], v[132:133], 0.5, v[240:241] op_sel_hi:[1,0,1]
	v_pk_fma_f32 v[126:127], v[126:127], 0.5, v[190:191] op_sel_hi:[1,0,1]
	v_pk_fma_f32 v[124:125], v[124:125], 0.5, v[242:243] op_sel_hi:[1,0,1]
	ds_write_b128 v235, v[132:135]
	ds_write_b128 v236, v[124:127]
	ds_read_b128 v[124:127], v234 offset:49152
	ds_read_b128 v[132:135], v234 offset:57344
	v_lshl_add_u64 v[188:189], s[40:41], 2, v[214:215]
	v_lshl_add_u64 v[188:189], v[188:189], 0, v[210:211]
	v_lshl_add_u64 v[188:189], v[188:189], 0, v[200:201]
	s_waitcnt lgkmcnt(1)
	global_store_dwordx4 v[188:189], v[124:127], off nt
	s_nop 1
	v_add_co_u32_e32 v124, vcc, 0x8000, v188
	s_nop 1
	v_addc_co_u32_e32 v125, vcc, 0, v189, vcc
	s_waitcnt lgkmcnt(0)
	global_store_dwordx4 v[124:125], v[132:135], off nt
